# GEMM K-loops: per-segment s_setprio toggles removed; waves 4-7 raised to priority 1 once before each K-loop (static priority)
# speedup vs baseline: 1.0070x; 1.0070x over previous
; #define PG8_STAGE(bufoff, gbase, voff) do { _Pragma("unroll") for (int _i = 0; _i < 2; ++_i) \
;         __builtin_amdgcn_global_load_lds((const unsigned*)((const char*)(gbase) + (voff)[_i]), (LAS unsigned*)(lds + (bufoff) + ldsw + _i * 8192), 16, 0, 0); } while (0)
; #define PG8_LDA(dst, b, h) do { _Pragma("unroll") for (int m = 0; m < 4; ++m) _Pragma("unroll") for (int k = 0; k < 2; ++k) dst[m][k] = *(const LAS bf16x8*)(lds + PG8_SA(b, h) + aoff + m * 2048 + k * 1024); } while (0)
; #define PG8_LDB(dst, b, h) do { _Pragma("unroll") for (int n = 0; n < 2; ++n) _Pragma("unroll") for (int k = 0; k < 2; ++k) dst[n][k] = *(const LAS bf16x8*)(lds + PG8_SB(b, h) + boff + n * 2048 + k * 1024); } while (0)
; #define PG8_WAIT_V(n) asm volatile("s_waitcnt vmcnt(" #n ")" ::: "memory")
; #define PG8_WAIT_L(n) asm volatile("s_waitcnt lgkmcnt(" #n ")" ::: "memory")
; #define PG8_BAR __builtin_amdgcn_s_barrier()
; #define PG8_SCHED __builtin_amdgcn_sched_barrier(0)
; template <class Epi, class Sched, bool ALIGN_EPI = true, bool SP2 = true>
; __device__ __forceinline__ void gemm_phase(LAS unsigned char* lds, const Gemm g, const Sched& S, const Epi& E) {
;     ...
;     for (;;) {
;         const bool has_next = S.next(ui + 1, nxt);
;         const char* nA = has_next ? (const char*)g.A + (size_t)nxt.pm * tstep : cA; const char* nB = has_next ? (const char*)g.Bt + (size_t)nxt.pn * tstep : cB;
;         for (int t = 0; t < nt; t += 2) {
;             const bool last = (t == nt - 2);
;             const char* a1 = cA + (size_t)(t + 1) * kstep;
;             const char* a2 = last ? nA : cA + (size_t)(t + 2) * kstep; const char* b2 = last ? nB : cB + (size_t)(t + 2) * kstep;
;             const char* a3 = a2 + kstep; const char* b3 = b2 + kstep;
;             if constexpr (SP2) {
;             PG8_LDB(B0, 0, 0); PG8_LDB(B1, 0, 1); PG8_SCHED; PG8_LDA(At, 0, 0); PG8_STAGE(PG8_SA(1, 1), a1 + hstep, voffA);
;             PG8_WAIT_V(8); PG8_WAIT_L(0); PG8_BAR; PG8_MMA(0, 0, At, B0); PG8_MMA(0, 1, At, B1); PG8_BAR; PG8_SCHED;
;     ...
; #pragma unroll
;         for (int a = 0; a < 2; ++a)
; #pragma unroll
;             for (int b = 0; b < 2; ++b)
; #pragma unroll
;                 for (int m = 0; m < 4; ++m)
; #pragma unroll
;                     for (int n = 0; n < 2; ++n) acc[a][b][m][n] = (f32x4){0.f, 0.f, 0.f, 0.f};
.LBB0_39:
	s_ashr_i32 s55, s54, 31
	s_lshl_b64 s[2:3], s[54:55], 18
	s_add_u32 s60, s28, s2
	s_addc_u32 s61, s79, s3
	s_and_b64 s[2:3], s[6:7], exec
	s_cselect_b32 s2, s61, s25
	s_cselect_b32 s3, s60, s24
	s_ashr_i32 s53, s52, 31
	s_lshl_b64 s[62:63], s[52:53], 18
	s_add_u32 s62, s41, s62
	s_addc_u32 s63, s92, s63
	s_and_b64 s[90:91], s[6:7], exec
	s_cselect_b32 s45, s63, s83
	s_cselect_b32 s53, s62, s82
	s_add_u32 s90, s24, 0x20080
	s_addc_u32 s91, s25, 0
	s_add_u32 s55, s82, 0x100
	v_mov_b32_e32 v0, 0
	s_mov_b64 s[12:13], s[48:49]
	s_addc_u32 vcc_lo, s83, 0
	s_mov_b32 vcc_hi, -2
	s_waitcnt lgkmcnt(0)
	v_mov_b32_e32 v1, v0
	v_mov_b32_e32 v2, v0
	v_mov_b32_e32 v3, v0
	v_mov_b32_e32 v4, v0
	v_mov_b32_e32 v5, v0
	v_mov_b32_e32 v6, v0
	v_mov_b32_e32 v7, v0
	v_mov_b32_e32 v16, v0
	v_mov_b32_e32 v17, v0
	v_mov_b32_e32 v18, v0
	v_mov_b32_e32 v19, v0
	v_mov_b32_e32 v20, v0
	v_mov_b32_e32 v21, v0
	v_mov_b32_e32 v22, v0
	v_mov_b32_e32 v23, v0
	v_mov_b32_e32 v32, v0
	v_mov_b32_e32 v33, v0
	v_mov_b32_e32 v34, v0
	v_mov_b32_e32 v35, v0
	s_waitcnt vmcnt(0)
	v_mov_b32_e32 v36, v0
	v_mov_b32_e32 v37, v0
	v_mov_b32_e32 v38, v0
	v_mov_b32_e32 v39, v0
	v_mov_b32_e32 v48, v0
	v_mov_b32_e32 v49, v0
	v_mov_b32_e32 v50, v0
	v_mov_b32_e32 v51, v0
	v_mov_b32_e32 v52, v0
	v_mov_b32_e32 v53, v0
	v_mov_b32_e32 v54, v0
	v_mov_b32_e32 v55, v0
	v_mov_b32_e32 v8, v0
	v_mov_b32_e32 v9, v0
	v_mov_b32_e32 v10, v0
	v_mov_b32_e32 v11, v0
	v_mov_b32_e32 v12, v0
	v_mov_b32_e32 v13, v0
	v_mov_b32_e32 v14, v0
	v_mov_b32_e32 v15, v0
	v_mov_b32_e32 v24, v0
	v_mov_b32_e32 v25, v0
	v_mov_b32_e32 v26, v0
	v_mov_b32_e32 v27, v0
	v_mov_b32_e32 v28, v0
	v_mov_b32_e32 v29, v0
	v_mov_b32_e32 v30, v0
	v_mov_b32_e32 v31, v0
	v_mov_b32_e32 v40, v0
	v_mov_b32_e32 v41, v0
	v_mov_b32_e32 v42, v0
	v_mov_b32_e32 v43, v0
	v_mov_b32_e32 v44, v0
	v_mov_b32_e32 v45, v0
	v_mov_b32_e32 v46, v0
	v_mov_b32_e32 v47, v0
	v_mov_b32_e32 v56, v0
	v_mov_b32_e32 v57, v0
	v_mov_b32_e32 v58, v0
	v_mov_b32_e32 v59, v0
	v_mov_b32_e32 v60, v0
	v_mov_b32_e32 v61, v0
	v_mov_b32_e32 v62, v0
	v_mov_b32_e32 v63, v0
	v_mov_b32_e32 v64, v0
	v_mov_b32_e32 v65, v0
	v_mov_b32_e32 v66, v0
	v_mov_b32_e32 v67, v0
	v_mov_b32_e32 v68, v0
	v_mov_b32_e32 v69, v0
	v_mov_b32_e32 v70, v0
	v_mov_b32_e32 v71, v0
	v_mov_b32_e32 v80, v0
	v_mov_b32_e32 v81, v0
	v_mov_b32_e32 v82, v0
	v_mov_b32_e32 v83, v0
	v_mov_b32_e32 v84, v0
	v_mov_b32_e32 v85, v0
	v_mov_b32_e32 v86, v0
	v_mov_b32_e32 v87, v0
	v_mov_b32_e32 v96, v0
	v_mov_b32_e32 v97, v0
	v_mov_b32_e32 v98, v0
	v_mov_b32_e32 v99, v0
	v_mov_b32_e32 v100, v0
	v_mov_b32_e32 v101, v0
	v_mov_b32_e32 v102, v0
	v_mov_b32_e32 v103, v0
	v_mov_b32_e32 v112, v0
	v_mov_b32_e32 v113, v0
	v_mov_b32_e32 v114, v0
	v_mov_b32_e32 v115, v0
	v_mov_b32_e32 v116, v0
	v_mov_b32_e32 v117, v0
	v_mov_b32_e32 v118, v0
	v_mov_b32_e32 v119, v0
	v_mov_b32_e32 v72, v0
	v_mov_b32_e32 v73, v0
	v_mov_b32_e32 v74, v0
	v_mov_b32_e32 v75, v0
	v_mov_b32_e32 v76, v0
	v_mov_b32_e32 v77, v0
	v_mov_b32_e32 v78, v0
	v_mov_b32_e32 v79, v0
	v_mov_b32_e32 v88, v0
	v_mov_b32_e32 v89, v0
	v_mov_b32_e32 v90, v0
	v_mov_b32_e32 v91, v0
	v_mov_b32_e32 v92, v0
	v_mov_b32_e32 v93, v0
	v_mov_b32_e32 v94, v0
	v_mov_b32_e32 v95, v0
	v_mov_b32_e32 v104, v0
	v_mov_b32_e32 v105, v0
	v_mov_b32_e32 v106, v0
	v_mov_b32_e32 v107, v0
	v_mov_b32_e32 v108, v0
	v_mov_b32_e32 v109, v0
	v_mov_b32_e32 v110, v0
	v_mov_b32_e32 v111, v0
	v_mov_b32_e32 v120, v0
	v_mov_b32_e32 v121, v0
	v_mov_b32_e32 v122, v0
	v_mov_b32_e32 v123, v0
	v_mov_b32_e32 v124, v0
	v_mov_b32_e32 v125, v0
	v_mov_b32_e32 v126, v0
	v_mov_b32_e32 v127, v0
	v_lshrrev_b32_e32 v226, 8, v238
	v_cmp_ne_u32_e64 s[98:99], 0, v226
	s_nop 3
	s_and_b64 s[98:99], s[98:99], exec
	s_cbranch_scc0 .Lprio_skip_40
	s_setprio 1
.Lprio_skip_40:
.LBB0_40:
	s_add_u32 s24, s90, 0xfffe0080
	s_addc_u32 s25, s91, -1
	s_add_i32 s46, 0, 0x10000
	s_cmp_eq_u32 vcc_hi, 4
	s_cselect_b32 s83, s2, s25
	s_cselect_b32 s82, s3, s24
	v_add_u32_e32 v142, s46, v145
	s_cselect_b32 s25, s45, vcc_lo
	s_cselect_b32 s24, s53, s55
	s_add_i32 s48, 0, 0x14000
	ds_read_b128 v[138:141], v142
	ds_read_b128 v[148:151], v142 offset:1024
	ds_read_b128 v[152:155], v142 offset:2048
	ds_read_b128 v[156:159], v142 offset:3072
	v_add_u32_e32 v142, s48, v145
	ds_read_b128 v[170:173], v142
	ds_read_b128 v[174:177], v142 offset:1024
	ds_read_b128 v[178:181], v142 offset:2048
	ds_read_b128 v[182:185], v142 offset:3072
	s_add_i32 m0, s67, 0xc000
	ds_read_b128 v[186:189], v147
	ds_read_b128 v[190:193], v147 offset:1024
	ds_read_b128 v[194:197], v147 offset:2048
	ds_read_b128 v[198:201], v147 offset:3072
	ds_read_b128 v[202:205], v147 offset:4096
	ds_read_b128 v[206:209], v147 offset:5120
	ds_read_b128 v[210:213], v147 offset:6144
	ds_read_b128 v[214:217], v147 offset:7168
	global_load_lds_dwordx4 v134, s[90:91]
	s_add_i32 m0, s67, 0xe000
	s_nop 0
	global_load_lds_dwordx4 v136, s[90:91]
	s_waitcnt vmcnt(8)
	s_waitcnt lgkmcnt(0)
	s_barrier
; #define PG8_STAGE(bufoff, gbase, voff) do { _Pragma("unroll") for (int _i = 0; _i < 2; ++_i) \
;         __builtin_amdgcn_global_load_lds((const unsigned*)((const char*)(gbase) + (voff)[_i]), (LAS unsigned*)(lds + (bufoff) + ldsw + _i * 8192), 16, 0, 0); } while (0)
; #define PG8_LDA(dst, b, h) do { _Pragma("unroll") for (int m = 0; m < 4; ++m) _Pragma("unroll") for (int k = 0; k < 2; ++k) dst[m][k] = *(const LAS bf16x8*)(lds + PG8_SA(b, h) + aoff + m * 2048 + k * 1024); } while (0)
; #define PG8_MMA(ai, bj, At, Bt) do { __builtin_amdgcn_s_setprio(1); _Pragma("unroll") for (int m = 0; m < 4; ++m) _Pragma("unroll") for (int n = 0; n < 2; ++n) _Pragma("unroll") for (int k = 0; k < 2; ++k) \
;         acc[ai][bj][m][n] = __builtin_amdgcn_mfma_f32_16x16x32_bf16(Bt[n][k], At[m][k], acc[ai][bj][m][n], 0, 0, 0); __builtin_amdgcn_s_setprio(0); } while (0)
; #define PG8_WAIT_V(n) asm volatile("s_waitcnt vmcnt(" #n ")" ::: "memory")
; #define PG8_WAIT_L(n) asm volatile("s_waitcnt lgkmcnt(" #n ")" ::: "memory")
; #define PG8_BAR __builtin_amdgcn_s_barrier()
; #define PG8_SCHED __builtin_amdgcn_sched_barrier(0)
; template <class Epi, class Sched, bool ALIGN_EPI = true, bool SP2 = true>
; __device__ __forceinline__ void gemm_phase(LAS unsigned char* lds, const Gemm g, const Sched& S, const Epi& E) {
;     ...
;             PG8_WAIT_V(8); PG8_WAIT_L(0); PG8_BAR; PG8_MMA(0, 0, At, B0); PG8_MMA(0, 1, At, B1); PG8_BAR; PG8_SCHED;
;             PG8_LDA(At, 0, 1); PG8_STAGE(PG8_SB(0, 0), b2, voffB); PG8_STAGE(PG8_SB(0, 1), b2 + hstep, voffB); PG8_STAGE(PG8_SA(0, 0), a2, voffA);
;             PG8_WAIT_V(8); PG8_WAIT_L(0); PG8_BAR; PG8_MMA(1, 0, At, B0); PG8_MMA(1, 1, At, B1); PG8_BAR; PG8_SCHED;
	s_waitcnt lgkmcnt(0)
	v_mfma_f32_16x16x32_bf16 v[124:127], v[138:141], v[186:189], v[124:127]
	v_mfma_f32_16x16x32_bf16 v[120:123], v[152:155], v[186:189], v[120:123]
	v_mfma_f32_16x16x32_bf16 v[108:111], v[138:141], v[194:197], v[108:111]
	v_mfma_f32_16x16x32_bf16 v[104:107], v[152:155], v[194:197], v[104:107]
	v_mfma_f32_16x16x32_bf16 v[92:95], v[138:141], v[202:205], v[92:95]
	v_mfma_f32_16x16x32_bf16 v[88:91], v[152:155], v[202:205], v[88:91]
	v_mfma_f32_16x16x32_bf16 v[76:79], v[138:141], v[210:213], v[76:79]
	v_mfma_f32_16x16x32_bf16 v[72:75], v[152:155], v[210:213], v[72:75]
	v_mfma_f32_16x16x32_bf16 v[124:127], v[148:151], v[190:193], v[124:127]
	v_mfma_f32_16x16x32_bf16 v[120:123], v[156:159], v[190:193], v[120:123]
	v_mfma_f32_16x16x32_bf16 v[108:111], v[148:151], v[198:201], v[108:111]
	v_mfma_f32_16x16x32_bf16 v[104:107], v[156:159], v[198:201], v[104:107]
	v_mfma_f32_16x16x32_bf16 v[92:95], v[148:151], v[206:209], v[92:95]
	v_mfma_f32_16x16x32_bf16 v[88:91], v[156:159], v[206:209], v[88:91]
	v_mfma_f32_16x16x32_bf16 v[76:79], v[148:151], v[214:217], v[76:79]
	v_mfma_f32_16x16x32_bf16 v[72:75], v[156:159], v[214:217], v[72:75]
	v_mfma_f32_16x16x32_bf16 v[116:119], v[170:173], v[186:189], v[116:119]
	v_mfma_f32_16x16x32_bf16 v[112:115], v[178:181], v[186:189], v[112:115]
	v_mfma_f32_16x16x32_bf16 v[100:103], v[170:173], v[194:197], v[100:103]
	v_mfma_f32_16x16x32_bf16 v[96:99], v[178:181], v[194:197], v[96:99]
	v_mfma_f32_16x16x32_bf16 v[84:87], v[170:173], v[202:205], v[84:87]
	v_mfma_f32_16x16x32_bf16 v[80:83], v[178:181], v[202:205], v[80:83]
	v_mfma_f32_16x16x32_bf16 v[68:71], v[170:173], v[210:213], v[68:71]
	v_mfma_f32_16x16x32_bf16 v[64:67], v[178:181], v[210:213], v[64:67]
	v_mfma_f32_16x16x32_bf16 v[116:119], v[174:177], v[190:193], v[116:119]
	v_mfma_f32_16x16x32_bf16 v[112:115], v[182:185], v[190:193], v[112:115]
	v_mfma_f32_16x16x32_bf16 v[100:103], v[174:177], v[198:201], v[100:103]
	v_mfma_f32_16x16x32_bf16 v[96:99], v[182:185], v[198:201], v[96:99]
	v_mfma_f32_16x16x32_bf16 v[84:87], v[174:177], v[206:209], v[84:87]
	v_mfma_f32_16x16x32_bf16 v[80:83], v[182:185], v[206:209], v[80:83]
	v_mfma_f32_16x16x32_bf16 v[68:71], v[174:177], v[214:217], v[68:71]
	v_mfma_f32_16x16x32_bf16 v[64:67], v[182:185], v[214:217], v[64:67]
	s_barrier
	s_add_i32 s46, s46, s93
	s_mov_b32 m0, s46
	ds_read_b128 v[186:189], v147 offset:16384
	ds_read_b128 v[190:193], v147 offset:17408
	ds_read_b128 v[194:197], v147 offset:18432
	ds_read_b128 v[198:201], v147 offset:19456
	ds_read_b128 v[202:205], v147 offset:20480
	ds_read_b128 v[206:209], v147 offset:21504
	ds_read_b128 v[210:213], v147 offset:22528
	ds_read_b128 v[214:217], v147 offset:23552
	global_load_lds_dwordx4 v160, s[24:25]
	s_add_i32 m0, s46, 0x2000
	s_add_u32 s46, s24, 0x20000
	s_addc_u32 s47, s25, 0
	s_add_i32 s48, s48, s93
	global_load_lds_dwordx4 v132, s[24:25]
	s_mov_b32 m0, s48
	s_nop 0
	global_load_lds_dwordx4 v160, s[46:47]
	s_add_i32 m0, s48, 0x2000
	s_nop 0
	global_load_lds_dwordx4 v132, s[46:47]
	s_mov_b32 m0, s67
	s_nop 0
	global_load_lds_dwordx4 v128, s[82:83]
	s_mov_b32 m0, s73
	s_nop 0
	global_load_lds_dwordx4 v130, s[82:83]
	s_waitcnt vmcnt(8)
	s_waitcnt lgkmcnt(0)
	s_barrier
	s_waitcnt lgkmcnt(0)
	v_mfma_f32_16x16x32_bf16 v[60:63], v[138:141], v[186:189], v[60:63]
	v_mfma_f32_16x16x32_bf16 v[56:59], v[152:155], v[186:189], v[56:59]
	v_mfma_f32_16x16x32_bf16 v[44:47], v[138:141], v[194:197], v[44:47]
	v_mfma_f32_16x16x32_bf16 v[40:43], v[152:155], v[194:197], v[40:43]
	v_mfma_f32_16x16x32_bf16 v[28:31], v[138:141], v[202:205], v[28:31]
	v_mfma_f32_16x16x32_bf16 v[24:27], v[152:155], v[202:205], v[24:27]
	v_mfma_f32_16x16x32_bf16 v[12:15], v[138:141], v[210:213], v[12:15]
	v_mfma_f32_16x16x32_bf16 v[8:11], v[152:155], v[210:213], v[8:11]
	v_mfma_f32_16x16x32_bf16 v[60:63], v[148:151], v[190:193], v[60:63]
	v_mfma_f32_16x16x32_bf16 v[56:59], v[156:159], v[190:193], v[56:59]
	v_mfma_f32_16x16x32_bf16 v[44:47], v[148:151], v[198:201], v[44:47]
	v_mfma_f32_16x16x32_bf16 v[40:43], v[156:159], v[198:201], v[40:43]
	v_mfma_f32_16x16x32_bf16 v[28:31], v[148:151], v[206:209], v[28:31]
	v_mfma_f32_16x16x32_bf16 v[24:27], v[156:159], v[206:209], v[24:27]
	v_mfma_f32_16x16x32_bf16 v[12:15], v[148:151], v[214:217], v[12:15]
	v_mfma_f32_16x16x32_bf16 v[8:11], v[156:159], v[214:217], v[8:11]
	v_mfma_f32_16x16x32_bf16 v[52:55], v[170:173], v[186:189], v[52:55]
	v_mfma_f32_16x16x32_bf16 v[48:51], v[178:181], v[186:189], v[48:51]
	v_mfma_f32_16x16x32_bf16 v[36:39], v[170:173], v[194:197], v[36:39]
	v_mfma_f32_16x16x32_bf16 v[32:35], v[178:181], v[194:197], v[32:35]
	v_mfma_f32_16x16x32_bf16 v[20:23], v[170:173], v[202:205], v[20:23]
	v_mfma_f32_16x16x32_bf16 v[16:19], v[178:181], v[202:205], v[16:19]
	v_mfma_f32_16x16x32_bf16 v[4:7], v[170:173], v[210:213], v[4:7]
	v_mfma_f32_16x16x32_bf16 v[0:3], v[178:181], v[210:213], v[0:3]
	v_mfma_f32_16x16x32_bf16 v[52:55], v[174:177], v[190:193], v[52:55]
	v_mfma_f32_16x16x32_bf16 v[48:51], v[182:185], v[190:193], v[48:51]
	v_mfma_f32_16x16x32_bf16 v[36:39], v[174:177], v[198:201], v[36:39]
	v_mfma_f32_16x16x32_bf16 v[32:35], v[182:185], v[198:201], v[32:35]
	v_mfma_f32_16x16x32_bf16 v[20:23], v[174:177], v[206:209], v[20:23]
	v_mfma_f32_16x16x32_bf16 v[16:19], v[182:185], v[206:209], v[16:19]
	v_mfma_f32_16x16x32_bf16 v[4:7], v[174:177], v[214:217], v[4:7]
	v_mfma_f32_16x16x32_bf16 v[0:3], v[182:185], v[214:217], v[0:3]
	s_barrier
; #define PG8_STAGE(bufoff, gbase, voff) do { _Pragma("unroll") for (int _i = 0; _i < 2; ++_i) \
;         __builtin_amdgcn_global_load_lds((const unsigned*)((const char*)(gbase) + (voff)[_i]), (LAS unsigned*)(lds + (bufoff) + ldsw + _i * 8192), 16, 0, 0); } while (0)
; #define PG8_LDA(dst, b, h) do { _Pragma("unroll") for (int m = 0; m < 4; ++m) _Pragma("unroll") for (int k = 0; k < 2; ++k) dst[m][k] = *(const LAS bf16x8*)(lds + PG8_SA(b, h) + aoff + m * 2048 + k * 1024); } while (0)
; #define PG8_LDB(dst, b, h) do { _Pragma("unroll") for (int n = 0; n < 2; ++n) _Pragma("unroll") for (int k = 0; k < 2; ++k) dst[n][k] = *(const LAS bf16x8*)(lds + PG8_SB(b, h) + boff + n * 2048 + k * 1024); } while (0)
; #define PG8_MMA(ai, bj, At, Bt) do { __builtin_amdgcn_s_setprio(1); _Pragma("unroll") for (int m = 0; m < 4; ++m) _Pragma("unroll") for (int n = 0; n < 2; ++n) _Pragma("unroll") for (int k = 0; k < 2; ++k) \
;         acc[ai][bj][m][n] = __builtin_amdgcn_mfma_f32_16x16x32_bf16(Bt[n][k], At[m][k], acc[ai][bj][m][n], 0, 0, 0); __builtin_amdgcn_s_setprio(0); } while (0)
; #define PG8_WAIT_V(n) asm volatile("s_waitcnt vmcnt(" #n ")" ::: "memory")
; #define PG8_WAIT_L(n) asm volatile("s_waitcnt lgkmcnt(" #n ")" ::: "memory")
; #define PG8_BAR __builtin_amdgcn_s_barrier()
; #define PG8_SCHED __builtin_amdgcn_sched_barrier(0)
; template <class Epi, class Sched, bool ALIGN_EPI = true, bool SP2 = true>
; __device__ __forceinline__ void gemm_phase(LAS unsigned char* lds, const Gemm g, const Sched& S, const Epi& E) {
;     ...
;             PG8_LDB(B0, 1, 0); PG8_LDB(B1, 1, 1); PG8_SCHED; PG8_LDA(At, 1, 0); PG8_STAGE(PG8_SA(0, 1), a2 + hstep, voffA);
;             PG8_WAIT_V(8); PG8_WAIT_L(0); PG8_BAR; PG8_MMA(0, 0, At, B0); PG8_MMA(0, 1, At, B1); PG8_BAR; PG8_SCHED;
;             PG8_LDA(At, 1, 1); PG8_STAGE(PG8_SB(1, 0), b3, voffB); PG8_STAGE(PG8_SB(1, 1), b3 + hstep, voffB); PG8_STAGE(PG8_SA(1, 0), a3, voffA);
;             PG8_WAIT_V(8); PG8_WAIT_L(0); PG8_BAR; PG8_MMA(1, 0, At, B0); PG8_MMA(1, 1, At, B1); PG8_BAR; PG8_SCHED;
	s_add_i32 s48, 0, 0x18000
	s_add_i32 s49, 0, 0x1c000
	v_add_u32_e32 v156, s48, v145
	v_add_u32_e32 v182, s49, v145
	ds_read_b128 v[138:141], v156
	ds_read_b128 v[148:151], v156 offset:1024
	ds_read_b128 v[152:155], v156 offset:2048
	ds_read_b128 v[156:159], v156 offset:3072
	ds_read_b128 v[170:173], v182
	ds_read_b128 v[174:177], v182 offset:1024
	ds_read_b128 v[178:181], v182 offset:2048
	ds_read_b128 v[182:185], v182 offset:3072
	s_add_u32 s46, s82, 0x20000
	s_addc_u32 s47, s83, 0
	s_mov_b32 m0, s94
	ds_read_b128 v[186:189], v147 offset:32768
	ds_read_b128 v[190:193], v147 offset:33792
	ds_read_b128 v[194:197], v147 offset:34816
	ds_read_b128 v[198:201], v147 offset:35840
	ds_read_b128 v[202:205], v147 offset:36864
	ds_read_b128 v[206:209], v147 offset:37888
	ds_read_b128 v[210:213], v147 offset:38912
	ds_read_b128 v[214:217], v147 offset:39936
	global_load_lds_dwordx4 v128, s[46:47]
	s_mov_b32 m0, s95
	s_nop 0
	global_load_lds_dwordx4 v130, s[46:47]
	s_waitcnt vmcnt(8)
	s_waitcnt lgkmcnt(0)
	s_barrier
	s_waitcnt lgkmcnt(0)
	v_mfma_f32_16x16x32_bf16 v[124:127], v[138:141], v[186:189], v[124:127]
	v_mfma_f32_16x16x32_bf16 v[120:123], v[152:155], v[186:189], v[120:123]
	v_mfma_f32_16x16x32_bf16 v[108:111], v[138:141], v[194:197], v[108:111]
	v_mfma_f32_16x16x32_bf16 v[104:107], v[152:155], v[194:197], v[104:107]
	v_mfma_f32_16x16x32_bf16 v[92:95], v[138:141], v[202:205], v[92:95]
	v_mfma_f32_16x16x32_bf16 v[88:91], v[152:155], v[202:205], v[88:91]
	v_mfma_f32_16x16x32_bf16 v[76:79], v[138:141], v[210:213], v[76:79]
	v_mfma_f32_16x16x32_bf16 v[72:75], v[152:155], v[210:213], v[72:75]
	v_mfma_f32_16x16x32_bf16 v[124:127], v[148:151], v[190:193], v[124:127]
	v_mfma_f32_16x16x32_bf16 v[120:123], v[156:159], v[190:193], v[120:123]
	v_mfma_f32_16x16x32_bf16 v[108:111], v[148:151], v[198:201], v[108:111]
	v_mfma_f32_16x16x32_bf16 v[104:107], v[156:159], v[198:201], v[104:107]
	v_mfma_f32_16x16x32_bf16 v[92:95], v[148:151], v[206:209], v[92:95]
	v_mfma_f32_16x16x32_bf16 v[88:91], v[156:159], v[206:209], v[88:91]
	v_mfma_f32_16x16x32_bf16 v[76:79], v[148:151], v[214:217], v[76:79]
	v_mfma_f32_16x16x32_bf16 v[72:75], v[156:159], v[214:217], v[72:75]
	v_mfma_f32_16x16x32_bf16 v[116:119], v[170:173], v[186:189], v[116:119]
	v_mfma_f32_16x16x32_bf16 v[112:115], v[178:181], v[186:189], v[112:115]
	v_mfma_f32_16x16x32_bf16 v[100:103], v[170:173], v[194:197], v[100:103]
	v_mfma_f32_16x16x32_bf16 v[96:99], v[178:181], v[194:197], v[96:99]
	v_mfma_f32_16x16x32_bf16 v[84:87], v[170:173], v[202:205], v[84:87]
	v_mfma_f32_16x16x32_bf16 v[80:83], v[178:181], v[202:205], v[80:83]
	v_mfma_f32_16x16x32_bf16 v[68:71], v[170:173], v[210:213], v[68:71]
	v_mfma_f32_16x16x32_bf16 v[64:67], v[178:181], v[210:213], v[64:67]
	v_mfma_f32_16x16x32_bf16 v[116:119], v[174:177], v[190:193], v[116:119]
	v_mfma_f32_16x16x32_bf16 v[112:115], v[182:185], v[190:193], v[112:115]
	v_mfma_f32_16x16x32_bf16 v[100:103], v[174:177], v[198:201], v[100:103]
	v_mfma_f32_16x16x32_bf16 v[96:99], v[182:185], v[198:201], v[96:99]
	v_mfma_f32_16x16x32_bf16 v[84:87], v[174:177], v[206:209], v[84:87]
	v_mfma_f32_16x16x32_bf16 v[80:83], v[182:185], v[206:209], v[80:83]
	v_mfma_f32_16x16x32_bf16 v[68:71], v[174:177], v[214:217], v[68:71]
	v_mfma_f32_16x16x32_bf16 v[64:67], v[182:185], v[214:217], v[64:67]
	s_barrier
	s_add_i32 s46, s48, s93
	s_mov_b32 m0, s46
	ds_read_b128 v[186:189], v147 offset:49152
	ds_read_b128 v[190:193], v147 offset:50176
	ds_read_b128 v[194:197], v147 offset:51200
	ds_read_b128 v[198:201], v147 offset:52224
	ds_read_b128 v[202:205], v147 offset:53248
	ds_read_b128 v[206:209], v147 offset:54272
	ds_read_b128 v[210:213], v147 offset:55296
	ds_read_b128 v[214:217], v147 offset:56320
	s_add_u32 s98, s24, 0x80
	s_addc_u32 s99, s25, 0
	global_load_lds_dwordx4 v160, s[98:99]
	s_add_i32 m0, s46, 0x2000
	s_add_u32 s24, s24, 0x20080
	s_addc_u32 s25, s25, 0
	s_add_i32 s46, s49, s93
	global_load_lds_dwordx4 v132, s[98:99]
	s_mov_b32 m0, s46
	s_nop 0
	global_load_lds_dwordx4 v160, s[24:25]
	s_add_i32 m0, s46, 0x2000
	s_nop 0
	global_load_lds_dwordx4 v132, s[24:25]
	s_mov_b32 m0, s96
	s_nop 0
	s_add_u32 s98, s82, 0x80
	s_addc_u32 s99, s83, 0
	global_load_lds_dwordx4 v128, s[98:99]
	s_mov_b32 m0, s97
	s_nop 0
	global_load_lds_dwordx4 v130, s[98:99]
	s_waitcnt vmcnt(8)
	s_waitcnt lgkmcnt(0)
	s_barrier
	s_waitcnt lgkmcnt(0)
	v_mfma_f32_16x16x32_bf16 v[60:63], v[138:141], v[186:189], v[60:63]
	v_mfma_f32_16x16x32_bf16 v[56:59], v[152:155], v[186:189], v[56:59]
	v_mfma_f32_16x16x32_bf16 v[44:47], v[138:141], v[194:197], v[44:47]
	v_mfma_f32_16x16x32_bf16 v[40:43], v[152:155], v[194:197], v[40:43]
	v_mfma_f32_16x16x32_bf16 v[28:31], v[138:141], v[202:205], v[28:31]
	v_mfma_f32_16x16x32_bf16 v[24:27], v[152:155], v[202:205], v[24:27]
	v_mfma_f32_16x16x32_bf16 v[12:15], v[138:141], v[210:213], v[12:15]
	v_mfma_f32_16x16x32_bf16 v[8:11], v[152:155], v[210:213], v[8:11]
	v_mfma_f32_16x16x32_bf16 v[60:63], v[148:151], v[190:193], v[60:63]
	v_mfma_f32_16x16x32_bf16 v[56:59], v[156:159], v[190:193], v[56:59]
	v_mfma_f32_16x16x32_bf16 v[44:47], v[148:151], v[198:201], v[44:47]
	v_mfma_f32_16x16x32_bf16 v[40:43], v[156:159], v[198:201], v[40:43]
	v_mfma_f32_16x16x32_bf16 v[28:31], v[148:151], v[206:209], v[28:31]
	v_mfma_f32_16x16x32_bf16 v[24:27], v[156:159], v[206:209], v[24:27]
	v_mfma_f32_16x16x32_bf16 v[12:15], v[148:151], v[214:217], v[12:15]
	v_mfma_f32_16x16x32_bf16 v[8:11], v[156:159], v[214:217], v[8:11]
	v_mfma_f32_16x16x32_bf16 v[52:55], v[170:173], v[186:189], v[52:55]
	v_mfma_f32_16x16x32_bf16 v[48:51], v[178:181], v[186:189], v[48:51]
	v_mfma_f32_16x16x32_bf16 v[36:39], v[170:173], v[194:197], v[36:39]
	v_mfma_f32_16x16x32_bf16 v[32:35], v[178:181], v[194:197], v[32:35]
	v_mfma_f32_16x16x32_bf16 v[20:23], v[170:173], v[202:205], v[20:23]
	v_mfma_f32_16x16x32_bf16 v[16:19], v[178:181], v[202:205], v[16:19]
	v_mfma_f32_16x16x32_bf16 v[4:7], v[170:173], v[210:213], v[4:7]
	v_mfma_f32_16x16x32_bf16 v[0:3], v[178:181], v[210:213], v[0:3]
	v_mfma_f32_16x16x32_bf16 v[52:55], v[174:177], v[190:193], v[52:55]
	v_mfma_f32_16x16x32_bf16 v[48:51], v[182:185], v[190:193], v[48:51]
	v_mfma_f32_16x16x32_bf16 v[36:39], v[174:177], v[198:201], v[36:39]
	v_mfma_f32_16x16x32_bf16 v[32:35], v[182:185], v[198:201], v[32:35]
	v_mfma_f32_16x16x32_bf16 v[20:23], v[174:177], v[206:209], v[20:23]
	v_mfma_f32_16x16x32_bf16 v[16:19], v[182:185], v[206:209], v[16:19]
	v_mfma_f32_16x16x32_bf16 v[4:7], v[174:177], v[214:217], v[4:7]
	v_mfma_f32_16x16x32_bf16 v[0:3], v[182:185], v[214:217], v[0:3]
	s_barrier
	s_add_i32 vcc_hi, vcc_hi, 2
	s_add_u32 s90, s90, 0x100
	s_addc_u32 s91, s91, 0
	s_add_u32 s55, s55, 0x100
	s_addc_u32 vcc_lo, vcc_lo, 0
	s_cmp_gt_u32 vcc_hi, 5
	s_cbranch_scc0 .LBB0_40
	s_setprio 0
	s_and_b64 vcc, exec, s[30:31]
	s_cbranch_vccz .LBB0_43
	s_barrier

; #define PG8_STAGE(bufoff, gbase, voff) do { _Pragma("unroll") for (int _i = 0; _i < 2; ++_i) \
;         __builtin_amdgcn_global_load_lds((const unsigned*)((const char*)(gbase) + (voff)[_i]), (LAS unsigned*)(lds + (bufoff) + ldsw + _i * 8192), 16, 0, 0); } while (0)
; #define PG8_LDA(dst, b, h) do { _Pragma("unroll") for (int m = 0; m < 4; ++m) _Pragma("unroll") for (int k = 0; k < 2; ++k) dst[m][k] = *(const LAS bf16x8*)(lds + PG8_SA(b, h) + aoff + m * 2048 + k * 1024); } while (0)
; #define PG8_LDB(dst, b, h) do { _Pragma("unroll") for (int n = 0; n < 2; ++n) _Pragma("unroll") for (int k = 0; k < 2; ++k) dst[n][k] = *(const LAS bf16x8*)(lds + PG8_SB(b, h) + boff + n * 2048 + k * 1024); } while (0)
; #define PG8_WAIT_V(n) asm volatile("s_waitcnt vmcnt(" #n ")" ::: "memory")
; #define PG8_WAIT_L(n) asm volatile("s_waitcnt lgkmcnt(" #n ")" ::: "memory")
; #define PG8_BAR __builtin_amdgcn_s_barrier()
; #define PG8_SCHED __builtin_amdgcn_sched_barrier(0)
; template <class Epi, class Sched, bool ALIGN_EPI = true, bool SP2 = true>
; __device__ __forceinline__ void gemm_phase(LAS unsigned char* lds, const Gemm g, const Sched& S, const Epi& E) {
;     ...
;     for (;;) {
;         const bool has_next = S.next(ui + 1, nxt);
;         const char* nA = has_next ? (const char*)g.A + (size_t)nxt.pm * tstep : cA; const char* nB = has_next ? (const char*)g.Bt + (size_t)nxt.pn * tstep : cB;
;         for (int t = 0; t < nt; t += 2) {
;             const bool last = (t == nt - 2);
;             const char* a1 = cA + (size_t)(t + 1) * kstep;
;             const char* a2 = last ? nA : cA + (size_t)(t + 2) * kstep; const char* b2 = last ? nB : cB + (size_t)(t + 2) * kstep;
;             const char* a3 = a2 + kstep; const char* b3 = b2 + kstep;
;             if constexpr (SP2) {
;             PG8_LDB(B0, 0, 0); PG8_LDB(B1, 0, 1); PG8_SCHED; PG8_LDA(At, 0, 0); PG8_STAGE(PG8_SA(1, 1), a1 + hstep, voffA);
;             PG8_WAIT_V(8); PG8_WAIT_L(0); PG8_BAR; PG8_MMA(0, 0, At, B0); PG8_MMA(0, 1, At, B1); PG8_BAR; PG8_SCHED;
;     ...
; #pragma unroll
;         for (int a = 0; a < 2; ++a)
; #pragma unroll
;             for (int b = 0; b < 2; ++b)
; #pragma unroll
;                 for (int m = 0; m < 4; ++m)
; #pragma unroll
;                     for (int n = 0; n < 2; ++n) acc[a][b][m][n] = (f32x4){0.f, 0.f, 0.f, 0.f};
.LBB0_92:
	s_ashr_i32 s31, s30, 31
	s_lshl_b64 s[2:3], s[30:31], 20
	s_add_u32 s52, s80, s2
	s_addc_u32 s53, s81, s3
	s_and_b64 s[2:3], s[4:5], exec
	s_cselect_b32 s2, s53, s25
	s_cselect_b32 s3, s52, s24
	s_ashr_i32 s19, s18, 31
	s_lshl_b64 s[54:55], s[18:19], 20
	s_add_u32 s54, s41, s54
	s_addc_u32 s55, s42, s55
	s_and_b64 s[62:63], s[4:5], exec
	s_cselect_b32 s19, s55, s67
	s_cselect_b32 s31, s54, s66
	s_add_u32 s62, s24, 0x80080
	s_addc_u32 s63, s25, 0
	s_add_u32 s91, s66, 0x100
	v_mov_b32_e32 v0, 0
	s_addc_u32 s92, s67, 0
	s_mov_b32 s93, -2
	v_mov_b32_e32 v1, v0
	v_mov_b32_e32 v2, v0
	v_mov_b32_e32 v3, v0
	v_mov_b32_e32 v4, v0
	v_mov_b32_e32 v5, v0
	v_mov_b32_e32 v6, v0
	v_mov_b32_e32 v7, v0
	v_mov_b32_e32 v16, v0
	v_mov_b32_e32 v17, v0
	v_mov_b32_e32 v18, v0
	v_mov_b32_e32 v19, v0
	v_mov_b32_e32 v20, v0
	v_mov_b32_e32 v21, v0
	v_mov_b32_e32 v22, v0
	v_mov_b32_e32 v23, v0
	v_mov_b32_e32 v32, v0
	v_mov_b32_e32 v33, v0
	v_mov_b32_e32 v34, v0
	v_mov_b32_e32 v35, v0
	s_waitcnt vmcnt(0)
	v_mov_b32_e32 v36, v0
	v_mov_b32_e32 v37, v0
	v_mov_b32_e32 v38, v0
	v_mov_b32_e32 v39, v0
	s_waitcnt vmcnt(0)
	v_mov_b32_e32 v48, v0
	v_mov_b32_e32 v49, v0
	v_mov_b32_e32 v50, v0
	v_mov_b32_e32 v51, v0
	v_mov_b32_e32 v52, v0
	v_mov_b32_e32 v53, v0
	v_mov_b32_e32 v54, v0
	v_mov_b32_e32 v55, v0
	v_mov_b32_e32 v8, v0
	v_mov_b32_e32 v9, v0
	v_mov_b32_e32 v10, v0
	v_mov_b32_e32 v11, v0
	v_mov_b32_e32 v12, v0
	v_mov_b32_e32 v13, v0
	v_mov_b32_e32 v14, v0
	v_mov_b32_e32 v15, v0
	v_mov_b32_e32 v24, v0
	v_mov_b32_e32 v25, v0
	v_mov_b32_e32 v26, v0
	v_mov_b32_e32 v27, v0
	v_mov_b32_e32 v28, v0
	v_mov_b32_e32 v29, v0
	v_mov_b32_e32 v30, v0
	v_mov_b32_e32 v31, v0
	v_mov_b32_e32 v40, v0
	v_mov_b32_e32 v41, v0
	v_mov_b32_e32 v42, v0
	v_mov_b32_e32 v43, v0
	v_mov_b32_e32 v44, v0
	v_mov_b32_e32 v45, v0
	v_mov_b32_e32 v46, v0
	v_mov_b32_e32 v47, v0
	v_mov_b32_e32 v56, v0
	v_mov_b32_e32 v57, v0
	v_mov_b32_e32 v58, v0
	v_mov_b32_e32 v59, v0
	v_mov_b32_e32 v60, v0
	v_mov_b32_e32 v61, v0
	v_mov_b32_e32 v62, v0
	v_mov_b32_e32 v63, v0
	v_mov_b32_e32 v64, v0
	v_mov_b32_e32 v65, v0
	v_mov_b32_e32 v66, v0
	v_mov_b32_e32 v67, v0
	v_mov_b32_e32 v68, v0
	v_mov_b32_e32 v69, v0
	v_mov_b32_e32 v70, v0
	v_mov_b32_e32 v71, v0
	v_mov_b32_e32 v80, v0
	v_mov_b32_e32 v81, v0
	v_mov_b32_e32 v82, v0
	v_mov_b32_e32 v83, v0
	v_mov_b32_e32 v84, v0
	v_mov_b32_e32 v85, v0
	v_mov_b32_e32 v86, v0
	v_mov_b32_e32 v87, v0
	v_mov_b32_e32 v96, v0
	v_mov_b32_e32 v97, v0
	v_mov_b32_e32 v98, v0
	v_mov_b32_e32 v99, v0
	v_mov_b32_e32 v100, v0
	v_mov_b32_e32 v101, v0
	v_mov_b32_e32 v102, v0
	v_mov_b32_e32 v103, v0
	v_mov_b32_e32 v112, v0
	v_mov_b32_e32 v113, v0
	v_mov_b32_e32 v114, v0
	v_mov_b32_e32 v115, v0
	v_mov_b32_e32 v116, v0
	v_mov_b32_e32 v117, v0
	v_mov_b32_e32 v118, v0
	v_mov_b32_e32 v119, v0
	v_mov_b32_e32 v72, v0
	v_mov_b32_e32 v73, v0
	v_mov_b32_e32 v74, v0
	v_mov_b32_e32 v75, v0
	v_mov_b32_e32 v76, v0
	v_mov_b32_e32 v77, v0
	v_mov_b32_e32 v78, v0
	v_mov_b32_e32 v79, v0
	v_mov_b32_e32 v88, v0
	v_mov_b32_e32 v89, v0
	v_mov_b32_e32 v90, v0
	v_mov_b32_e32 v91, v0
	v_mov_b32_e32 v92, v0
	v_mov_b32_e32 v93, v0
	v_mov_b32_e32 v94, v0
	v_mov_b32_e32 v95, v0
	v_mov_b32_e32 v104, v0
	v_mov_b32_e32 v105, v0
	v_mov_b32_e32 v106, v0
	v_mov_b32_e32 v107, v0
	v_mov_b32_e32 v108, v0
	v_mov_b32_e32 v109, v0
	v_mov_b32_e32 v110, v0
	v_mov_b32_e32 v111, v0
	v_mov_b32_e32 v120, v0
	v_mov_b32_e32 v121, v0
	v_mov_b32_e32 v122, v0
	v_mov_b32_e32 v123, v0
	v_mov_b32_e32 v124, v0
	v_mov_b32_e32 v125, v0
	v_mov_b32_e32 v126, v0
	v_mov_b32_e32 v127, v0
	v_lshrrev_b32_e32 v226, 8, v238
	v_cmp_ne_u32_e64 s[98:99], 0, v226
	s_nop 3
	s_and_b64 s[98:99], s[98:99], exec
	s_cbranch_scc0 .Lprio_skip_93
	s_setprio 1
.Lprio_skip_93:
.LBB0_93:
	s_add_u32 s24, s62, 0xfff80080
	s_addc_u32 s25, s63, -1
	s_add_i32 s46, 0, 0x10000
	s_cmp_eq_u32 s93, 28
	s_cselect_b32 s67, s2, s25
	s_cselect_b32 s66, s3, s24
	s_cselect_b32 s25, s19, s92
	s_cselect_b32 s24, s31, s91
	s_add_i32 s47, 0, 0x14000
	v_add_u32_e32 v154, s46, v143
	v_add_u32_e32 v158, s47, v143
	ds_read_b128 v[138:141], v154
	ds_read_b128 v[146:149], v154 offset:1024
	ds_read_b128 v[150:153], v154 offset:2048
	ds_read_b128 v[154:157], v154 offset:3072
	ds_read_b128 v[170:173], v158
	ds_read_b128 v[174:177], v158 offset:1024
	ds_read_b128 v[178:181], v158 offset:2048
	ds_read_b128 v[182:185], v158 offset:3072
	s_add_i32 m0, s44, 0xc000
	ds_read_b128 v[186:189], v145
	ds_read_b128 v[190:193], v145 offset:1024
	ds_read_b128 v[194:197], v145 offset:2048
	ds_read_b128 v[198:201], v145 offset:3072
	ds_read_b128 v[202:205], v145 offset:4096
	ds_read_b128 v[206:209], v145 offset:5120
	ds_read_b128 v[210:213], v145 offset:6144
	ds_read_b128 v[214:217], v145 offset:7168
	global_load_lds_dwordx4 v134, s[62:63]
	s_add_i32 m0, s44, 0xe000
	s_nop 0
	global_load_lds_dwordx4 v136, s[62:63]
	s_waitcnt vmcnt(8)
	s_waitcnt lgkmcnt(0)
	s_barrier
; #define PG8_STAGE(bufoff, gbase, voff) do { _Pragma("unroll") for (int _i = 0; _i < 2; ++_i) \
;         __builtin_amdgcn_global_load_lds((const unsigned*)((const char*)(gbase) + (voff)[_i]), (LAS unsigned*)(lds + (bufoff) + ldsw + _i * 8192), 16, 0, 0); } while (0)
; #define PG8_LDA(dst, b, h) do { _Pragma("unroll") for (int m = 0; m < 4; ++m) _Pragma("unroll") for (int k = 0; k < 2; ++k) dst[m][k] = *(const LAS bf16x8*)(lds + PG8_SA(b, h) + aoff + m * 2048 + k * 1024); } while (0)
; #define PG8_MMA(ai, bj, At, Bt) do { __builtin_amdgcn_s_setprio(1); _Pragma("unroll") for (int m = 0; m < 4; ++m) _Pragma("unroll") for (int n = 0; n < 2; ++n) _Pragma("unroll") for (int k = 0; k < 2; ++k) \
;         acc[ai][bj][m][n] = __builtin_amdgcn_mfma_f32_16x16x32_bf16(Bt[n][k], At[m][k], acc[ai][bj][m][n], 0, 0, 0); __builtin_amdgcn_s_setprio(0); } while (0)
; #define PG8_WAIT_V(n) asm volatile("s_waitcnt vmcnt(" #n ")" ::: "memory")
; #define PG8_WAIT_L(n) asm volatile("s_waitcnt lgkmcnt(" #n ")" ::: "memory")
; #define PG8_BAR __builtin_amdgcn_s_barrier()
; #define PG8_SCHED __builtin_amdgcn_sched_barrier(0)
; template <class Epi, class Sched, bool ALIGN_EPI = true, bool SP2 = true>
; __device__ __forceinline__ void gemm_phase(LAS unsigned char* lds, const Gemm g, const Sched& S, const Epi& E) {
;     ...
;             PG8_WAIT_V(8); PG8_WAIT_L(0); PG8_BAR; PG8_MMA(0, 0, At, B0); PG8_MMA(0, 1, At, B1); PG8_BAR; PG8_SCHED;
;             PG8_LDA(At, 0, 1); PG8_STAGE(PG8_SB(0, 0), b2, voffB); PG8_STAGE(PG8_SB(0, 1), b2 + hstep, voffB); PG8_STAGE(PG8_SA(0, 0), a2, voffA);
;             PG8_WAIT_V(8); PG8_WAIT_L(0); PG8_BAR; PG8_MMA(1, 0, At, B0); PG8_MMA(1, 1, At, B1); PG8_BAR; PG8_SCHED;
	s_waitcnt lgkmcnt(0)
	v_mfma_f32_16x16x32_bf16 v[124:127], v[138:141], v[186:189], v[124:127]
	v_mfma_f32_16x16x32_bf16 v[120:123], v[150:153], v[186:189], v[120:123]
	v_mfma_f32_16x16x32_bf16 v[108:111], v[138:141], v[194:197], v[108:111]
	v_mfma_f32_16x16x32_bf16 v[104:107], v[150:153], v[194:197], v[104:107]
	v_mfma_f32_16x16x32_bf16 v[92:95], v[138:141], v[202:205], v[92:95]
	v_mfma_f32_16x16x32_bf16 v[88:91], v[150:153], v[202:205], v[88:91]
	v_mfma_f32_16x16x32_bf16 v[76:79], v[138:141], v[210:213], v[76:79]
	v_mfma_f32_16x16x32_bf16 v[72:75], v[150:153], v[210:213], v[72:75]
	v_mfma_f32_16x16x32_bf16 v[124:127], v[146:149], v[190:193], v[124:127]
	v_mfma_f32_16x16x32_bf16 v[120:123], v[154:157], v[190:193], v[120:123]
	v_mfma_f32_16x16x32_bf16 v[108:111], v[146:149], v[198:201], v[108:111]
	v_mfma_f32_16x16x32_bf16 v[104:107], v[154:157], v[198:201], v[104:107]
	v_mfma_f32_16x16x32_bf16 v[92:95], v[146:149], v[206:209], v[92:95]
	v_mfma_f32_16x16x32_bf16 v[88:91], v[154:157], v[206:209], v[88:91]
	v_mfma_f32_16x16x32_bf16 v[76:79], v[146:149], v[214:217], v[76:79]
	v_mfma_f32_16x16x32_bf16 v[72:75], v[154:157], v[214:217], v[72:75]
	v_mfma_f32_16x16x32_bf16 v[116:119], v[170:173], v[186:189], v[116:119]
	v_mfma_f32_16x16x32_bf16 v[112:115], v[178:181], v[186:189], v[112:115]
	v_mfma_f32_16x16x32_bf16 v[100:103], v[170:173], v[194:197], v[100:103]
	v_mfma_f32_16x16x32_bf16 v[96:99], v[178:181], v[194:197], v[96:99]
	v_mfma_f32_16x16x32_bf16 v[84:87], v[170:173], v[202:205], v[84:87]
	v_mfma_f32_16x16x32_bf16 v[80:83], v[178:181], v[202:205], v[80:83]
	v_mfma_f32_16x16x32_bf16 v[68:71], v[170:173], v[210:213], v[68:71]
	v_mfma_f32_16x16x32_bf16 v[64:67], v[178:181], v[210:213], v[64:67]
	v_mfma_f32_16x16x32_bf16 v[116:119], v[174:177], v[190:193], v[116:119]
	v_mfma_f32_16x16x32_bf16 v[112:115], v[182:185], v[190:193], v[112:115]
	v_mfma_f32_16x16x32_bf16 v[100:103], v[174:177], v[198:201], v[100:103]
	v_mfma_f32_16x16x32_bf16 v[96:99], v[182:185], v[198:201], v[96:99]
	v_mfma_f32_16x16x32_bf16 v[84:87], v[174:177], v[206:209], v[84:87]
	v_mfma_f32_16x16x32_bf16 v[80:83], v[182:185], v[206:209], v[80:83]
	v_mfma_f32_16x16x32_bf16 v[68:71], v[174:177], v[214:217], v[68:71]
	v_mfma_f32_16x16x32_bf16 v[64:67], v[182:185], v[214:217], v[64:67]
	s_barrier
	s_add_i32 s46, s46, s43
	s_mov_b32 m0, s46
	ds_read_b128 v[186:189], v145 offset:16384
	ds_read_b128 v[190:193], v145 offset:17408
	ds_read_b128 v[194:197], v145 offset:18432
	ds_read_b128 v[198:201], v145 offset:19456
	ds_read_b128 v[202:205], v145 offset:20480
	ds_read_b128 v[206:209], v145 offset:21504
	ds_read_b128 v[210:213], v145 offset:22528
	ds_read_b128 v[214:217], v145 offset:23552
	global_load_lds_dwordx4 v160, s[24:25]
	s_add_i32 m0, s46, 0x2000
	s_add_u32 s94, s24, 0x80000
	s_addc_u32 s95, s25, 0
	s_add_i32 s46, s47, s43
	global_load_lds_dwordx4 v132, s[24:25]
	s_mov_b32 m0, s46
	s_nop 0
	global_load_lds_dwordx4 v160, s[94:95]
	s_add_i32 m0, s46, 0x2000
	s_nop 0
	global_load_lds_dwordx4 v132, s[94:95]
	s_mov_b32 m0, s44
	s_nop 0
	global_load_lds_dwordx4 v128, s[66:67]
	s_mov_b32 m0, s45
	s_nop 0
	global_load_lds_dwordx4 v130, s[66:67]
	s_waitcnt vmcnt(8)
	s_waitcnt lgkmcnt(0)
	s_barrier
	s_waitcnt lgkmcnt(0)
	v_mfma_f32_16x16x32_bf16 v[60:63], v[138:141], v[186:189], v[60:63]
	v_mfma_f32_16x16x32_bf16 v[56:59], v[150:153], v[186:189], v[56:59]
	v_mfma_f32_16x16x32_bf16 v[44:47], v[138:141], v[194:197], v[44:47]
	v_mfma_f32_16x16x32_bf16 v[40:43], v[150:153], v[194:197], v[40:43]
	v_mfma_f32_16x16x32_bf16 v[28:31], v[138:141], v[202:205], v[28:31]
	v_mfma_f32_16x16x32_bf16 v[24:27], v[150:153], v[202:205], v[24:27]
	v_mfma_f32_16x16x32_bf16 v[12:15], v[138:141], v[210:213], v[12:15]
	v_mfma_f32_16x16x32_bf16 v[8:11], v[150:153], v[210:213], v[8:11]
	v_mfma_f32_16x16x32_bf16 v[60:63], v[146:149], v[190:193], v[60:63]
	v_mfma_f32_16x16x32_bf16 v[56:59], v[154:157], v[190:193], v[56:59]
	v_mfma_f32_16x16x32_bf16 v[44:47], v[146:149], v[198:201], v[44:47]
	v_mfma_f32_16x16x32_bf16 v[40:43], v[154:157], v[198:201], v[40:43]
	v_mfma_f32_16x16x32_bf16 v[28:31], v[146:149], v[206:209], v[28:31]
	v_mfma_f32_16x16x32_bf16 v[24:27], v[154:157], v[206:209], v[24:27]
	v_mfma_f32_16x16x32_bf16 v[12:15], v[146:149], v[214:217], v[12:15]
	v_mfma_f32_16x16x32_bf16 v[8:11], v[154:157], v[214:217], v[8:11]
	v_mfma_f32_16x16x32_bf16 v[52:55], v[170:173], v[186:189], v[52:55]
	v_mfma_f32_16x16x32_bf16 v[48:51], v[178:181], v[186:189], v[48:51]
	v_mfma_f32_16x16x32_bf16 v[36:39], v[170:173], v[194:197], v[36:39]
	v_mfma_f32_16x16x32_bf16 v[32:35], v[178:181], v[194:197], v[32:35]
	v_mfma_f32_16x16x32_bf16 v[20:23], v[170:173], v[202:205], v[20:23]
	v_mfma_f32_16x16x32_bf16 v[16:19], v[178:181], v[202:205], v[16:19]
	v_mfma_f32_16x16x32_bf16 v[4:7], v[170:173], v[210:213], v[4:7]
	v_mfma_f32_16x16x32_bf16 v[0:3], v[178:181], v[210:213], v[0:3]
	v_mfma_f32_16x16x32_bf16 v[52:55], v[174:177], v[190:193], v[52:55]
	v_mfma_f32_16x16x32_bf16 v[48:51], v[182:185], v[190:193], v[48:51]
	v_mfma_f32_16x16x32_bf16 v[36:39], v[174:177], v[198:201], v[36:39]
	v_mfma_f32_16x16x32_bf16 v[32:35], v[182:185], v[198:201], v[32:35]
	v_mfma_f32_16x16x32_bf16 v[20:23], v[174:177], v[206:209], v[20:23]
	v_mfma_f32_16x16x32_bf16 v[16:19], v[182:185], v[206:209], v[16:19]
	v_mfma_f32_16x16x32_bf16 v[4:7], v[174:177], v[214:217], v[4:7]
	v_mfma_f32_16x16x32_bf16 v[0:3], v[182:185], v[214:217], v[0:3]
	s_barrier
; #define PG8_STAGE(bufoff, gbase, voff) do { _Pragma("unroll") for (int _i = 0; _i < 2; ++_i) \
;         __builtin_amdgcn_global_load_lds((const unsigned*)((const char*)(gbase) + (voff)[_i]), (LAS unsigned*)(lds + (bufoff) + ldsw + _i * 8192), 16, 0, 0); } while (0)
; #define PG8_LDA(dst, b, h) do { _Pragma("unroll") for (int m = 0; m < 4; ++m) _Pragma("unroll") for (int k = 0; k < 2; ++k) dst[m][k] = *(const LAS bf16x8*)(lds + PG8_SA(b, h) + aoff + m * 2048 + k * 1024); } while (0)
; #define PG8_LDB(dst, b, h) do { _Pragma("unroll") for (int n = 0; n < 2; ++n) _Pragma("unroll") for (int k = 0; k < 2; ++k) dst[n][k] = *(const LAS bf16x8*)(lds + PG8_SB(b, h) + boff + n * 2048 + k * 1024); } while (0)
; #define PG8_MMA(ai, bj, At, Bt) do { __builtin_amdgcn_s_setprio(1); _Pragma("unroll") for (int m = 0; m < 4; ++m) _Pragma("unroll") for (int n = 0; n < 2; ++n) _Pragma("unroll") for (int k = 0; k < 2; ++k) \
;         acc[ai][bj][m][n] = __builtin_amdgcn_mfma_f32_16x16x32_bf16(Bt[n][k], At[m][k], acc[ai][bj][m][n], 0, 0, 0); __builtin_amdgcn_s_setprio(0); } while (0)
; #define PG8_WAIT_V(n) asm volatile("s_waitcnt vmcnt(" #n ")" ::: "memory")
; #define PG8_WAIT_L(n) asm volatile("s_waitcnt lgkmcnt(" #n ")" ::: "memory")
; #define PG8_BAR __builtin_amdgcn_s_barrier()
; #define PG8_SCHED __builtin_amdgcn_sched_barrier(0)
; template <class Epi, class Sched, bool ALIGN_EPI = true, bool SP2 = true>
; __device__ __forceinline__ void gemm_phase(LAS unsigned char* lds, const Gemm g, const Sched& S, const Epi& E) {
;     ...
;             PG8_LDB(B0, 1, 0); PG8_LDB(B1, 1, 1); PG8_SCHED; PG8_LDA(At, 1, 0); PG8_STAGE(PG8_SA(0, 1), a2 + hstep, voffA);
;             PG8_WAIT_V(8); PG8_WAIT_L(0); PG8_BAR; PG8_MMA(0, 0, At, B0); PG8_MMA(0, 1, At, B1); PG8_BAR; PG8_SCHED;
;             PG8_LDA(At, 1, 1); PG8_STAGE(PG8_SB(1, 0), b3, voffB); PG8_STAGE(PG8_SB(1, 1), b3 + hstep, voffB); PG8_STAGE(PG8_SA(1, 0), a3, voffA);
;             PG8_WAIT_V(8); PG8_WAIT_L(0); PG8_BAR; PG8_MMA(1, 0, At, B0); PG8_MMA(1, 1, At, B1); PG8_BAR; PG8_SCHED;
	s_add_i32 s46, 0, 0x18000
	s_add_i32 s47, 0, 0x1c000
	v_add_u32_e32 v154, s46, v143
	v_add_u32_e32 v182, s47, v143
	ds_read_b128 v[138:141], v154
	ds_read_b128 v[146:149], v154 offset:1024
	ds_read_b128 v[150:153], v154 offset:2048
	ds_read_b128 v[154:157], v154 offset:3072
	ds_read_b128 v[170:173], v182
	ds_read_b128 v[174:177], v182 offset:1024
	ds_read_b128 v[178:181], v182 offset:2048
	ds_read_b128 v[182:185], v182 offset:3072
	s_add_u32 s66, s66, 0x80000
	s_addc_u32 s67, s67, 0
	s_mov_b32 m0, s61
	ds_read_b128 v[186:189], v145 offset:32768
	ds_read_b128 v[190:193], v145 offset:33792
	ds_read_b128 v[194:197], v145 offset:34816
	ds_read_b128 v[198:201], v145 offset:35840
	ds_read_b128 v[202:205], v145 offset:36864
	ds_read_b128 v[206:209], v145 offset:37888
	ds_read_b128 v[210:213], v145 offset:38912
	ds_read_b128 v[214:217], v145 offset:39936
	global_load_lds_dwordx4 v128, s[66:67]
	s_mov_b32 m0, s72
	s_nop 0
	global_load_lds_dwordx4 v130, s[66:67]
	s_waitcnt vmcnt(8)
	s_waitcnt lgkmcnt(0)
	s_barrier
	s_waitcnt lgkmcnt(0)
	v_mfma_f32_16x16x32_bf16 v[124:127], v[138:141], v[186:189], v[124:127]
	v_mfma_f32_16x16x32_bf16 v[120:123], v[150:153], v[186:189], v[120:123]
	v_mfma_f32_16x16x32_bf16 v[108:111], v[138:141], v[194:197], v[108:111]
	v_mfma_f32_16x16x32_bf16 v[104:107], v[150:153], v[194:197], v[104:107]
	v_mfma_f32_16x16x32_bf16 v[92:95], v[138:141], v[202:205], v[92:95]
	v_mfma_f32_16x16x32_bf16 v[88:91], v[150:153], v[202:205], v[88:91]
	v_mfma_f32_16x16x32_bf16 v[76:79], v[138:141], v[210:213], v[76:79]
	v_mfma_f32_16x16x32_bf16 v[72:75], v[150:153], v[210:213], v[72:75]
	v_mfma_f32_16x16x32_bf16 v[124:127], v[146:149], v[190:193], v[124:127]
	v_mfma_f32_16x16x32_bf16 v[120:123], v[154:157], v[190:193], v[120:123]
	v_mfma_f32_16x16x32_bf16 v[108:111], v[146:149], v[198:201], v[108:111]
	v_mfma_f32_16x16x32_bf16 v[104:107], v[154:157], v[198:201], v[104:107]
	v_mfma_f32_16x16x32_bf16 v[92:95], v[146:149], v[206:209], v[92:95]
	v_mfma_f32_16x16x32_bf16 v[88:91], v[154:157], v[206:209], v[88:91]
	v_mfma_f32_16x16x32_bf16 v[76:79], v[146:149], v[214:217], v[76:79]
	v_mfma_f32_16x16x32_bf16 v[72:75], v[154:157], v[214:217], v[72:75]
	v_mfma_f32_16x16x32_bf16 v[116:119], v[170:173], v[186:189], v[116:119]
	v_mfma_f32_16x16x32_bf16 v[112:115], v[178:181], v[186:189], v[112:115]
	v_mfma_f32_16x16x32_bf16 v[100:103], v[170:173], v[194:197], v[100:103]
	v_mfma_f32_16x16x32_bf16 v[96:99], v[178:181], v[194:197], v[96:99]
	v_mfma_f32_16x16x32_bf16 v[84:87], v[170:173], v[202:205], v[84:87]
	v_mfma_f32_16x16x32_bf16 v[80:83], v[178:181], v[202:205], v[80:83]
	v_mfma_f32_16x16x32_bf16 v[68:71], v[170:173], v[210:213], v[68:71]
	v_mfma_f32_16x16x32_bf16 v[64:67], v[178:181], v[210:213], v[64:67]
	v_mfma_f32_16x16x32_bf16 v[116:119], v[174:177], v[190:193], v[116:119]
	v_mfma_f32_16x16x32_bf16 v[112:115], v[182:185], v[190:193], v[112:115]
	v_mfma_f32_16x16x32_bf16 v[100:103], v[174:177], v[198:201], v[100:103]
	v_mfma_f32_16x16x32_bf16 v[96:99], v[182:185], v[198:201], v[96:99]
	v_mfma_f32_16x16x32_bf16 v[84:87], v[174:177], v[206:209], v[84:87]
	v_mfma_f32_16x16x32_bf16 v[80:83], v[182:185], v[206:209], v[80:83]
	v_mfma_f32_16x16x32_bf16 v[68:71], v[174:177], v[214:217], v[68:71]
	v_mfma_f32_16x16x32_bf16 v[64:67], v[182:185], v[214:217], v[64:67]
	s_barrier
	s_add_i32 s46, s46, s43
	s_mov_b32 m0, s46
	ds_read_b128 v[186:189], v145 offset:49152
	ds_read_b128 v[190:193], v145 offset:50176
	ds_read_b128 v[194:197], v145 offset:51200
	ds_read_b128 v[198:201], v145 offset:52224
	ds_read_b128 v[202:205], v145 offset:53248
	ds_read_b128 v[206:209], v145 offset:54272
	ds_read_b128 v[210:213], v145 offset:55296
	ds_read_b128 v[214:217], v145 offset:56320
	s_add_u32 s98, s24, 0x80
	s_addc_u32 s99, s25, 0
	global_load_lds_dwordx4 v160, s[98:99]
	s_add_i32 m0, s46, 0x2000
	s_add_u32 s24, s24, 0x80080
	s_addc_u32 s25, s25, 0
	s_add_i32 s46, s47, s43
	global_load_lds_dwordx4 v132, s[98:99]
	s_mov_b32 m0, s46
	s_nop 0
	global_load_lds_dwordx4 v160, s[24:25]
	s_add_i32 m0, s46, 0x2000
	s_nop 0
	global_load_lds_dwordx4 v132, s[24:25]
	s_mov_b32 m0, s73
	s_nop 0
	s_add_u32 s98, s66, 0xfff80080
	s_addc_u32 s99, s67, -1
	global_load_lds_dwordx4 v128, s[98:99]
	s_mov_b32 m0, s79
	s_nop 0
	global_load_lds_dwordx4 v130, s[98:99]
	s_waitcnt vmcnt(8)
	s_waitcnt lgkmcnt(0)
	s_barrier
	s_waitcnt lgkmcnt(0)
	v_mfma_f32_16x16x32_bf16 v[60:63], v[138:141], v[186:189], v[60:63]
	v_mfma_f32_16x16x32_bf16 v[56:59], v[150:153], v[186:189], v[56:59]
	v_mfma_f32_16x16x32_bf16 v[44:47], v[138:141], v[194:197], v[44:47]
	v_mfma_f32_16x16x32_bf16 v[40:43], v[150:153], v[194:197], v[40:43]
	v_mfma_f32_16x16x32_bf16 v[28:31], v[138:141], v[202:205], v[28:31]
	v_mfma_f32_16x16x32_bf16 v[24:27], v[150:153], v[202:205], v[24:27]
	v_mfma_f32_16x16x32_bf16 v[12:15], v[138:141], v[210:213], v[12:15]
	v_mfma_f32_16x16x32_bf16 v[8:11], v[150:153], v[210:213], v[8:11]
	v_mfma_f32_16x16x32_bf16 v[60:63], v[146:149], v[190:193], v[60:63]
	v_mfma_f32_16x16x32_bf16 v[56:59], v[154:157], v[190:193], v[56:59]
	v_mfma_f32_16x16x32_bf16 v[44:47], v[146:149], v[198:201], v[44:47]
	v_mfma_f32_16x16x32_bf16 v[40:43], v[154:157], v[198:201], v[40:43]
	v_mfma_f32_16x16x32_bf16 v[28:31], v[146:149], v[206:209], v[28:31]
	v_mfma_f32_16x16x32_bf16 v[24:27], v[154:157], v[206:209], v[24:27]
	v_mfma_f32_16x16x32_bf16 v[12:15], v[146:149], v[214:217], v[12:15]
	v_mfma_f32_16x16x32_bf16 v[8:11], v[154:157], v[214:217], v[8:11]
	v_mfma_f32_16x16x32_bf16 v[52:55], v[170:173], v[186:189], v[52:55]
	v_mfma_f32_16x16x32_bf16 v[48:51], v[178:181], v[186:189], v[48:51]
	v_mfma_f32_16x16x32_bf16 v[36:39], v[170:173], v[194:197], v[36:39]
	v_mfma_f32_16x16x32_bf16 v[32:35], v[178:181], v[194:197], v[32:35]
	v_mfma_f32_16x16x32_bf16 v[20:23], v[170:173], v[202:205], v[20:23]
	v_mfma_f32_16x16x32_bf16 v[16:19], v[178:181], v[202:205], v[16:19]
	v_mfma_f32_16x16x32_bf16 v[4:7], v[170:173], v[210:213], v[4:7]
	v_mfma_f32_16x16x32_bf16 v[0:3], v[178:181], v[210:213], v[0:3]
	v_mfma_f32_16x16x32_bf16 v[52:55], v[174:177], v[190:193], v[52:55]
	v_mfma_f32_16x16x32_bf16 v[48:51], v[182:185], v[190:193], v[48:51]
	v_mfma_f32_16x16x32_bf16 v[36:39], v[174:177], v[198:201], v[36:39]
	v_mfma_f32_16x16x32_bf16 v[32:35], v[182:185], v[198:201], v[32:35]
	v_mfma_f32_16x16x32_bf16 v[20:23], v[174:177], v[206:209], v[20:23]
	v_mfma_f32_16x16x32_bf16 v[16:19], v[182:185], v[206:209], v[16:19]
	v_mfma_f32_16x16x32_bf16 v[4:7], v[174:177], v[214:217], v[4:7]
	v_mfma_f32_16x16x32_bf16 v[0:3], v[182:185], v[214:217], v[0:3]
	s_barrier
	s_add_i32 s93, s93, 2
	s_add_u32 s62, s62, 0x100
	s_addc_u32 s63, s63, 0
	s_add_u32 s91, s91, 0x100
	s_addc_u32 s92, s92, 0
	s_cmp_gt_u32 s93, 29
	s_cbranch_scc0 .LBB0_93
	s_setprio 0
	s_and_b64 vcc, exec, s[16:17]
	s_movk_i32 s91, 0x161
	s_movk_i32 s92, 0x7ff
	s_cbranch_vccz .LBB0_96
	s_barrier

; #define PG8_STAGE(bufoff, gbase, voff) do { _Pragma("unroll") for (int _i = 0; _i < 2; ++_i) \
;         __builtin_amdgcn_global_load_lds((const unsigned*)((const char*)(gbase) + (voff)[_i]), (LAS unsigned*)(lds + (bufoff) + ldsw + _i * 8192), 16, 0, 0); } while (0)
; #define PG8_LDA(dst, b, h) do { _Pragma("unroll") for (int m = 0; m < 4; ++m) _Pragma("unroll") for (int k = 0; k < 2; ++k) dst[m][k] = *(const LAS bf16x8*)(lds + PG8_SA(b, h) + aoff + m * 2048 + k * 1024); } while (0)
; #define PG8_LDB(dst, b, h) do { _Pragma("unroll") for (int n = 0; n < 2; ++n) _Pragma("unroll") for (int k = 0; k < 2; ++k) dst[n][k] = *(const LAS bf16x8*)(lds + PG8_SB(b, h) + boff + n * 2048 + k * 1024); } while (0)
; #define PG8_WAIT_V(n) asm volatile("s_waitcnt vmcnt(" #n ")" ::: "memory")
; #define PG8_WAIT_L(n) asm volatile("s_waitcnt lgkmcnt(" #n ")" ::: "memory")
; #define PG8_BAR __builtin_amdgcn_s_barrier()
; #define PG8_SCHED __builtin_amdgcn_sched_barrier(0)
; template <class Epi, class Sched, bool ALIGN_EPI = true, bool SP2 = true>
; __device__ __forceinline__ void gemm_phase(LAS unsigned char* lds, const Gemm g, const Sched& S, const Epi& E) {
;     ...
;     for (;;) {
;         const bool has_next = S.next(ui + 1, nxt);
;         const char* nA = has_next ? (const char*)g.A + (size_t)nxt.pm * tstep : cA; const char* nB = has_next ? (const char*)g.Bt + (size_t)nxt.pn * tstep : cB;
;         for (int t = 0; t < nt; t += 2) {
;             const bool last = (t == nt - 2);
;             const char* a1 = cA + (size_t)(t + 1) * kstep;
;             const char* a2 = last ? nA : cA + (size_t)(t + 2) * kstep; const char* b2 = last ? nB : cB + (size_t)(t + 2) * kstep;
;             const char* a3 = a2 + kstep; const char* b3 = b2 + kstep;
;             if constexpr (SP2) {
;             PG8_LDB(B0, 0, 0); PG8_LDB(B1, 0, 1); PG8_SCHED; PG8_LDA(At, 0, 0); PG8_STAGE(PG8_SA(1, 1), a1 + hstep, voffA);
;             PG8_WAIT_V(8); PG8_WAIT_L(0); PG8_BAR; PG8_MMA(0, 0, At, B0); PG8_MMA(0, 1, At, B1); PG8_BAR; PG8_SCHED;
;     ...
; #pragma unroll
;         for (int a = 0; a < 2; ++a)
; #pragma unroll
;             for (int b = 0; b < 2; ++b)
; #pragma unroll
;                 for (int m = 0; m < 4; ++m)
; #pragma unroll
;                     for (int n = 0; n < 2; ++n) acc[a][b][m][n] = (f32x4){0.f, 0.f, 0.f, 0.f};
.LBB0_116:
	s_ashr_i32 s19, s18, 31
	s_lshl_b64 s[2:3], s[18:19], 20
	s_add_u32 s30, s45, s2
	s_addc_u32 s31, s72, s3
	s_and_b64 s[2:3], s[54:55], exec
	s_cselect_b32 s2, s31, s25
	s_cselect_b32 s3, s30, s24
	s_ashr_i32 s17, s16, 31
	s_lshl_b64 s[52:53], s[16:17], 20
	s_add_u32 s52, s42, s52
	s_addc_u32 s53, s43, s53
	s_and_b64 s[62:63], s[54:55], exec
	s_cselect_b32 s17, s53, s67
	s_cselect_b32 s19, s52, s66
	s_add_u32 s62, s24, 0x80080
	s_addc_u32 s63, s25, 0
	s_add_u32 s94, s66, 0x100
	v_mov_b32_e32 v0, 0
	s_addc_u32 s95, s67, 0
	s_mov_b32 s96, -2
	v_mov_b32_e32 v1, v0
	v_mov_b32_e32 v2, v0
	v_mov_b32_e32 v3, v0
	v_mov_b32_e32 v4, v0
	v_mov_b32_e32 v5, v0
	v_mov_b32_e32 v6, v0
	v_mov_b32_e32 v7, v0
	v_mov_b32_e32 v16, v0
	v_mov_b32_e32 v17, v0
	v_mov_b32_e32 v18, v0
	v_mov_b32_e32 v19, v0
	v_mov_b32_e32 v20, v0
	v_mov_b32_e32 v21, v0
	v_mov_b32_e32 v22, v0
	v_mov_b32_e32 v23, v0
	v_mov_b32_e32 v32, v0
	v_mov_b32_e32 v33, v0
	v_mov_b32_e32 v34, v0
	v_mov_b32_e32 v35, v0
	s_waitcnt vmcnt(0)
	v_mov_b32_e32 v36, v0
	v_mov_b32_e32 v37, v0
	v_mov_b32_e32 v38, v0
	v_mov_b32_e32 v39, v0
	s_waitcnt vmcnt(0)
	v_mov_b32_e32 v48, v0
	v_mov_b32_e32 v49, v0
	v_mov_b32_e32 v50, v0
	v_mov_b32_e32 v51, v0
	v_mov_b32_e32 v52, v0
	v_mov_b32_e32 v53, v0
	v_mov_b32_e32 v54, v0
	v_mov_b32_e32 v55, v0
	v_mov_b32_e32 v8, v0
	v_mov_b32_e32 v9, v0
	v_mov_b32_e32 v10, v0
	v_mov_b32_e32 v11, v0
	v_mov_b32_e32 v12, v0
	v_mov_b32_e32 v13, v0
	v_mov_b32_e32 v14, v0
	v_mov_b32_e32 v15, v0
	v_mov_b32_e32 v24, v0
	v_mov_b32_e32 v25, v0
	v_mov_b32_e32 v26, v0
	v_mov_b32_e32 v27, v0
	v_mov_b32_e32 v28, v0
	v_mov_b32_e32 v29, v0
	v_mov_b32_e32 v30, v0
	v_mov_b32_e32 v31, v0
	v_mov_b32_e32 v40, v0
	v_mov_b32_e32 v41, v0
	v_mov_b32_e32 v42, v0
	v_mov_b32_e32 v43, v0
	v_mov_b32_e32 v44, v0
	v_mov_b32_e32 v45, v0
	v_mov_b32_e32 v46, v0
	v_mov_b32_e32 v47, v0
	v_mov_b32_e32 v56, v0
	v_mov_b32_e32 v57, v0
	v_mov_b32_e32 v58, v0
	v_mov_b32_e32 v59, v0
	v_mov_b32_e32 v60, v0
	v_mov_b32_e32 v61, v0
	v_mov_b32_e32 v62, v0
	v_mov_b32_e32 v63, v0
	v_mov_b32_e32 v64, v0
	v_mov_b32_e32 v65, v0
	v_mov_b32_e32 v66, v0
	v_mov_b32_e32 v67, v0
	v_mov_b32_e32 v68, v0
	v_mov_b32_e32 v69, v0
	v_mov_b32_e32 v70, v0
	v_mov_b32_e32 v71, v0
	v_mov_b32_e32 v80, v0
	v_mov_b32_e32 v81, v0
	v_mov_b32_e32 v82, v0
	v_mov_b32_e32 v83, v0
	v_mov_b32_e32 v84, v0
	v_mov_b32_e32 v85, v0
	v_mov_b32_e32 v86, v0
	v_mov_b32_e32 v87, v0
	v_mov_b32_e32 v96, v0
	v_mov_b32_e32 v97, v0
	v_mov_b32_e32 v98, v0
	v_mov_b32_e32 v99, v0
	v_mov_b32_e32 v100, v0
	v_mov_b32_e32 v101, v0
	v_mov_b32_e32 v102, v0
	v_mov_b32_e32 v103, v0
	v_mov_b32_e32 v112, v0
	v_mov_b32_e32 v113, v0
	v_mov_b32_e32 v114, v0
	v_mov_b32_e32 v115, v0
	v_mov_b32_e32 v116, v0
	v_mov_b32_e32 v117, v0
	v_mov_b32_e32 v118, v0
	v_mov_b32_e32 v119, v0
	v_mov_b32_e32 v72, v0
	v_mov_b32_e32 v73, v0
	v_mov_b32_e32 v74, v0
	v_mov_b32_e32 v75, v0
	v_mov_b32_e32 v76, v0
	v_mov_b32_e32 v77, v0
	v_mov_b32_e32 v78, v0
	v_mov_b32_e32 v79, v0
	v_mov_b32_e32 v88, v0
	v_mov_b32_e32 v89, v0
	v_mov_b32_e32 v90, v0
	v_mov_b32_e32 v91, v0
	v_mov_b32_e32 v92, v0
	v_mov_b32_e32 v93, v0
	v_mov_b32_e32 v94, v0
	v_mov_b32_e32 v95, v0
	v_mov_b32_e32 v104, v0
	v_mov_b32_e32 v105, v0
	v_mov_b32_e32 v106, v0
	v_mov_b32_e32 v107, v0
	v_mov_b32_e32 v108, v0
	v_mov_b32_e32 v109, v0
	v_mov_b32_e32 v110, v0
	v_mov_b32_e32 v111, v0
	v_mov_b32_e32 v120, v0
	v_mov_b32_e32 v121, v0
	v_mov_b32_e32 v122, v0
	v_mov_b32_e32 v123, v0
	v_mov_b32_e32 v124, v0
	v_mov_b32_e32 v125, v0
	v_mov_b32_e32 v126, v0
	v_mov_b32_e32 v127, v0
	v_lshrrev_b32_e32 v226, 8, v238
	v_cmp_ne_u32_e64 s[98:99], 0, v226
	s_nop 3
	s_and_b64 s[98:99], s[98:99], exec
	s_cbranch_scc0 .Lprio_skip_117
	s_setprio 1
.Lprio_skip_117:
.LBB0_117:
	s_add_u32 s24, s62, 0xfff80080
	s_addc_u32 s25, s63, -1
	s_add_i32 s46, 0, 0x10000
	s_cmp_eq_u32 s96, 28
	s_cselect_b32 s67, s2, s25
	s_cselect_b32 s66, s3, s24
	s_cselect_b32 s25, s17, s95
	s_cselect_b32 s24, s19, s94
	s_add_i32 s47, 0, 0x14000
	v_add_u32_e32 v154, s46, v143
	v_add_u32_e32 v158, s47, v143
	ds_read_b128 v[138:141], v154
	ds_read_b128 v[146:149], v154 offset:1024
	ds_read_b128 v[150:153], v154 offset:2048
	ds_read_b128 v[154:157], v154 offset:3072
	ds_read_b128 v[170:173], v158
	ds_read_b128 v[174:177], v158 offset:1024
	ds_read_b128 v[178:181], v158 offset:2048
	ds_read_b128 v[182:185], v158 offset:3072
	s_add_i32 m0, s61, 0xc000
	ds_read_b128 v[186:189], v145
	ds_read_b128 v[190:193], v145 offset:1024
	ds_read_b128 v[194:197], v145 offset:2048
	ds_read_b128 v[198:201], v145 offset:3072
	ds_read_b128 v[202:205], v145 offset:4096
	ds_read_b128 v[206:209], v145 offset:5120
	ds_read_b128 v[210:213], v145 offset:6144
	ds_read_b128 v[214:217], v145 offset:7168
	global_load_lds_dwordx4 v134, s[62:63]
	s_add_i32 m0, s61, 0xe000
	s_nop 0
	global_load_lds_dwordx4 v136, s[62:63]
	s_waitcnt vmcnt(8)
	s_waitcnt lgkmcnt(0)
	s_barrier
; #define PG8_STAGE(bufoff, gbase, voff) do { _Pragma("unroll") for (int _i = 0; _i < 2; ++_i) \
;         __builtin_amdgcn_global_load_lds((const unsigned*)((const char*)(gbase) + (voff)[_i]), (LAS unsigned*)(lds + (bufoff) + ldsw + _i * 8192), 16, 0, 0); } while (0)
; #define PG8_LDA(dst, b, h) do { _Pragma("unroll") for (int m = 0; m < 4; ++m) _Pragma("unroll") for (int k = 0; k < 2; ++k) dst[m][k] = *(const LAS bf16x8*)(lds + PG8_SA(b, h) + aoff + m * 2048 + k * 1024); } while (0)
; #define PG8_MMA(ai, bj, At, Bt) do { __builtin_amdgcn_s_setprio(1); _Pragma("unroll") for (int m = 0; m < 4; ++m) _Pragma("unroll") for (int n = 0; n < 2; ++n) _Pragma("unroll") for (int k = 0; k < 2; ++k) \
;         acc[ai][bj][m][n] = __builtin_amdgcn_mfma_f32_16x16x32_bf16(Bt[n][k], At[m][k], acc[ai][bj][m][n], 0, 0, 0); __builtin_amdgcn_s_setprio(0); } while (0)
; #define PG8_WAIT_V(n) asm volatile("s_waitcnt vmcnt(" #n ")" ::: "memory")
; #define PG8_WAIT_L(n) asm volatile("s_waitcnt lgkmcnt(" #n ")" ::: "memory")
; #define PG8_BAR __builtin_amdgcn_s_barrier()
; #define PG8_SCHED __builtin_amdgcn_sched_barrier(0)
; template <class Epi, class Sched, bool ALIGN_EPI = true, bool SP2 = true>
; __device__ __forceinline__ void gemm_phase(LAS unsigned char* lds, const Gemm g, const Sched& S, const Epi& E) {
;     ...
;             PG8_WAIT_V(8); PG8_WAIT_L(0); PG8_BAR; PG8_MMA(0, 0, At, B0); PG8_MMA(0, 1, At, B1); PG8_BAR; PG8_SCHED;
;             PG8_LDA(At, 0, 1); PG8_STAGE(PG8_SB(0, 0), b2, voffB); PG8_STAGE(PG8_SB(0, 1), b2 + hstep, voffB); PG8_STAGE(PG8_SA(0, 0), a2, voffA);
;             PG8_WAIT_V(8); PG8_WAIT_L(0); PG8_BAR; PG8_MMA(1, 0, At, B0); PG8_MMA(1, 1, At, B1); PG8_BAR; PG8_SCHED;
	s_waitcnt lgkmcnt(0)
	v_mfma_f32_16x16x32_bf16 v[124:127], v[138:141], v[186:189], v[124:127]
	v_mfma_f32_16x16x32_bf16 v[120:123], v[150:153], v[186:189], v[120:123]
	v_mfma_f32_16x16x32_bf16 v[108:111], v[138:141], v[194:197], v[108:111]
	v_mfma_f32_16x16x32_bf16 v[104:107], v[150:153], v[194:197], v[104:107]
	v_mfma_f32_16x16x32_bf16 v[92:95], v[138:141], v[202:205], v[92:95]
	v_mfma_f32_16x16x32_bf16 v[88:91], v[150:153], v[202:205], v[88:91]
	v_mfma_f32_16x16x32_bf16 v[76:79], v[138:141], v[210:213], v[76:79]
	v_mfma_f32_16x16x32_bf16 v[72:75], v[150:153], v[210:213], v[72:75]
	v_mfma_f32_16x16x32_bf16 v[124:127], v[146:149], v[190:193], v[124:127]
	v_mfma_f32_16x16x32_bf16 v[120:123], v[154:157], v[190:193], v[120:123]
	v_mfma_f32_16x16x32_bf16 v[108:111], v[146:149], v[198:201], v[108:111]
	v_mfma_f32_16x16x32_bf16 v[104:107], v[154:157], v[198:201], v[104:107]
	v_mfma_f32_16x16x32_bf16 v[92:95], v[146:149], v[206:209], v[92:95]
	v_mfma_f32_16x16x32_bf16 v[88:91], v[154:157], v[206:209], v[88:91]
	v_mfma_f32_16x16x32_bf16 v[76:79], v[146:149], v[214:217], v[76:79]
	v_mfma_f32_16x16x32_bf16 v[72:75], v[154:157], v[214:217], v[72:75]
	v_mfma_f32_16x16x32_bf16 v[116:119], v[170:173], v[186:189], v[116:119]
	v_mfma_f32_16x16x32_bf16 v[112:115], v[178:181], v[186:189], v[112:115]
	v_mfma_f32_16x16x32_bf16 v[100:103], v[170:173], v[194:197], v[100:103]
	v_mfma_f32_16x16x32_bf16 v[96:99], v[178:181], v[194:197], v[96:99]
	v_mfma_f32_16x16x32_bf16 v[84:87], v[170:173], v[202:205], v[84:87]
	v_mfma_f32_16x16x32_bf16 v[80:83], v[178:181], v[202:205], v[80:83]
	v_mfma_f32_16x16x32_bf16 v[68:71], v[170:173], v[210:213], v[68:71]
	v_mfma_f32_16x16x32_bf16 v[64:67], v[178:181], v[210:213], v[64:67]
	v_mfma_f32_16x16x32_bf16 v[116:119], v[174:177], v[190:193], v[116:119]
	v_mfma_f32_16x16x32_bf16 v[112:115], v[182:185], v[190:193], v[112:115]
	v_mfma_f32_16x16x32_bf16 v[100:103], v[174:177], v[198:201], v[100:103]
	v_mfma_f32_16x16x32_bf16 v[96:99], v[182:185], v[198:201], v[96:99]
	v_mfma_f32_16x16x32_bf16 v[84:87], v[174:177], v[206:209], v[84:87]
	v_mfma_f32_16x16x32_bf16 v[80:83], v[182:185], v[206:209], v[80:83]
	v_mfma_f32_16x16x32_bf16 v[68:71], v[174:177], v[214:217], v[68:71]
	v_mfma_f32_16x16x32_bf16 v[64:67], v[182:185], v[214:217], v[64:67]
	s_barrier
	s_add_i32 s46, s46, s44
	s_mov_b32 m0, s46
	ds_read_b128 v[186:189], v145 offset:16384
	ds_read_b128 v[190:193], v145 offset:17408
	ds_read_b128 v[194:197], v145 offset:18432
	ds_read_b128 v[198:201], v145 offset:19456
	ds_read_b128 v[202:205], v145 offset:20480
	ds_read_b128 v[206:209], v145 offset:21504
	ds_read_b128 v[210:213], v145 offset:22528
	ds_read_b128 v[214:217], v145 offset:23552
	global_load_lds_dwordx4 v160, s[24:25]
	s_add_i32 m0, s46, 0x2000
	s_add_u32 vcc_lo, s24, 0x80000
	s_addc_u32 vcc_hi, s25, 0
	s_add_i32 s46, s47, s44
	global_load_lds_dwordx4 v132, s[24:25]
	v_lshl_add_u64 v[218:219], vcc, 0, v[160:161]
	s_mov_b32 m0, s46
	s_nop 0
	global_load_lds_dwordx4 v[218:219], off
	v_lshl_add_u64 v[218:219], vcc, 0, v[132:133]
	s_add_i32 m0, s46, 0x2000
	s_nop 0
	global_load_lds_dwordx4 v[218:219], off
	s_mov_b32 m0, s61
	s_nop 0
	global_load_lds_dwordx4 v128, s[66:67]
	s_mov_b32 m0, s73
	s_nop 0
	global_load_lds_dwordx4 v130, s[66:67]
	s_waitcnt vmcnt(8)
	s_waitcnt lgkmcnt(0)
	s_barrier
	s_waitcnt lgkmcnt(0)
	v_mfma_f32_16x16x32_bf16 v[60:63], v[138:141], v[186:189], v[60:63]
	v_mfma_f32_16x16x32_bf16 v[56:59], v[150:153], v[186:189], v[56:59]
	v_mfma_f32_16x16x32_bf16 v[44:47], v[138:141], v[194:197], v[44:47]
	v_mfma_f32_16x16x32_bf16 v[40:43], v[150:153], v[194:197], v[40:43]
	v_mfma_f32_16x16x32_bf16 v[28:31], v[138:141], v[202:205], v[28:31]
	v_mfma_f32_16x16x32_bf16 v[24:27], v[150:153], v[202:205], v[24:27]
	v_mfma_f32_16x16x32_bf16 v[12:15], v[138:141], v[210:213], v[12:15]
	v_mfma_f32_16x16x32_bf16 v[8:11], v[150:153], v[210:213], v[8:11]
	v_mfma_f32_16x16x32_bf16 v[60:63], v[146:149], v[190:193], v[60:63]
	v_mfma_f32_16x16x32_bf16 v[56:59], v[154:157], v[190:193], v[56:59]
	v_mfma_f32_16x16x32_bf16 v[44:47], v[146:149], v[198:201], v[44:47]
	v_mfma_f32_16x16x32_bf16 v[40:43], v[154:157], v[198:201], v[40:43]
	v_mfma_f32_16x16x32_bf16 v[28:31], v[146:149], v[206:209], v[28:31]
	v_mfma_f32_16x16x32_bf16 v[24:27], v[154:157], v[206:209], v[24:27]
	v_mfma_f32_16x16x32_bf16 v[12:15], v[146:149], v[214:217], v[12:15]
	v_mfma_f32_16x16x32_bf16 v[8:11], v[154:157], v[214:217], v[8:11]
	v_mfma_f32_16x16x32_bf16 v[52:55], v[170:173], v[186:189], v[52:55]
	v_mfma_f32_16x16x32_bf16 v[48:51], v[178:181], v[186:189], v[48:51]
	v_mfma_f32_16x16x32_bf16 v[36:39], v[170:173], v[194:197], v[36:39]
	v_mfma_f32_16x16x32_bf16 v[32:35], v[178:181], v[194:197], v[32:35]
	v_mfma_f32_16x16x32_bf16 v[20:23], v[170:173], v[202:205], v[20:23]
	v_mfma_f32_16x16x32_bf16 v[16:19], v[178:181], v[202:205], v[16:19]
	v_mfma_f32_16x16x32_bf16 v[4:7], v[170:173], v[210:213], v[4:7]
	v_mfma_f32_16x16x32_bf16 v[0:3], v[178:181], v[210:213], v[0:3]
	v_mfma_f32_16x16x32_bf16 v[52:55], v[174:177], v[190:193], v[52:55]
	v_mfma_f32_16x16x32_bf16 v[48:51], v[182:185], v[190:193], v[48:51]
	v_mfma_f32_16x16x32_bf16 v[36:39], v[174:177], v[198:201], v[36:39]
	v_mfma_f32_16x16x32_bf16 v[32:35], v[182:185], v[198:201], v[32:35]
	v_mfma_f32_16x16x32_bf16 v[20:23], v[174:177], v[206:209], v[20:23]
	v_mfma_f32_16x16x32_bf16 v[16:19], v[182:185], v[206:209], v[16:19]
	v_mfma_f32_16x16x32_bf16 v[4:7], v[174:177], v[214:217], v[4:7]
	v_mfma_f32_16x16x32_bf16 v[0:3], v[182:185], v[214:217], v[0:3]
	s_barrier
; #define PG8_STAGE(bufoff, gbase, voff) do { _Pragma("unroll") for (int _i = 0; _i < 2; ++_i) \
;         __builtin_amdgcn_global_load_lds((const unsigned*)((const char*)(gbase) + (voff)[_i]), (LAS unsigned*)(lds + (bufoff) + ldsw + _i * 8192), 16, 0, 0); } while (0)
; #define PG8_LDA(dst, b, h) do { _Pragma("unroll") for (int m = 0; m < 4; ++m) _Pragma("unroll") for (int k = 0; k < 2; ++k) dst[m][k] = *(const LAS bf16x8*)(lds + PG8_SA(b, h) + aoff + m * 2048 + k * 1024); } while (0)
; #define PG8_LDB(dst, b, h) do { _Pragma("unroll") for (int n = 0; n < 2; ++n) _Pragma("unroll") for (int k = 0; k < 2; ++k) dst[n][k] = *(const LAS bf16x8*)(lds + PG8_SB(b, h) + boff + n * 2048 + k * 1024); } while (0)
; #define PG8_MMA(ai, bj, At, Bt) do { __builtin_amdgcn_s_setprio(1); _Pragma("unroll") for (int m = 0; m < 4; ++m) _Pragma("unroll") for (int n = 0; n < 2; ++n) _Pragma("unroll") for (int k = 0; k < 2; ++k) \
;         acc[ai][bj][m][n] = __builtin_amdgcn_mfma_f32_16x16x32_bf16(Bt[n][k], At[m][k], acc[ai][bj][m][n], 0, 0, 0); __builtin_amdgcn_s_setprio(0); } while (0)
; #define PG8_WAIT_V(n) asm volatile("s_waitcnt vmcnt(" #n ")" ::: "memory")
; #define PG8_WAIT_L(n) asm volatile("s_waitcnt lgkmcnt(" #n ")" ::: "memory")
; #define PG8_BAR __builtin_amdgcn_s_barrier()
; #define PG8_SCHED __builtin_amdgcn_sched_barrier(0)
; template <class Epi, class Sched, bool ALIGN_EPI = true, bool SP2 = true>
; __device__ __forceinline__ void gemm_phase(LAS unsigned char* lds, const Gemm g, const Sched& S, const Epi& E) {
;     ...
;             PG8_LDB(B0, 1, 0); PG8_LDB(B1, 1, 1); PG8_SCHED; PG8_LDA(At, 1, 0); PG8_STAGE(PG8_SA(0, 1), a2 + hstep, voffA);
;             PG8_WAIT_V(8); PG8_WAIT_L(0); PG8_BAR; PG8_MMA(0, 0, At, B0); PG8_MMA(0, 1, At, B1); PG8_BAR; PG8_SCHED;
;             PG8_LDA(At, 1, 1); PG8_STAGE(PG8_SB(1, 0), b3, voffB); PG8_STAGE(PG8_SB(1, 1), b3 + hstep, voffB); PG8_STAGE(PG8_SA(1, 0), a3, voffA);
;             PG8_WAIT_V(8); PG8_WAIT_L(0); PG8_BAR; PG8_MMA(1, 0, At, B0); PG8_MMA(1, 1, At, B1); PG8_BAR; PG8_SCHED;
	s_add_i32 s46, 0, 0x18000
	s_add_i32 s47, 0, 0x1c000
	v_add_u32_e32 v154, s46, v143
	v_add_u32_e32 v182, s47, v143
	ds_read_b128 v[138:141], v154
	ds_read_b128 v[146:149], v154 offset:1024
	ds_read_b128 v[150:153], v154 offset:2048
	ds_read_b128 v[154:157], v154 offset:3072
	ds_read_b128 v[170:173], v182
	ds_read_b128 v[174:177], v182 offset:1024
	ds_read_b128 v[178:181], v182 offset:2048
	ds_read_b128 v[182:185], v182 offset:3072
	s_add_u32 s66, s66, 0x80000
	s_addc_u32 s67, s67, 0
	s_mov_b32 m0, s79
	ds_read_b128 v[186:189], v145 offset:32768
	ds_read_b128 v[190:193], v145 offset:33792
	ds_read_b128 v[194:197], v145 offset:34816
	ds_read_b128 v[198:201], v145 offset:35840
	ds_read_b128 v[202:205], v145 offset:36864
	ds_read_b128 v[206:209], v145 offset:37888
	ds_read_b128 v[210:213], v145 offset:38912
	ds_read_b128 v[214:217], v145 offset:39936
	global_load_lds_dwordx4 v128, s[66:67]
	s_mov_b32 m0, s82
	s_nop 0
	global_load_lds_dwordx4 v130, s[66:67]
	s_waitcnt vmcnt(8)
	s_waitcnt lgkmcnt(0)
	s_barrier
	s_waitcnt lgkmcnt(0)
	v_mfma_f32_16x16x32_bf16 v[124:127], v[138:141], v[186:189], v[124:127]
	v_mfma_f32_16x16x32_bf16 v[120:123], v[150:153], v[186:189], v[120:123]
	v_mfma_f32_16x16x32_bf16 v[108:111], v[138:141], v[194:197], v[108:111]
	v_mfma_f32_16x16x32_bf16 v[104:107], v[150:153], v[194:197], v[104:107]
	v_mfma_f32_16x16x32_bf16 v[92:95], v[138:141], v[202:205], v[92:95]
	v_mfma_f32_16x16x32_bf16 v[88:91], v[150:153], v[202:205], v[88:91]
	v_mfma_f32_16x16x32_bf16 v[76:79], v[138:141], v[210:213], v[76:79]
	v_mfma_f32_16x16x32_bf16 v[72:75], v[150:153], v[210:213], v[72:75]
	v_mfma_f32_16x16x32_bf16 v[124:127], v[146:149], v[190:193], v[124:127]
	v_mfma_f32_16x16x32_bf16 v[120:123], v[154:157], v[190:193], v[120:123]
	v_mfma_f32_16x16x32_bf16 v[108:111], v[146:149], v[198:201], v[108:111]
	v_mfma_f32_16x16x32_bf16 v[104:107], v[154:157], v[198:201], v[104:107]
	v_mfma_f32_16x16x32_bf16 v[92:95], v[146:149], v[206:209], v[92:95]
	v_mfma_f32_16x16x32_bf16 v[88:91], v[154:157], v[206:209], v[88:91]
	v_mfma_f32_16x16x32_bf16 v[76:79], v[146:149], v[214:217], v[76:79]
	v_mfma_f32_16x16x32_bf16 v[72:75], v[154:157], v[214:217], v[72:75]
	v_mfma_f32_16x16x32_bf16 v[116:119], v[170:173], v[186:189], v[116:119]
	v_mfma_f32_16x16x32_bf16 v[112:115], v[178:181], v[186:189], v[112:115]
	v_mfma_f32_16x16x32_bf16 v[100:103], v[170:173], v[194:197], v[100:103]
	v_mfma_f32_16x16x32_bf16 v[96:99], v[178:181], v[194:197], v[96:99]
	v_mfma_f32_16x16x32_bf16 v[84:87], v[170:173], v[202:205], v[84:87]
	v_mfma_f32_16x16x32_bf16 v[80:83], v[178:181], v[202:205], v[80:83]
	v_mfma_f32_16x16x32_bf16 v[68:71], v[170:173], v[210:213], v[68:71]
	v_mfma_f32_16x16x32_bf16 v[64:67], v[178:181], v[210:213], v[64:67]
	v_mfma_f32_16x16x32_bf16 v[116:119], v[174:177], v[190:193], v[116:119]
	v_mfma_f32_16x16x32_bf16 v[112:115], v[182:185], v[190:193], v[112:115]
	v_mfma_f32_16x16x32_bf16 v[100:103], v[174:177], v[198:201], v[100:103]
	v_mfma_f32_16x16x32_bf16 v[96:99], v[182:185], v[198:201], v[96:99]
	v_mfma_f32_16x16x32_bf16 v[84:87], v[174:177], v[206:209], v[84:87]
	v_mfma_f32_16x16x32_bf16 v[80:83], v[182:185], v[206:209], v[80:83]
	v_mfma_f32_16x16x32_bf16 v[68:71], v[174:177], v[214:217], v[68:71]
	v_mfma_f32_16x16x32_bf16 v[64:67], v[182:185], v[214:217], v[64:67]
	s_barrier
	s_add_i32 s46, s46, s44
	s_mov_b32 m0, s46
	ds_read_b128 v[186:189], v145 offset:49152
	ds_read_b128 v[190:193], v145 offset:50176
	ds_read_b128 v[194:197], v145 offset:51200
	ds_read_b128 v[198:201], v145 offset:52224
	ds_read_b128 v[202:205], v145 offset:53248
	ds_read_b128 v[206:209], v145 offset:54272
	ds_read_b128 v[210:213], v145 offset:55296
	ds_read_b128 v[214:217], v145 offset:56320
	s_add_u32 s98, s24, 0x80
	s_addc_u32 s99, s25, 0
	global_load_lds_dwordx4 v160, s[98:99]
	s_add_i32 m0, s46, 0x2000
	s_add_u32 s24, s24, 0x80080
	s_addc_u32 s25, s25, 0
	s_add_i32 s46, s47, s44
	global_load_lds_dwordx4 v132, s[98:99]
	s_mov_b32 m0, s46
	s_nop 0
	global_load_lds_dwordx4 v160, s[24:25]
	s_add_i32 m0, s46, 0x2000
	s_nop 0
	global_load_lds_dwordx4 v132, s[24:25]
	s_mov_b32 m0, s83
	s_nop 0
	s_add_u32 s98, s66, 0xfff80080
	s_addc_u32 s99, s67, -1
	global_load_lds_dwordx4 v128, s[98:99]
	s_mov_b32 m0, s90
	s_nop 0
	global_load_lds_dwordx4 v130, s[98:99]
	s_waitcnt vmcnt(8)
	s_waitcnt lgkmcnt(0)
	s_barrier
	s_waitcnt lgkmcnt(0)
	v_mfma_f32_16x16x32_bf16 v[60:63], v[138:141], v[186:189], v[60:63]
	v_mfma_f32_16x16x32_bf16 v[56:59], v[150:153], v[186:189], v[56:59]
	v_mfma_f32_16x16x32_bf16 v[44:47], v[138:141], v[194:197], v[44:47]
	v_mfma_f32_16x16x32_bf16 v[40:43], v[150:153], v[194:197], v[40:43]
	v_mfma_f32_16x16x32_bf16 v[28:31], v[138:141], v[202:205], v[28:31]
	v_mfma_f32_16x16x32_bf16 v[24:27], v[150:153], v[202:205], v[24:27]
	v_mfma_f32_16x16x32_bf16 v[12:15], v[138:141], v[210:213], v[12:15]
	v_mfma_f32_16x16x32_bf16 v[8:11], v[150:153], v[210:213], v[8:11]
	v_mfma_f32_16x16x32_bf16 v[60:63], v[146:149], v[190:193], v[60:63]
	v_mfma_f32_16x16x32_bf16 v[56:59], v[154:157], v[190:193], v[56:59]
	v_mfma_f32_16x16x32_bf16 v[44:47], v[146:149], v[198:201], v[44:47]
	v_mfma_f32_16x16x32_bf16 v[40:43], v[154:157], v[198:201], v[40:43]
	v_mfma_f32_16x16x32_bf16 v[28:31], v[146:149], v[206:209], v[28:31]
	v_mfma_f32_16x16x32_bf16 v[24:27], v[154:157], v[206:209], v[24:27]
	v_mfma_f32_16x16x32_bf16 v[12:15], v[146:149], v[214:217], v[12:15]
	v_mfma_f32_16x16x32_bf16 v[8:11], v[154:157], v[214:217], v[8:11]
	v_mfma_f32_16x16x32_bf16 v[52:55], v[170:173], v[186:189], v[52:55]
	v_mfma_f32_16x16x32_bf16 v[48:51], v[178:181], v[186:189], v[48:51]
	v_mfma_f32_16x16x32_bf16 v[36:39], v[170:173], v[194:197], v[36:39]
	v_mfma_f32_16x16x32_bf16 v[32:35], v[178:181], v[194:197], v[32:35]
	v_mfma_f32_16x16x32_bf16 v[20:23], v[170:173], v[202:205], v[20:23]
	v_mfma_f32_16x16x32_bf16 v[16:19], v[178:181], v[202:205], v[16:19]
	v_mfma_f32_16x16x32_bf16 v[4:7], v[170:173], v[210:213], v[4:7]
	v_mfma_f32_16x16x32_bf16 v[0:3], v[178:181], v[210:213], v[0:3]
	v_mfma_f32_16x16x32_bf16 v[52:55], v[174:177], v[190:193], v[52:55]
	v_mfma_f32_16x16x32_bf16 v[48:51], v[182:185], v[190:193], v[48:51]
	v_mfma_f32_16x16x32_bf16 v[36:39], v[174:177], v[198:201], v[36:39]
	v_mfma_f32_16x16x32_bf16 v[32:35], v[182:185], v[198:201], v[32:35]
	v_mfma_f32_16x16x32_bf16 v[20:23], v[174:177], v[206:209], v[20:23]
	v_mfma_f32_16x16x32_bf16 v[16:19], v[182:185], v[206:209], v[16:19]
	v_mfma_f32_16x16x32_bf16 v[4:7], v[174:177], v[214:217], v[4:7]
	v_mfma_f32_16x16x32_bf16 v[0:3], v[182:185], v[214:217], v[0:3]
	s_barrier
	s_add_i32 s96, s96, 2
	s_add_u32 s62, s62, 0x100
	s_addc_u32 s63, s63, 0
	s_add_u32 s94, s94, 0x100
	s_addc_u32 s95, s95, 0
	s_cmp_gt_u32 s96, 29
	s_cbranch_scc0 .LBB0_117
	s_setprio 0
	s_and_b64 vcc, exec, s[10:11]
	s_mov_b64 s[96:97], 0x80000
	s_cbranch_vccz .LBB0_120
	s_barrier

; #define PG8_STAGE(bufoff, gbase, voff) do { _Pragma("unroll") for (int _i = 0; _i < 2; ++_i) \
;         __builtin_amdgcn_global_load_lds((const unsigned*)((const char*)(gbase) + (voff)[_i]), (LAS unsigned*)(lds + (bufoff) + ldsw + _i * 8192), 16, 0, 0); } while (0)
; #define PG8_LDA(dst, b, h) do { _Pragma("unroll") for (int m = 0; m < 4; ++m) _Pragma("unroll") for (int k = 0; k < 2; ++k) dst[m][k] = *(const LAS bf16x8*)(lds + PG8_SA(b, h) + aoff + m * 2048 + k * 1024); } while (0)
; #define PG8_LDB(dst, b, h) do { _Pragma("unroll") for (int n = 0; n < 2; ++n) _Pragma("unroll") for (int k = 0; k < 2; ++k) dst[n][k] = *(const LAS bf16x8*)(lds + PG8_SB(b, h) + boff + n * 2048 + k * 1024); } while (0)
; #define PG8_WAIT_V(n) asm volatile("s_waitcnt vmcnt(" #n ")" ::: "memory")
; #define PG8_WAIT_L(n) asm volatile("s_waitcnt lgkmcnt(" #n ")" ::: "memory")
; #define PG8_BAR __builtin_amdgcn_s_barrier()
; #define PG8_SCHED __builtin_amdgcn_sched_barrier(0)
; template <class Epi, class Sched, bool ALIGN_EPI = true, bool SP2 = true>
; __device__ __forceinline__ void gemm_phase(LAS unsigned char* lds, const Gemm g, const Sched& S, const Epi& E) {
;     ...
;     for (;;) {
;         const bool has_next = S.next(ui + 1, nxt);
;         const char* nA = has_next ? (const char*)g.A + (size_t)nxt.pm * tstep : cA; const char* nB = has_next ? (const char*)g.Bt + (size_t)nxt.pn * tstep : cB;
;         for (int t = 0; t < nt; t += 2) {
;             const bool last = (t == nt - 2);
;             const char* a1 = cA + (size_t)(t + 1) * kstep;
;             const char* a2 = last ? nA : cA + (size_t)(t + 2) * kstep; const char* b2 = last ? nB : cB + (size_t)(t + 2) * kstep;
;             const char* a3 = a2 + kstep; const char* b3 = b2 + kstep;
;             if constexpr (SP2) {
;             PG8_LDB(B0, 0, 0); PG8_LDB(B1, 0, 1); PG8_SCHED; PG8_LDA(At, 0, 0); PG8_STAGE(PG8_SA(1, 1), a1 + hstep, voffA);
;             PG8_WAIT_V(8); PG8_WAIT_L(0); PG8_BAR; PG8_MMA(0, 0, At, B0); PG8_MMA(0, 1, At, B1); PG8_BAR; PG8_SCHED;
;     ...
; #pragma unroll
;         for (int a = 0; a < 2; ++a)
; #pragma unroll
;             for (int b = 0; b < 2; ++b)
; #pragma unroll
;                 for (int m = 0; m < 4; ++m)
; #pragma unroll
;                     for (int n = 0; n < 2; ++n) acc[a][b][m][n] = (f32x4){0.f, 0.f, 0.f, 0.f};
.LBB0_144:
	s_ashr_i32 s53, s52, 31
	s_lshl_b64 s[2:3], s[52:53], 20
	s_add_u32 s54, s8, s2
	s_addc_u32 s55, s9, s3
	s_and_b64 s[2:3], s[6:7], exec
	s_cselect_b32 s2, s55, s25
	s_cselect_b32 s3, s54, s24
	s_ashr_i32 s31, s30, 31
	s_lshl_b64 s[44:45], s[30:31], 20
	s_add_u32 s60, s28, s44
	s_addc_u32 s61, s41, s45
	s_and_b64 s[44:45], s[6:7], exec
	s_cselect_b32 s31, s61, s83
	s_cselect_b32 s44, s60, s82
	s_add_u32 s72, s24, 0x80080
	s_addc_u32 s73, s25, 0
	s_add_u32 s45, s82, 0x100
	v_mov_b32_e32 v0, 0
	s_addc_u32 s53, s83, 0
	s_mov_b32 s95, -2
	s_waitcnt lgkmcnt(0)
	v_mov_b32_e32 v1, v0
	v_mov_b32_e32 v2, v0
	v_mov_b32_e32 v3, v0
	v_mov_b32_e32 v4, v0
	v_mov_b32_e32 v5, v0
	v_mov_b32_e32 v6, v0
	v_mov_b32_e32 v7, v0
	v_mov_b32_e32 v16, v0
	v_mov_b32_e32 v17, v0
	v_mov_b32_e32 v18, v0
	v_mov_b32_e32 v19, v0
	v_mov_b32_e32 v20, v0
	v_mov_b32_e32 v21, v0
	v_mov_b32_e32 v22, v0
	v_mov_b32_e32 v23, v0
	v_mov_b32_e32 v32, v0
	v_mov_b32_e32 v33, v0
	v_mov_b32_e32 v34, v0
	v_mov_b32_e32 v35, v0
	s_waitcnt vmcnt(0)
	v_mov_b32_e32 v36, v0
	v_mov_b32_e32 v37, v0
	v_mov_b32_e32 v38, v0
	v_mov_b32_e32 v39, v0
	s_waitcnt vmcnt(0)
	v_mov_b32_e32 v48, v0
	v_mov_b32_e32 v49, v0
	v_mov_b32_e32 v50, v0
	v_mov_b32_e32 v51, v0
	v_mov_b32_e32 v52, v0
	v_mov_b32_e32 v53, v0
	v_mov_b32_e32 v54, v0
	v_mov_b32_e32 v55, v0
	v_mov_b32_e32 v8, v0
	v_mov_b32_e32 v9, v0
	v_mov_b32_e32 v10, v0
	v_mov_b32_e32 v11, v0
	v_mov_b32_e32 v12, v0
	v_mov_b32_e32 v13, v0
	v_mov_b32_e32 v14, v0
	v_mov_b32_e32 v15, v0
	v_mov_b32_e32 v24, v0
	v_mov_b32_e32 v25, v0
	v_mov_b32_e32 v26, v0
	v_mov_b32_e32 v27, v0
	v_mov_b32_e32 v28, v0
	v_mov_b32_e32 v29, v0
	v_mov_b32_e32 v30, v0
	v_mov_b32_e32 v31, v0
	v_mov_b32_e32 v40, v0
	v_mov_b32_e32 v41, v0
	v_mov_b32_e32 v42, v0
	v_mov_b32_e32 v43, v0
	v_mov_b32_e32 v44, v0
	v_mov_b32_e32 v45, v0
	v_mov_b32_e32 v46, v0
	v_mov_b32_e32 v47, v0
	v_mov_b32_e32 v56, v0
	v_mov_b32_e32 v57, v0
	v_mov_b32_e32 v58, v0
	v_mov_b32_e32 v59, v0
	v_mov_b32_e32 v60, v0
	v_mov_b32_e32 v61, v0
	v_mov_b32_e32 v62, v0
	v_mov_b32_e32 v63, v0
	v_mov_b32_e32 v64, v0
	v_mov_b32_e32 v65, v0
	v_mov_b32_e32 v66, v0
	v_mov_b32_e32 v67, v0
	v_mov_b32_e32 v68, v0
	v_mov_b32_e32 v69, v0
	v_mov_b32_e32 v70, v0
	v_mov_b32_e32 v71, v0
	v_mov_b32_e32 v80, v0
	v_mov_b32_e32 v81, v0
	v_mov_b32_e32 v82, v0
	v_mov_b32_e32 v83, v0
	v_mov_b32_e32 v84, v0
	v_mov_b32_e32 v85, v0
	v_mov_b32_e32 v86, v0
	v_mov_b32_e32 v87, v0
	v_mov_b32_e32 v96, v0
	v_mov_b32_e32 v97, v0
	v_mov_b32_e32 v98, v0
	v_mov_b32_e32 v99, v0
	v_mov_b32_e32 v100, v0
	v_mov_b32_e32 v101, v0
	v_mov_b32_e32 v102, v0
	v_mov_b32_e32 v103, v0
	v_mov_b32_e32 v112, v0
	v_mov_b32_e32 v113, v0
	v_mov_b32_e32 v114, v0
	v_mov_b32_e32 v115, v0
	v_mov_b32_e32 v116, v0
	v_mov_b32_e32 v117, v0
	v_mov_b32_e32 v118, v0
	v_mov_b32_e32 v119, v0
	v_mov_b32_e32 v72, v0
	v_mov_b32_e32 v73, v0
	v_mov_b32_e32 v74, v0
	v_mov_b32_e32 v75, v0
	v_mov_b32_e32 v76, v0
	v_mov_b32_e32 v77, v0
	v_mov_b32_e32 v78, v0
	v_mov_b32_e32 v79, v0
	v_mov_b32_e32 v88, v0
	v_mov_b32_e32 v89, v0
	v_mov_b32_e32 v90, v0
	v_mov_b32_e32 v91, v0
	v_mov_b32_e32 v92, v0
	v_mov_b32_e32 v93, v0
	v_mov_b32_e32 v94, v0
	v_mov_b32_e32 v95, v0
	v_mov_b32_e32 v104, v0
	v_mov_b32_e32 v105, v0
	v_mov_b32_e32 v106, v0
	v_mov_b32_e32 v107, v0
	v_mov_b32_e32 v108, v0
	v_mov_b32_e32 v109, v0
	v_mov_b32_e32 v110, v0
	v_mov_b32_e32 v111, v0
	v_mov_b32_e32 v120, v0
	v_mov_b32_e32 v121, v0
	v_mov_b32_e32 v122, v0
	v_mov_b32_e32 v123, v0
	v_mov_b32_e32 v124, v0
	v_mov_b32_e32 v125, v0
	v_mov_b32_e32 v126, v0
	v_mov_b32_e32 v127, v0
	v_lshrrev_b32_e32 v226, 8, v238
	v_cmp_ne_u32_e64 s[98:99], 0, v226
	s_nop 3
	s_and_b64 s[98:99], s[98:99], exec
	s_cbranch_scc0 .Lprio_skip_145
	s_setprio 1
.Lprio_skip_145:
.LBB0_145:
	s_add_u32 s24, s72, 0xfff80080
	s_addc_u32 s25, s73, -1
	s_add_i32 s46, 0, 0x10000
	s_cmp_eq_u32 s95, 28
	s_cselect_b32 s83, s2, s25
	s_cselect_b32 s82, s3, s24
	v_add_u32_e32 v142, s46, v145
	s_cselect_b32 s25, s31, s53
	s_cselect_b32 s24, s44, s45
	s_add_i32 s47, 0, 0x14000
	ds_read_b128 v[138:141], v142
	ds_read_b128 v[148:151], v142 offset:1024
	ds_read_b128 v[152:155], v142 offset:2048
	ds_read_b128 v[156:159], v142 offset:3072
	v_add_u32_e32 v142, s47, v145
	ds_read_b128 v[170:173], v142
	ds_read_b128 v[174:177], v142 offset:1024
	ds_read_b128 v[178:181], v142 offset:2048
	ds_read_b128 v[182:185], v142 offset:3072
	s_add_i32 m0, s63, 0xc000
	ds_read_b128 v[186:189], v147
	ds_read_b128 v[190:193], v147 offset:1024
	ds_read_b128 v[194:197], v147 offset:2048
	ds_read_b128 v[198:201], v147 offset:3072
	ds_read_b128 v[202:205], v147 offset:4096
	ds_read_b128 v[206:209], v147 offset:5120
	ds_read_b128 v[210:213], v147 offset:6144
	ds_read_b128 v[214:217], v147 offset:7168
	global_load_lds_dwordx4 v134, s[72:73]
	s_add_i32 m0, s63, 0xe000
	s_nop 0
	global_load_lds_dwordx4 v136, s[72:73]
	s_waitcnt vmcnt(8)
	s_waitcnt lgkmcnt(0)
	s_barrier
; #define PG8_STAGE(bufoff, gbase, voff) do { _Pragma("unroll") for (int _i = 0; _i < 2; ++_i) \
;         __builtin_amdgcn_global_load_lds((const unsigned*)((const char*)(gbase) + (voff)[_i]), (LAS unsigned*)(lds + (bufoff) + ldsw + _i * 8192), 16, 0, 0); } while (0)
; #define PG8_LDA(dst, b, h) do { _Pragma("unroll") for (int m = 0; m < 4; ++m) _Pragma("unroll") for (int k = 0; k < 2; ++k) dst[m][k] = *(const LAS bf16x8*)(lds + PG8_SA(b, h) + aoff + m * 2048 + k * 1024); } while (0)
; #define PG8_MMA(ai, bj, At, Bt) do { __builtin_amdgcn_s_setprio(1); _Pragma("unroll") for (int m = 0; m < 4; ++m) _Pragma("unroll") for (int n = 0; n < 2; ++n) _Pragma("unroll") for (int k = 0; k < 2; ++k) \
;         acc[ai][bj][m][n] = __builtin_amdgcn_mfma_f32_16x16x32_bf16(Bt[n][k], At[m][k], acc[ai][bj][m][n], 0, 0, 0); __builtin_amdgcn_s_setprio(0); } while (0)
; #define PG8_WAIT_V(n) asm volatile("s_waitcnt vmcnt(" #n ")" ::: "memory")
; #define PG8_WAIT_L(n) asm volatile("s_waitcnt lgkmcnt(" #n ")" ::: "memory")
; #define PG8_BAR __builtin_amdgcn_s_barrier()
; #define PG8_SCHED __builtin_amdgcn_sched_barrier(0)
; template <class Epi, class Sched, bool ALIGN_EPI = true, bool SP2 = true>
; __device__ __forceinline__ void gemm_phase(LAS unsigned char* lds, const Gemm g, const Sched& S, const Epi& E) {
;     ...
;             PG8_WAIT_V(8); PG8_WAIT_L(0); PG8_BAR; PG8_MMA(0, 0, At, B0); PG8_MMA(0, 1, At, B1); PG8_BAR; PG8_SCHED;
;             PG8_LDA(At, 0, 1); PG8_STAGE(PG8_SB(0, 0), b2, voffB); PG8_STAGE(PG8_SB(0, 1), b2 + hstep, voffB); PG8_STAGE(PG8_SA(0, 0), a2, voffA);
;             PG8_WAIT_V(8); PG8_WAIT_L(0); PG8_BAR; PG8_MMA(1, 0, At, B0); PG8_MMA(1, 1, At, B1); PG8_BAR; PG8_SCHED;
	s_waitcnt lgkmcnt(0)
	v_mfma_f32_16x16x32_bf16 v[124:127], v[138:141], v[186:189], v[124:127]
	v_mfma_f32_16x16x32_bf16 v[120:123], v[152:155], v[186:189], v[120:123]
	v_mfma_f32_16x16x32_bf16 v[108:111], v[138:141], v[194:197], v[108:111]
	v_mfma_f32_16x16x32_bf16 v[104:107], v[152:155], v[194:197], v[104:107]
	v_mfma_f32_16x16x32_bf16 v[92:95], v[138:141], v[202:205], v[92:95]
	v_mfma_f32_16x16x32_bf16 v[88:91], v[152:155], v[202:205], v[88:91]
	v_mfma_f32_16x16x32_bf16 v[76:79], v[138:141], v[210:213], v[76:79]
	v_mfma_f32_16x16x32_bf16 v[72:75], v[152:155], v[210:213], v[72:75]
	v_mfma_f32_16x16x32_bf16 v[124:127], v[148:151], v[190:193], v[124:127]
	v_mfma_f32_16x16x32_bf16 v[120:123], v[156:159], v[190:193], v[120:123]
	v_mfma_f32_16x16x32_bf16 v[108:111], v[148:151], v[198:201], v[108:111]
	v_mfma_f32_16x16x32_bf16 v[104:107], v[156:159], v[198:201], v[104:107]
	v_mfma_f32_16x16x32_bf16 v[92:95], v[148:151], v[206:209], v[92:95]
	v_mfma_f32_16x16x32_bf16 v[88:91], v[156:159], v[206:209], v[88:91]
	v_mfma_f32_16x16x32_bf16 v[76:79], v[148:151], v[214:217], v[76:79]
	v_mfma_f32_16x16x32_bf16 v[72:75], v[156:159], v[214:217], v[72:75]
	v_mfma_f32_16x16x32_bf16 v[116:119], v[170:173], v[186:189], v[116:119]
	v_mfma_f32_16x16x32_bf16 v[112:115], v[178:181], v[186:189], v[112:115]
	v_mfma_f32_16x16x32_bf16 v[100:103], v[170:173], v[194:197], v[100:103]
	v_mfma_f32_16x16x32_bf16 v[96:99], v[178:181], v[194:197], v[96:99]
	v_mfma_f32_16x16x32_bf16 v[84:87], v[170:173], v[202:205], v[84:87]
	v_mfma_f32_16x16x32_bf16 v[80:83], v[178:181], v[202:205], v[80:83]
	v_mfma_f32_16x16x32_bf16 v[68:71], v[170:173], v[210:213], v[68:71]
	v_mfma_f32_16x16x32_bf16 v[64:67], v[178:181], v[210:213], v[64:67]
	v_mfma_f32_16x16x32_bf16 v[116:119], v[174:177], v[190:193], v[116:119]
	v_mfma_f32_16x16x32_bf16 v[112:115], v[182:185], v[190:193], v[112:115]
	v_mfma_f32_16x16x32_bf16 v[100:103], v[174:177], v[198:201], v[100:103]
	v_mfma_f32_16x16x32_bf16 v[96:99], v[182:185], v[198:201], v[96:99]
	v_mfma_f32_16x16x32_bf16 v[84:87], v[174:177], v[206:209], v[84:87]
	v_mfma_f32_16x16x32_bf16 v[80:83], v[182:185], v[206:209], v[80:83]
	v_mfma_f32_16x16x32_bf16 v[68:71], v[174:177], v[214:217], v[68:71]
	v_mfma_f32_16x16x32_bf16 v[64:67], v[182:185], v[214:217], v[64:67]
	s_barrier
	s_add_i32 s46, s46, s79
	s_mov_b32 m0, s46
	ds_read_b128 v[186:189], v147 offset:16384
	ds_read_b128 v[190:193], v147 offset:17408
	ds_read_b128 v[194:197], v147 offset:18432
	ds_read_b128 v[198:201], v147 offset:19456
	ds_read_b128 v[202:205], v147 offset:20480
	ds_read_b128 v[206:209], v147 offset:21504
	ds_read_b128 v[210:213], v147 offset:22528
	ds_read_b128 v[214:217], v147 offset:23552
	global_load_lds_dwordx4 v160, s[24:25]
	s_add_i32 m0, s46, 0x2000
	s_add_u32 s96, s24, 0x80000
	s_addc_u32 s97, s25, 0
	s_add_i32 s46, s47, s79
	global_load_lds_dwordx4 v132, s[24:25]
	s_mov_b32 m0, s46
	s_nop 0
	global_load_lds_dwordx4 v160, s[96:97]
	s_add_i32 m0, s46, 0x2000
	s_nop 0
	global_load_lds_dwordx4 v132, s[96:97]
	s_mov_b32 m0, s63
	s_nop 0
	global_load_lds_dwordx4 v128, s[82:83]
	s_mov_b32 m0, s67
	s_nop 0
	global_load_lds_dwordx4 v130, s[82:83]
	s_waitcnt vmcnt(8)
	s_waitcnt lgkmcnt(0)
	s_barrier
	s_waitcnt lgkmcnt(0)
	v_mfma_f32_16x16x32_bf16 v[60:63], v[138:141], v[186:189], v[60:63]
	v_mfma_f32_16x16x32_bf16 v[56:59], v[152:155], v[186:189], v[56:59]
	v_mfma_f32_16x16x32_bf16 v[44:47], v[138:141], v[194:197], v[44:47]
	v_mfma_f32_16x16x32_bf16 v[40:43], v[152:155], v[194:197], v[40:43]
	v_mfma_f32_16x16x32_bf16 v[28:31], v[138:141], v[202:205], v[28:31]
	v_mfma_f32_16x16x32_bf16 v[24:27], v[152:155], v[202:205], v[24:27]
	v_mfma_f32_16x16x32_bf16 v[12:15], v[138:141], v[210:213], v[12:15]
	v_mfma_f32_16x16x32_bf16 v[8:11], v[152:155], v[210:213], v[8:11]
	v_mfma_f32_16x16x32_bf16 v[60:63], v[148:151], v[190:193], v[60:63]
	v_mfma_f32_16x16x32_bf16 v[56:59], v[156:159], v[190:193], v[56:59]
	v_mfma_f32_16x16x32_bf16 v[44:47], v[148:151], v[198:201], v[44:47]
	v_mfma_f32_16x16x32_bf16 v[40:43], v[156:159], v[198:201], v[40:43]
	v_mfma_f32_16x16x32_bf16 v[28:31], v[148:151], v[206:209], v[28:31]
	v_mfma_f32_16x16x32_bf16 v[24:27], v[156:159], v[206:209], v[24:27]
	v_mfma_f32_16x16x32_bf16 v[12:15], v[148:151], v[214:217], v[12:15]
	v_mfma_f32_16x16x32_bf16 v[8:11], v[156:159], v[214:217], v[8:11]
	v_mfma_f32_16x16x32_bf16 v[52:55], v[170:173], v[186:189], v[52:55]
	v_mfma_f32_16x16x32_bf16 v[48:51], v[178:181], v[186:189], v[48:51]
	v_mfma_f32_16x16x32_bf16 v[36:39], v[170:173], v[194:197], v[36:39]
	v_mfma_f32_16x16x32_bf16 v[32:35], v[178:181], v[194:197], v[32:35]
	v_mfma_f32_16x16x32_bf16 v[20:23], v[170:173], v[202:205], v[20:23]
	v_mfma_f32_16x16x32_bf16 v[16:19], v[178:181], v[202:205], v[16:19]
	v_mfma_f32_16x16x32_bf16 v[4:7], v[170:173], v[210:213], v[4:7]
	v_mfma_f32_16x16x32_bf16 v[0:3], v[178:181], v[210:213], v[0:3]
	v_mfma_f32_16x16x32_bf16 v[52:55], v[174:177], v[190:193], v[52:55]
	v_mfma_f32_16x16x32_bf16 v[48:51], v[182:185], v[190:193], v[48:51]
	v_mfma_f32_16x16x32_bf16 v[36:39], v[174:177], v[198:201], v[36:39]
	v_mfma_f32_16x16x32_bf16 v[32:35], v[182:185], v[198:201], v[32:35]
	v_mfma_f32_16x16x32_bf16 v[20:23], v[174:177], v[206:209], v[20:23]
	v_mfma_f32_16x16x32_bf16 v[16:19], v[182:185], v[206:209], v[16:19]
	v_mfma_f32_16x16x32_bf16 v[4:7], v[174:177], v[214:217], v[4:7]
	v_mfma_f32_16x16x32_bf16 v[0:3], v[182:185], v[214:217], v[0:3]
	s_barrier
; #define PG8_STAGE(bufoff, gbase, voff) do { _Pragma("unroll") for (int _i = 0; _i < 2; ++_i) \
;         __builtin_amdgcn_global_load_lds((const unsigned*)((const char*)(gbase) + (voff)[_i]), (LAS unsigned*)(lds + (bufoff) + ldsw + _i * 8192), 16, 0, 0); } while (0)
; #define PG8_LDA(dst, b, h) do { _Pragma("unroll") for (int m = 0; m < 4; ++m) _Pragma("unroll") for (int k = 0; k < 2; ++k) dst[m][k] = *(const LAS bf16x8*)(lds + PG8_SA(b, h) + aoff + m * 2048 + k * 1024); } while (0)
; #define PG8_LDB(dst, b, h) do { _Pragma("unroll") for (int n = 0; n < 2; ++n) _Pragma("unroll") for (int k = 0; k < 2; ++k) dst[n][k] = *(const LAS bf16x8*)(lds + PG8_SB(b, h) + boff + n * 2048 + k * 1024); } while (0)
; #define PG8_MMA(ai, bj, At, Bt) do { __builtin_amdgcn_s_setprio(1); _Pragma("unroll") for (int m = 0; m < 4; ++m) _Pragma("unroll") for (int n = 0; n < 2; ++n) _Pragma("unroll") for (int k = 0; k < 2; ++k) \
;         acc[ai][bj][m][n] = __builtin_amdgcn_mfma_f32_16x16x32_bf16(Bt[n][k], At[m][k], acc[ai][bj][m][n], 0, 0, 0); __builtin_amdgcn_s_setprio(0); } while (0)
; #define PG8_WAIT_V(n) asm volatile("s_waitcnt vmcnt(" #n ")" ::: "memory")
; #define PG8_WAIT_L(n) asm volatile("s_waitcnt lgkmcnt(" #n ")" ::: "memory")
; #define PG8_BAR __builtin_amdgcn_s_barrier()
; #define PG8_SCHED __builtin_amdgcn_sched_barrier(0)
; template <class Epi, class Sched, bool ALIGN_EPI = true, bool SP2 = true>
; __device__ __forceinline__ void gemm_phase(LAS unsigned char* lds, const Gemm g, const Sched& S, const Epi& E) {
;     ...
;             PG8_LDB(B0, 1, 0); PG8_LDB(B1, 1, 1); PG8_SCHED; PG8_LDA(At, 1, 0); PG8_STAGE(PG8_SA(0, 1), a2 + hstep, voffA);
;             PG8_WAIT_V(8); PG8_WAIT_L(0); PG8_BAR; PG8_MMA(0, 0, At, B0); PG8_MMA(0, 1, At, B1); PG8_BAR; PG8_SCHED;
;             PG8_LDA(At, 1, 1); PG8_STAGE(PG8_SB(1, 0), b3, voffB); PG8_STAGE(PG8_SB(1, 1), b3 + hstep, voffB); PG8_STAGE(PG8_SA(1, 0), a3, voffA);
;             PG8_WAIT_V(8); PG8_WAIT_L(0); PG8_BAR; PG8_MMA(1, 0, At, B0); PG8_MMA(1, 1, At, B1); PG8_BAR; PG8_SCHED;
	s_add_i32 s46, 0, 0x18000
	s_add_i32 s47, 0, 0x1c000
	v_add_u32_e32 v156, s46, v145
	v_add_u32_e32 v182, s47, v145
	ds_read_b128 v[138:141], v156
	ds_read_b128 v[148:151], v156 offset:1024
	ds_read_b128 v[152:155], v156 offset:2048
	ds_read_b128 v[156:159], v156 offset:3072
	ds_read_b128 v[170:173], v182
	ds_read_b128 v[174:177], v182 offset:1024
	ds_read_b128 v[178:181], v182 offset:2048
	ds_read_b128 v[182:185], v182 offset:3072
	s_add_u32 s82, s82, 0x80000
	s_addc_u32 s83, s83, 0
	s_mov_b32 m0, s90
	ds_read_b128 v[186:189], v147 offset:32768
	ds_read_b128 v[190:193], v147 offset:33792
	ds_read_b128 v[194:197], v147 offset:34816
	ds_read_b128 v[198:201], v147 offset:35840
	ds_read_b128 v[202:205], v147 offset:36864
	ds_read_b128 v[206:209], v147 offset:37888
	ds_read_b128 v[210:213], v147 offset:38912
	ds_read_b128 v[214:217], v147 offset:39936
	global_load_lds_dwordx4 v128, s[82:83]
	s_mov_b32 m0, s91
	s_nop 0
	global_load_lds_dwordx4 v130, s[82:83]
	s_waitcnt vmcnt(8)
	s_waitcnt lgkmcnt(0)
	s_barrier
	s_waitcnt lgkmcnt(0)
	v_mfma_f32_16x16x32_bf16 v[124:127], v[138:141], v[186:189], v[124:127]
	v_mfma_f32_16x16x32_bf16 v[120:123], v[152:155], v[186:189], v[120:123]
	v_mfma_f32_16x16x32_bf16 v[108:111], v[138:141], v[194:197], v[108:111]
	v_mfma_f32_16x16x32_bf16 v[104:107], v[152:155], v[194:197], v[104:107]
	v_mfma_f32_16x16x32_bf16 v[92:95], v[138:141], v[202:205], v[92:95]
	v_mfma_f32_16x16x32_bf16 v[88:91], v[152:155], v[202:205], v[88:91]
	v_mfma_f32_16x16x32_bf16 v[76:79], v[138:141], v[210:213], v[76:79]
	v_mfma_f32_16x16x32_bf16 v[72:75], v[152:155], v[210:213], v[72:75]
	v_mfma_f32_16x16x32_bf16 v[124:127], v[148:151], v[190:193], v[124:127]
	v_mfma_f32_16x16x32_bf16 v[120:123], v[156:159], v[190:193], v[120:123]
	v_mfma_f32_16x16x32_bf16 v[108:111], v[148:151], v[198:201], v[108:111]
	v_mfma_f32_16x16x32_bf16 v[104:107], v[156:159], v[198:201], v[104:107]
	v_mfma_f32_16x16x32_bf16 v[92:95], v[148:151], v[206:209], v[92:95]
	v_mfma_f32_16x16x32_bf16 v[88:91], v[156:159], v[206:209], v[88:91]
	v_mfma_f32_16x16x32_bf16 v[76:79], v[148:151], v[214:217], v[76:79]
	v_mfma_f32_16x16x32_bf16 v[72:75], v[156:159], v[214:217], v[72:75]
	v_mfma_f32_16x16x32_bf16 v[116:119], v[170:173], v[186:189], v[116:119]
	v_mfma_f32_16x16x32_bf16 v[112:115], v[178:181], v[186:189], v[112:115]
	v_mfma_f32_16x16x32_bf16 v[100:103], v[170:173], v[194:197], v[100:103]
	v_mfma_f32_16x16x32_bf16 v[96:99], v[178:181], v[194:197], v[96:99]
	v_mfma_f32_16x16x32_bf16 v[84:87], v[170:173], v[202:205], v[84:87]
	v_mfma_f32_16x16x32_bf16 v[80:83], v[178:181], v[202:205], v[80:83]
	v_mfma_f32_16x16x32_bf16 v[68:71], v[170:173], v[210:213], v[68:71]
	v_mfma_f32_16x16x32_bf16 v[64:67], v[178:181], v[210:213], v[64:67]
	v_mfma_f32_16x16x32_bf16 v[116:119], v[174:177], v[190:193], v[116:119]
	v_mfma_f32_16x16x32_bf16 v[112:115], v[182:185], v[190:193], v[112:115]
	v_mfma_f32_16x16x32_bf16 v[100:103], v[174:177], v[198:201], v[100:103]
	v_mfma_f32_16x16x32_bf16 v[96:99], v[182:185], v[198:201], v[96:99]
	v_mfma_f32_16x16x32_bf16 v[84:87], v[174:177], v[206:209], v[84:87]
	v_mfma_f32_16x16x32_bf16 v[80:83], v[182:185], v[206:209], v[80:83]
	v_mfma_f32_16x16x32_bf16 v[68:71], v[174:177], v[214:217], v[68:71]
	v_mfma_f32_16x16x32_bf16 v[64:67], v[182:185], v[214:217], v[64:67]
	s_barrier
	s_add_i32 s46, s46, s79
	s_mov_b32 m0, s46
	ds_read_b128 v[186:189], v147 offset:49152
	ds_read_b128 v[190:193], v147 offset:50176
	ds_read_b128 v[194:197], v147 offset:51200
	ds_read_b128 v[198:201], v147 offset:52224
	ds_read_b128 v[202:205], v147 offset:53248
	ds_read_b128 v[206:209], v147 offset:54272
	ds_read_b128 v[210:213], v147 offset:55296
	ds_read_b128 v[214:217], v147 offset:56320
	s_add_u32 s98, s24, 0x80
	s_addc_u32 s99, s25, 0
	global_load_lds_dwordx4 v160, s[98:99]
	s_add_i32 m0, s46, 0x2000
	s_add_u32 s24, s24, 0x80080
	s_addc_u32 s25, s25, 0
	s_add_i32 s46, s47, s79
	global_load_lds_dwordx4 v132, s[98:99]
	s_mov_b32 m0, s46
	s_nop 0
	global_load_lds_dwordx4 v160, s[24:25]
	s_add_i32 m0, s46, 0x2000
	s_nop 0
	global_load_lds_dwordx4 v132, s[24:25]
	s_mov_b32 m0, s92
	s_nop 0
	s_add_u32 s98, s82, 0xfff80080
	s_addc_u32 s99, s83, -1
	global_load_lds_dwordx4 v128, s[98:99]
	s_mov_b32 m0, s93
	s_nop 0
	global_load_lds_dwordx4 v130, s[98:99]
	s_waitcnt vmcnt(8)
	s_waitcnt lgkmcnt(0)
	s_barrier
	s_waitcnt lgkmcnt(0)
	v_mfma_f32_16x16x32_bf16 v[60:63], v[138:141], v[186:189], v[60:63]
	v_mfma_f32_16x16x32_bf16 v[56:59], v[152:155], v[186:189], v[56:59]
	v_mfma_f32_16x16x32_bf16 v[44:47], v[138:141], v[194:197], v[44:47]
	v_mfma_f32_16x16x32_bf16 v[40:43], v[152:155], v[194:197], v[40:43]
	v_mfma_f32_16x16x32_bf16 v[28:31], v[138:141], v[202:205], v[28:31]
	v_mfma_f32_16x16x32_bf16 v[24:27], v[152:155], v[202:205], v[24:27]
	v_mfma_f32_16x16x32_bf16 v[12:15], v[138:141], v[210:213], v[12:15]
	v_mfma_f32_16x16x32_bf16 v[8:11], v[152:155], v[210:213], v[8:11]
	v_mfma_f32_16x16x32_bf16 v[60:63], v[148:151], v[190:193], v[60:63]
	v_mfma_f32_16x16x32_bf16 v[56:59], v[156:159], v[190:193], v[56:59]
	v_mfma_f32_16x16x32_bf16 v[44:47], v[148:151], v[198:201], v[44:47]
	v_mfma_f32_16x16x32_bf16 v[40:43], v[156:159], v[198:201], v[40:43]
	v_mfma_f32_16x16x32_bf16 v[28:31], v[148:151], v[206:209], v[28:31]
	v_mfma_f32_16x16x32_bf16 v[24:27], v[156:159], v[206:209], v[24:27]
	v_mfma_f32_16x16x32_bf16 v[12:15], v[148:151], v[214:217], v[12:15]
	v_mfma_f32_16x16x32_bf16 v[8:11], v[156:159], v[214:217], v[8:11]
	v_mfma_f32_16x16x32_bf16 v[52:55], v[170:173], v[186:189], v[52:55]
	v_mfma_f32_16x16x32_bf16 v[48:51], v[178:181], v[186:189], v[48:51]
	v_mfma_f32_16x16x32_bf16 v[36:39], v[170:173], v[194:197], v[36:39]
	v_mfma_f32_16x16x32_bf16 v[32:35], v[178:181], v[194:197], v[32:35]
	v_mfma_f32_16x16x32_bf16 v[20:23], v[170:173], v[202:205], v[20:23]
	v_mfma_f32_16x16x32_bf16 v[16:19], v[178:181], v[202:205], v[16:19]
	v_mfma_f32_16x16x32_bf16 v[4:7], v[170:173], v[210:213], v[4:7]
	v_mfma_f32_16x16x32_bf16 v[0:3], v[178:181], v[210:213], v[0:3]
	v_mfma_f32_16x16x32_bf16 v[52:55], v[174:177], v[190:193], v[52:55]
	v_mfma_f32_16x16x32_bf16 v[48:51], v[182:185], v[190:193], v[48:51]
	v_mfma_f32_16x16x32_bf16 v[36:39], v[174:177], v[198:201], v[36:39]
	v_mfma_f32_16x16x32_bf16 v[32:35], v[182:185], v[198:201], v[32:35]
	v_mfma_f32_16x16x32_bf16 v[20:23], v[174:177], v[206:209], v[20:23]
	v_mfma_f32_16x16x32_bf16 v[16:19], v[182:185], v[206:209], v[16:19]
	v_mfma_f32_16x16x32_bf16 v[4:7], v[174:177], v[214:217], v[4:7]
	v_mfma_f32_16x16x32_bf16 v[0:3], v[182:185], v[214:217], v[0:3]
	s_barrier
	s_add_i32 s95, s95, 2
	s_add_u32 s72, s72, 0x100
	s_addc_u32 s73, s73, 0
	s_add_u32 s45, s45, 0x100
	s_addc_u32 s53, s53, 0
	s_cmp_gt_u32 s95, 29
	s_cbranch_scc0 .LBB0_145
	s_setprio 0
	s_and_b64 vcc, exec, s[18:19]
	s_cbranch_vccz .LBB0_148
	s_barrier

; #define PG8_STAGE(bufoff, gbase, voff) do { _Pragma("unroll") for (int _i = 0; _i < 2; ++_i) \
;         __builtin_amdgcn_global_load_lds((const unsigned*)((const char*)(gbase) + (voff)[_i]), (LAS unsigned*)(lds + (bufoff) + ldsw + _i * 8192), 16, 0, 0); } while (0)
; #define PG8_LDA(dst, b, h) do { _Pragma("unroll") for (int m = 0; m < 4; ++m) _Pragma("unroll") for (int k = 0; k < 2; ++k) dst[m][k] = *(const LAS bf16x8*)(lds + PG8_SA(b, h) + aoff + m * 2048 + k * 1024); } while (0)
; #define PG8_LDB(dst, b, h) do { _Pragma("unroll") for (int n = 0; n < 2; ++n) _Pragma("unroll") for (int k = 0; k < 2; ++k) dst[n][k] = *(const LAS bf16x8*)(lds + PG8_SB(b, h) + boff + n * 2048 + k * 1024); } while (0)
; #define PG8_WAIT_V(n) asm volatile("s_waitcnt vmcnt(" #n ")" ::: "memory")
; #define PG8_WAIT_L(n) asm volatile("s_waitcnt lgkmcnt(" #n ")" ::: "memory")
; #define PG8_BAR __builtin_amdgcn_s_barrier()
; #define PG8_SCHED __builtin_amdgcn_sched_barrier(0)
; template <class Epi, class Sched, bool ALIGN_EPI = true, bool SP2 = true>
; __device__ __forceinline__ void gemm_phase(LAS unsigned char* lds, const Gemm g, const Sched& S, const Epi& E) {
;     ...
;     for (;;) {
;         const bool has_next = S.next(ui + 1, nxt);
;         const char* nA = has_next ? (const char*)g.A + (size_t)nxt.pm * tstep : cA; const char* nB = has_next ? (const char*)g.Bt + (size_t)nxt.pn * tstep : cB;
;         for (int t = 0; t < nt; t += 2) {
;             const bool last = (t == nt - 2);
;             const char* a1 = cA + (size_t)(t + 1) * kstep;
;             const char* a2 = last ? nA : cA + (size_t)(t + 2) * kstep; const char* b2 = last ? nB : cB + (size_t)(t + 2) * kstep;
;             const char* a3 = a2 + kstep; const char* b3 = b2 + kstep;
;             if constexpr (SP2) {
;             PG8_LDB(B0, 0, 0); PG8_LDB(B1, 0, 1); PG8_SCHED; PG8_LDA(At, 0, 0); PG8_STAGE(PG8_SA(1, 1), a1 + hstep, voffA);
;             PG8_WAIT_V(8); PG8_WAIT_L(0); PG8_BAR; PG8_MMA(0, 0, At, B0); PG8_MMA(0, 1, At, B1); PG8_BAR; PG8_SCHED;
;     ...
; #pragma unroll
;         for (int a = 0; a < 2; ++a)
; #pragma unroll
;             for (int b = 0; b < 2; ++b)
; #pragma unroll
;                 for (int m = 0; m < 4; ++m)
; #pragma unroll
;                     for (int n = 0; n < 2; ++n) acc[a][b][m][n] = (f32x4){0.f, 0.f, 0.f, 0.f};
.LBB0_186:
	s_ashr_i32 s53, s52, 31
	s_lshl_b64 s[2:3], s[52:53], 19
	s_add_u32 s54, s41, s2
	s_addc_u32 s55, s79, s3
	s_and_b64 s[2:3], s[4:5], exec
	s_cselect_b32 s2, s55, s25
	s_cselect_b32 s3, s54, s24
	s_ashr_i32 s31, s30, 31
	s_lshl_b64 s[44:45], s[30:31], 19
	s_add_u32 s60, s82, s44
	s_addc_u32 s61, s83, s45
	s_and_b64 s[44:45], s[4:5], exec
	s_cselect_b32 s31, s61, s73
	s_cselect_b32 s43, s60, s72
	s_add_u32 s66, s24, 0x40080
	s_addc_u32 s67, s25, 0
	s_add_u32 s44, s72, 0x100
	v_mov_b32_e32 v0, 0
	s_addc_u32 s45, s73, 0
	s_mov_b32 s53, -2
	v_mov_b32_e32 v1, v0
	v_mov_b32_e32 v2, v0
	v_mov_b32_e32 v3, v0
	v_mov_b32_e32 v4, v0
	v_mov_b32_e32 v5, v0
	v_mov_b32_e32 v6, v0
	v_mov_b32_e32 v7, v0
	v_mov_b32_e32 v16, v0
	v_mov_b32_e32 v17, v0
	v_mov_b32_e32 v18, v0
	v_mov_b32_e32 v19, v0
	v_mov_b32_e32 v20, v0
	v_mov_b32_e32 v21, v0
	v_mov_b32_e32 v22, v0
	v_mov_b32_e32 v23, v0
	v_mov_b32_e32 v32, v0
	v_mov_b32_e32 v33, v0
	v_mov_b32_e32 v34, v0
	v_mov_b32_e32 v35, v0
	s_waitcnt vmcnt(0)
	v_mov_b32_e32 v36, v0
	v_mov_b32_e32 v37, v0
	v_mov_b32_e32 v38, v0
	v_mov_b32_e32 v39, v0
	s_waitcnt vmcnt(0)
	v_mov_b32_e32 v48, v0
	v_mov_b32_e32 v49, v0
	v_mov_b32_e32 v50, v0
	v_mov_b32_e32 v51, v0
	v_mov_b32_e32 v52, v0
	v_mov_b32_e32 v53, v0
	v_mov_b32_e32 v54, v0
	v_mov_b32_e32 v55, v0
	v_mov_b32_e32 v8, v0
	v_mov_b32_e32 v9, v0
	v_mov_b32_e32 v10, v0
	v_mov_b32_e32 v11, v0
	v_mov_b32_e32 v12, v0
	v_mov_b32_e32 v13, v0
	v_mov_b32_e32 v14, v0
	v_mov_b32_e32 v15, v0
	v_mov_b32_e32 v24, v0
	v_mov_b32_e32 v25, v0
	v_mov_b32_e32 v26, v0
	v_mov_b32_e32 v27, v0
	v_mov_b32_e32 v28, v0
	v_mov_b32_e32 v29, v0
	v_mov_b32_e32 v30, v0
	v_mov_b32_e32 v31, v0
	v_mov_b32_e32 v40, v0
	v_mov_b32_e32 v41, v0
	v_mov_b32_e32 v42, v0
	v_mov_b32_e32 v43, v0
	v_mov_b32_e32 v44, v0
	v_mov_b32_e32 v45, v0
	v_mov_b32_e32 v46, v0
	v_mov_b32_e32 v47, v0
	v_mov_b32_e32 v56, v0
	v_mov_b32_e32 v57, v0
	v_mov_b32_e32 v58, v0
	v_mov_b32_e32 v59, v0
	v_mov_b32_e32 v60, v0
	v_mov_b32_e32 v61, v0
	v_mov_b32_e32 v62, v0
	v_mov_b32_e32 v63, v0
	v_mov_b32_e32 v64, v0
	v_mov_b32_e32 v65, v0
	v_mov_b32_e32 v66, v0
	v_mov_b32_e32 v67, v0
	v_mov_b32_e32 v68, v0
	v_mov_b32_e32 v69, v0
	v_mov_b32_e32 v70, v0
	v_mov_b32_e32 v71, v0
	v_mov_b32_e32 v80, v0
	v_mov_b32_e32 v81, v0
	v_mov_b32_e32 v82, v0
	v_mov_b32_e32 v83, v0
	v_mov_b32_e32 v84, v0
	v_mov_b32_e32 v85, v0
	v_mov_b32_e32 v86, v0
	v_mov_b32_e32 v87, v0
	v_mov_b32_e32 v96, v0
	v_mov_b32_e32 v97, v0
	v_mov_b32_e32 v98, v0
	v_mov_b32_e32 v99, v0
	v_mov_b32_e32 v100, v0
	v_mov_b32_e32 v101, v0
	v_mov_b32_e32 v102, v0
	v_mov_b32_e32 v103, v0
	v_mov_b32_e32 v112, v0
	v_mov_b32_e32 v113, v0
	v_mov_b32_e32 v114, v0
	v_mov_b32_e32 v115, v0
	v_mov_b32_e32 v116, v0
	v_mov_b32_e32 v117, v0
	v_mov_b32_e32 v118, v0
	v_mov_b32_e32 v119, v0
	v_mov_b32_e32 v72, v0
	v_mov_b32_e32 v73, v0
	v_mov_b32_e32 v74, v0
	v_mov_b32_e32 v75, v0
	v_mov_b32_e32 v76, v0
	v_mov_b32_e32 v77, v0
	v_mov_b32_e32 v78, v0
	v_mov_b32_e32 v79, v0
	v_mov_b32_e32 v88, v0
	v_mov_b32_e32 v89, v0
	v_mov_b32_e32 v90, v0
	v_mov_b32_e32 v91, v0
	v_mov_b32_e32 v92, v0
	v_mov_b32_e32 v93, v0
	v_mov_b32_e32 v94, v0
	v_mov_b32_e32 v95, v0
	v_mov_b32_e32 v104, v0
	v_mov_b32_e32 v105, v0
	v_mov_b32_e32 v106, v0
	v_mov_b32_e32 v107, v0
	v_mov_b32_e32 v108, v0
	v_mov_b32_e32 v109, v0
	v_mov_b32_e32 v110, v0
	v_mov_b32_e32 v111, v0
	v_mov_b32_e32 v120, v0
	v_mov_b32_e32 v121, v0
	v_mov_b32_e32 v122, v0
	v_mov_b32_e32 v123, v0
	v_mov_b32_e32 v124, v0
	v_mov_b32_e32 v125, v0
	v_mov_b32_e32 v126, v0
	v_mov_b32_e32 v127, v0
	v_lshrrev_b32_e32 v226, 8, v238
	v_cmp_ne_u32_e64 s[98:99], 0, v226
	s_nop 3
	s_and_b64 s[98:99], s[98:99], exec
	s_cbranch_scc0 .Lprio_skip_187
	s_setprio 1
.Lprio_skip_187:
.LBB0_187:
	s_add_u32 s24, s66, 0xfffc0080
	s_addc_u32 s25, s67, -1
	s_add_i32 s46, 0, 0x10000
	s_cmp_eq_u32 s53, 12
	s_cselect_b32 s73, s2, s25
	s_cselect_b32 s72, s3, s24
	s_cselect_b32 s25, s31, s45
	s_cselect_b32 s24, s43, s44
	s_add_i32 s47, 0, 0x14000
	v_add_u32_e32 v154, s46, v147
	v_add_u32_e32 v158, s47, v147
	ds_read_b128 v[138:141], v154
	ds_read_b128 v[142:145], v154 offset:1024
	ds_read_b128 v[150:153], v154 offset:2048
	ds_read_b128 v[154:157], v154 offset:3072
	ds_read_b128 v[170:173], v158
	ds_read_b128 v[174:177], v158 offset:1024
	ds_read_b128 v[178:181], v158 offset:2048
	ds_read_b128 v[182:185], v158 offset:3072
	s_add_i32 m0, s63, 0xc000
	ds_read_b128 v[186:189], v149
	ds_read_b128 v[190:193], v149 offset:1024
	ds_read_b128 v[194:197], v149 offset:2048
	ds_read_b128 v[198:201], v149 offset:3072
	ds_read_b128 v[202:205], v149 offset:4096
	ds_read_b128 v[206:209], v149 offset:5120
	ds_read_b128 v[210:213], v149 offset:6144
	ds_read_b128 v[214:217], v149 offset:7168
	global_load_lds_dwordx4 v134, s[66:67]
	s_add_i32 m0, s63, 0xe000
	s_nop 0
	global_load_lds_dwordx4 v136, s[66:67]
	s_waitcnt vmcnt(8)
	s_waitcnt lgkmcnt(0)
	s_barrier
; #define PG8_STAGE(bufoff, gbase, voff) do { _Pragma("unroll") for (int _i = 0; _i < 2; ++_i) \
;         __builtin_amdgcn_global_load_lds((const unsigned*)((const char*)(gbase) + (voff)[_i]), (LAS unsigned*)(lds + (bufoff) + ldsw + _i * 8192), 16, 0, 0); } while (0)
; #define PG8_LDA(dst, b, h) do { _Pragma("unroll") for (int m = 0; m < 4; ++m) _Pragma("unroll") for (int k = 0; k < 2; ++k) dst[m][k] = *(const LAS bf16x8*)(lds + PG8_SA(b, h) + aoff + m * 2048 + k * 1024); } while (0)
; #define PG8_MMA(ai, bj, At, Bt) do { __builtin_amdgcn_s_setprio(1); _Pragma("unroll") for (int m = 0; m < 4; ++m) _Pragma("unroll") for (int n = 0; n < 2; ++n) _Pragma("unroll") for (int k = 0; k < 2; ++k) \
;         acc[ai][bj][m][n] = __builtin_amdgcn_mfma_f32_16x16x32_bf16(Bt[n][k], At[m][k], acc[ai][bj][m][n], 0, 0, 0); __builtin_amdgcn_s_setprio(0); } while (0)
; #define PG8_WAIT_V(n) asm volatile("s_waitcnt vmcnt(" #n ")" ::: "memory")
; #define PG8_WAIT_L(n) asm volatile("s_waitcnt lgkmcnt(" #n ")" ::: "memory")
; #define PG8_BAR __builtin_amdgcn_s_barrier()
; #define PG8_SCHED __builtin_amdgcn_sched_barrier(0)
; template <class Epi, class Sched, bool ALIGN_EPI = true, bool SP2 = true>
; __device__ __forceinline__ void gemm_phase(LAS unsigned char* lds, const Gemm g, const Sched& S, const Epi& E) {
;     ...
;             PG8_WAIT_V(8); PG8_WAIT_L(0); PG8_BAR; PG8_MMA(0, 0, At, B0); PG8_MMA(0, 1, At, B1); PG8_BAR; PG8_SCHED;
;             PG8_LDA(At, 0, 1); PG8_STAGE(PG8_SB(0, 0), b2, voffB); PG8_STAGE(PG8_SB(0, 1), b2 + hstep, voffB); PG8_STAGE(PG8_SA(0, 0), a2, voffA);
;             PG8_WAIT_V(8); PG8_WAIT_L(0); PG8_BAR; PG8_MMA(1, 0, At, B0); PG8_MMA(1, 1, At, B1); PG8_BAR; PG8_SCHED;
	s_waitcnt lgkmcnt(0)
	v_mfma_f32_16x16x32_bf16 v[124:127], v[138:141], v[186:189], v[124:127]
	v_mfma_f32_16x16x32_bf16 v[120:123], v[150:153], v[186:189], v[120:123]
	v_mfma_f32_16x16x32_bf16 v[108:111], v[138:141], v[194:197], v[108:111]
	v_mfma_f32_16x16x32_bf16 v[104:107], v[150:153], v[194:197], v[104:107]
	v_mfma_f32_16x16x32_bf16 v[92:95], v[138:141], v[202:205], v[92:95]
	v_mfma_f32_16x16x32_bf16 v[88:91], v[150:153], v[202:205], v[88:91]
	v_mfma_f32_16x16x32_bf16 v[76:79], v[138:141], v[210:213], v[76:79]
	v_mfma_f32_16x16x32_bf16 v[72:75], v[150:153], v[210:213], v[72:75]
	v_mfma_f32_16x16x32_bf16 v[124:127], v[142:145], v[190:193], v[124:127]
	v_mfma_f32_16x16x32_bf16 v[120:123], v[154:157], v[190:193], v[120:123]
	v_mfma_f32_16x16x32_bf16 v[108:111], v[142:145], v[198:201], v[108:111]
	v_mfma_f32_16x16x32_bf16 v[104:107], v[154:157], v[198:201], v[104:107]
	v_mfma_f32_16x16x32_bf16 v[92:95], v[142:145], v[206:209], v[92:95]
	v_mfma_f32_16x16x32_bf16 v[88:91], v[154:157], v[206:209], v[88:91]
	v_mfma_f32_16x16x32_bf16 v[76:79], v[142:145], v[214:217], v[76:79]
	v_mfma_f32_16x16x32_bf16 v[72:75], v[154:157], v[214:217], v[72:75]
	v_mfma_f32_16x16x32_bf16 v[116:119], v[170:173], v[186:189], v[116:119]
	v_mfma_f32_16x16x32_bf16 v[112:115], v[178:181], v[186:189], v[112:115]
	v_mfma_f32_16x16x32_bf16 v[100:103], v[170:173], v[194:197], v[100:103]
	v_mfma_f32_16x16x32_bf16 v[96:99], v[178:181], v[194:197], v[96:99]
	v_mfma_f32_16x16x32_bf16 v[84:87], v[170:173], v[202:205], v[84:87]
	v_mfma_f32_16x16x32_bf16 v[80:83], v[178:181], v[202:205], v[80:83]
	v_mfma_f32_16x16x32_bf16 v[68:71], v[170:173], v[210:213], v[68:71]
	v_mfma_f32_16x16x32_bf16 v[64:67], v[178:181], v[210:213], v[64:67]
	v_mfma_f32_16x16x32_bf16 v[116:119], v[174:177], v[190:193], v[116:119]
	v_mfma_f32_16x16x32_bf16 v[112:115], v[182:185], v[190:193], v[112:115]
	v_mfma_f32_16x16x32_bf16 v[100:103], v[174:177], v[198:201], v[100:103]
	v_mfma_f32_16x16x32_bf16 v[96:99], v[182:185], v[198:201], v[96:99]
	v_mfma_f32_16x16x32_bf16 v[84:87], v[174:177], v[206:209], v[84:87]
	v_mfma_f32_16x16x32_bf16 v[80:83], v[182:185], v[206:209], v[80:83]
	v_mfma_f32_16x16x32_bf16 v[68:71], v[174:177], v[214:217], v[68:71]
	v_mfma_f32_16x16x32_bf16 v[64:67], v[182:185], v[214:217], v[64:67]
	s_barrier
	s_add_i32 s46, s46, s90
	s_mov_b32 m0, s46
	ds_read_b128 v[186:189], v149 offset:16384
	ds_read_b128 v[190:193], v149 offset:17408
	ds_read_b128 v[194:197], v149 offset:18432
	ds_read_b128 v[198:201], v149 offset:19456
	ds_read_b128 v[202:205], v149 offset:20480
	ds_read_b128 v[206:209], v149 offset:21504
	ds_read_b128 v[210:213], v149 offset:22528
	ds_read_b128 v[214:217], v149 offset:23552
	global_load_lds_dwordx4 v160, s[24:25]
	s_add_i32 m0, s46, 0x2000
	s_add_u32 vcc_lo, s24, 0x40000
	s_addc_u32 vcc_hi, s25, 0
	s_add_i32 s46, s47, s90
	global_load_lds_dwordx4 v132, s[24:25]
	v_lshl_add_u64 v[218:219], vcc, 0, v[160:161]
	s_mov_b32 m0, s46
	s_nop 0
	global_load_lds_dwordx4 v[218:219], off
	v_lshl_add_u64 v[218:219], vcc, 0, v[132:133]
	s_add_i32 m0, s46, 0x2000
	s_nop 0
	global_load_lds_dwordx4 v[218:219], off
	s_mov_b32 m0, s63
	s_nop 0
	global_load_lds_dwordx4 v128, s[72:73]
	s_mov_b32 m0, s91
	s_nop 0
	global_load_lds_dwordx4 v130, s[72:73]
	s_waitcnt vmcnt(8)
	s_waitcnt lgkmcnt(0)
	s_barrier
	s_waitcnt lgkmcnt(0)
	v_mfma_f32_16x16x32_bf16 v[60:63], v[138:141], v[186:189], v[60:63]
	v_mfma_f32_16x16x32_bf16 v[56:59], v[150:153], v[186:189], v[56:59]
	v_mfma_f32_16x16x32_bf16 v[44:47], v[138:141], v[194:197], v[44:47]
	v_mfma_f32_16x16x32_bf16 v[40:43], v[150:153], v[194:197], v[40:43]
	v_mfma_f32_16x16x32_bf16 v[28:31], v[138:141], v[202:205], v[28:31]
	v_mfma_f32_16x16x32_bf16 v[24:27], v[150:153], v[202:205], v[24:27]
	v_mfma_f32_16x16x32_bf16 v[12:15], v[138:141], v[210:213], v[12:15]
	v_mfma_f32_16x16x32_bf16 v[8:11], v[150:153], v[210:213], v[8:11]
	v_mfma_f32_16x16x32_bf16 v[60:63], v[142:145], v[190:193], v[60:63]
	v_mfma_f32_16x16x32_bf16 v[56:59], v[154:157], v[190:193], v[56:59]
	v_mfma_f32_16x16x32_bf16 v[44:47], v[142:145], v[198:201], v[44:47]
	v_mfma_f32_16x16x32_bf16 v[40:43], v[154:157], v[198:201], v[40:43]
	v_mfma_f32_16x16x32_bf16 v[28:31], v[142:145], v[206:209], v[28:31]
	v_mfma_f32_16x16x32_bf16 v[24:27], v[154:157], v[206:209], v[24:27]
	v_mfma_f32_16x16x32_bf16 v[12:15], v[142:145], v[214:217], v[12:15]
	v_mfma_f32_16x16x32_bf16 v[8:11], v[154:157], v[214:217], v[8:11]
	v_mfma_f32_16x16x32_bf16 v[52:55], v[170:173], v[186:189], v[52:55]
	v_mfma_f32_16x16x32_bf16 v[48:51], v[178:181], v[186:189], v[48:51]
	v_mfma_f32_16x16x32_bf16 v[36:39], v[170:173], v[194:197], v[36:39]
	v_mfma_f32_16x16x32_bf16 v[32:35], v[178:181], v[194:197], v[32:35]
	v_mfma_f32_16x16x32_bf16 v[20:23], v[170:173], v[202:205], v[20:23]
	v_mfma_f32_16x16x32_bf16 v[16:19], v[178:181], v[202:205], v[16:19]
	v_mfma_f32_16x16x32_bf16 v[4:7], v[170:173], v[210:213], v[4:7]
	v_mfma_f32_16x16x32_bf16 v[0:3], v[178:181], v[210:213], v[0:3]
	v_mfma_f32_16x16x32_bf16 v[52:55], v[174:177], v[190:193], v[52:55]
	v_mfma_f32_16x16x32_bf16 v[48:51], v[182:185], v[190:193], v[48:51]
	v_mfma_f32_16x16x32_bf16 v[36:39], v[174:177], v[198:201], v[36:39]
	v_mfma_f32_16x16x32_bf16 v[32:35], v[182:185], v[198:201], v[32:35]
	v_mfma_f32_16x16x32_bf16 v[20:23], v[174:177], v[206:209], v[20:23]
	v_mfma_f32_16x16x32_bf16 v[16:19], v[182:185], v[206:209], v[16:19]
	v_mfma_f32_16x16x32_bf16 v[4:7], v[174:177], v[214:217], v[4:7]
	v_mfma_f32_16x16x32_bf16 v[0:3], v[182:185], v[214:217], v[0:3]
	s_barrier
; #define PG8_STAGE(bufoff, gbase, voff) do { _Pragma("unroll") for (int _i = 0; _i < 2; ++_i) \
;         __builtin_amdgcn_global_load_lds((const unsigned*)((const char*)(gbase) + (voff)[_i]), (LAS unsigned*)(lds + (bufoff) + ldsw + _i * 8192), 16, 0, 0); } while (0)
; #define PG8_LDA(dst, b, h) do { _Pragma("unroll") for (int m = 0; m < 4; ++m) _Pragma("unroll") for (int k = 0; k < 2; ++k) dst[m][k] = *(const LAS bf16x8*)(lds + PG8_SA(b, h) + aoff + m * 2048 + k * 1024); } while (0)
; #define PG8_LDB(dst, b, h) do { _Pragma("unroll") for (int n = 0; n < 2; ++n) _Pragma("unroll") for (int k = 0; k < 2; ++k) dst[n][k] = *(const LAS bf16x8*)(lds + PG8_SB(b, h) + boff + n * 2048 + k * 1024); } while (0)
; #define PG8_MMA(ai, bj, At, Bt) do { __builtin_amdgcn_s_setprio(1); _Pragma("unroll") for (int m = 0; m < 4; ++m) _Pragma("unroll") for (int n = 0; n < 2; ++n) _Pragma("unroll") for (int k = 0; k < 2; ++k) \
;         acc[ai][bj][m][n] = __builtin_amdgcn_mfma_f32_16x16x32_bf16(Bt[n][k], At[m][k], acc[ai][bj][m][n], 0, 0, 0); __builtin_amdgcn_s_setprio(0); } while (0)
; #define PG8_WAIT_V(n) asm volatile("s_waitcnt vmcnt(" #n ")" ::: "memory")
; #define PG8_WAIT_L(n) asm volatile("s_waitcnt lgkmcnt(" #n ")" ::: "memory")
; #define PG8_BAR __builtin_amdgcn_s_barrier()
; #define PG8_SCHED __builtin_amdgcn_sched_barrier(0)
; template <class Epi, class Sched, bool ALIGN_EPI = true, bool SP2 = true>
; __device__ __forceinline__ void gemm_phase(LAS unsigned char* lds, const Gemm g, const Sched& S, const Epi& E) {
;     ...
;             PG8_LDB(B0, 1, 0); PG8_LDB(B1, 1, 1); PG8_SCHED; PG8_LDA(At, 1, 0); PG8_STAGE(PG8_SA(0, 1), a2 + hstep, voffA);
;             PG8_WAIT_V(8); PG8_WAIT_L(0); PG8_BAR; PG8_MMA(0, 0, At, B0); PG8_MMA(0, 1, At, B1); PG8_BAR; PG8_SCHED;
;             PG8_LDA(At, 1, 1); PG8_STAGE(PG8_SB(1, 0), b3, voffB); PG8_STAGE(PG8_SB(1, 1), b3 + hstep, voffB); PG8_STAGE(PG8_SA(1, 0), a3, voffA);
;             PG8_WAIT_V(8); PG8_WAIT_L(0); PG8_BAR; PG8_MMA(1, 0, At, B0); PG8_MMA(1, 1, At, B1); PG8_BAR; PG8_SCHED;
;     ...
;         if constexpr (ALIGN_EPI) { if (wr == 0) PG8_BAR; }
	s_add_i32 s46, 0, 0x18000
	s_add_i32 s47, 0, 0x1c000
	v_add_u32_e32 v154, s46, v147
	v_add_u32_e32 v182, s47, v147
	ds_read_b128 v[138:141], v154
	ds_read_b128 v[142:145], v154 offset:1024
	ds_read_b128 v[150:153], v154 offset:2048
	ds_read_b128 v[154:157], v154 offset:3072
	ds_read_b128 v[170:173], v182
	ds_read_b128 v[174:177], v182 offset:1024
	ds_read_b128 v[178:181], v182 offset:2048
	ds_read_b128 v[182:185], v182 offset:3072
	s_add_u32 s72, s72, 0x40000
	s_addc_u32 s73, s73, 0
	s_mov_b32 m0, s92
	ds_read_b128 v[186:189], v149 offset:32768
	ds_read_b128 v[190:193], v149 offset:33792
	ds_read_b128 v[194:197], v149 offset:34816
	ds_read_b128 v[198:201], v149 offset:35840
	ds_read_b128 v[202:205], v149 offset:36864
	ds_read_b128 v[206:209], v149 offset:37888
	ds_read_b128 v[210:213], v149 offset:38912
	ds_read_b128 v[214:217], v149 offset:39936
	global_load_lds_dwordx4 v128, s[72:73]
	s_mov_b32 m0, s93
	s_nop 0
	global_load_lds_dwordx4 v130, s[72:73]
	s_waitcnt vmcnt(8)
	s_waitcnt lgkmcnt(0)
	s_barrier
	s_waitcnt lgkmcnt(0)
	v_mfma_f32_16x16x32_bf16 v[124:127], v[138:141], v[186:189], v[124:127]
	v_mfma_f32_16x16x32_bf16 v[120:123], v[150:153], v[186:189], v[120:123]
	v_mfma_f32_16x16x32_bf16 v[108:111], v[138:141], v[194:197], v[108:111]
	v_mfma_f32_16x16x32_bf16 v[104:107], v[150:153], v[194:197], v[104:107]
	v_mfma_f32_16x16x32_bf16 v[92:95], v[138:141], v[202:205], v[92:95]
	v_mfma_f32_16x16x32_bf16 v[88:91], v[150:153], v[202:205], v[88:91]
	v_mfma_f32_16x16x32_bf16 v[76:79], v[138:141], v[210:213], v[76:79]
	v_mfma_f32_16x16x32_bf16 v[72:75], v[150:153], v[210:213], v[72:75]
	v_mfma_f32_16x16x32_bf16 v[124:127], v[142:145], v[190:193], v[124:127]
	v_mfma_f32_16x16x32_bf16 v[120:123], v[154:157], v[190:193], v[120:123]
	v_mfma_f32_16x16x32_bf16 v[108:111], v[142:145], v[198:201], v[108:111]
	v_mfma_f32_16x16x32_bf16 v[104:107], v[154:157], v[198:201], v[104:107]
	v_mfma_f32_16x16x32_bf16 v[92:95], v[142:145], v[206:209], v[92:95]
	v_mfma_f32_16x16x32_bf16 v[88:91], v[154:157], v[206:209], v[88:91]
	v_mfma_f32_16x16x32_bf16 v[76:79], v[142:145], v[214:217], v[76:79]
	v_mfma_f32_16x16x32_bf16 v[72:75], v[154:157], v[214:217], v[72:75]
	v_mfma_f32_16x16x32_bf16 v[116:119], v[170:173], v[186:189], v[116:119]
	v_mfma_f32_16x16x32_bf16 v[112:115], v[178:181], v[186:189], v[112:115]
	v_mfma_f32_16x16x32_bf16 v[100:103], v[170:173], v[194:197], v[100:103]
	v_mfma_f32_16x16x32_bf16 v[96:99], v[178:181], v[194:197], v[96:99]
	v_mfma_f32_16x16x32_bf16 v[84:87], v[170:173], v[202:205], v[84:87]
	v_mfma_f32_16x16x32_bf16 v[80:83], v[178:181], v[202:205], v[80:83]
	v_mfma_f32_16x16x32_bf16 v[68:71], v[170:173], v[210:213], v[68:71]
	v_mfma_f32_16x16x32_bf16 v[64:67], v[178:181], v[210:213], v[64:67]
	v_mfma_f32_16x16x32_bf16 v[116:119], v[174:177], v[190:193], v[116:119]
	v_mfma_f32_16x16x32_bf16 v[112:115], v[182:185], v[190:193], v[112:115]
	v_mfma_f32_16x16x32_bf16 v[100:103], v[174:177], v[198:201], v[100:103]
	v_mfma_f32_16x16x32_bf16 v[96:99], v[182:185], v[198:201], v[96:99]
	v_mfma_f32_16x16x32_bf16 v[84:87], v[174:177], v[206:209], v[84:87]
	v_mfma_f32_16x16x32_bf16 v[80:83], v[182:185], v[206:209], v[80:83]
	v_mfma_f32_16x16x32_bf16 v[68:71], v[174:177], v[214:217], v[68:71]
	v_mfma_f32_16x16x32_bf16 v[64:67], v[182:185], v[214:217], v[64:67]
	s_barrier
	s_add_i32 s46, s46, s90
	s_mov_b32 m0, s46
	ds_read_b128 v[186:189], v149 offset:49152
	ds_read_b128 v[190:193], v149 offset:50176
	ds_read_b128 v[194:197], v149 offset:51200
	ds_read_b128 v[198:201], v149 offset:52224
	ds_read_b128 v[202:205], v149 offset:53248
	ds_read_b128 v[206:209], v149 offset:54272
	ds_read_b128 v[210:213], v149 offset:55296
	ds_read_b128 v[214:217], v149 offset:56320
	s_add_u32 s98, s24, 0x80
	s_addc_u32 s99, s25, 0
	global_load_lds_dwordx4 v160, s[98:99]
	s_add_i32 m0, s46, 0x2000
	s_add_u32 s24, s24, 0x40080
	s_addc_u32 s25, s25, 0
	s_add_i32 s46, s47, s90
	global_load_lds_dwordx4 v132, s[98:99]
	s_mov_b32 m0, s46
	s_nop 0
	global_load_lds_dwordx4 v160, s[24:25]
	s_add_i32 m0, s46, 0x2000
	s_nop 0
	global_load_lds_dwordx4 v132, s[24:25]
	s_mov_b32 m0, s94
	s_nop 0
	s_add_u32 s98, s72, 0xfffc0080
	s_addc_u32 s99, s73, -1
	global_load_lds_dwordx4 v128, s[98:99]
	s_mov_b32 m0, s95
	s_nop 0
	global_load_lds_dwordx4 v130, s[98:99]
	s_waitcnt vmcnt(8)
	s_waitcnt lgkmcnt(0)
	s_barrier
	s_waitcnt lgkmcnt(0)
	v_mfma_f32_16x16x32_bf16 v[60:63], v[138:141], v[186:189], v[60:63]
	v_mfma_f32_16x16x32_bf16 v[56:59], v[150:153], v[186:189], v[56:59]
	v_mfma_f32_16x16x32_bf16 v[44:47], v[138:141], v[194:197], v[44:47]
	v_mfma_f32_16x16x32_bf16 v[40:43], v[150:153], v[194:197], v[40:43]
	v_mfma_f32_16x16x32_bf16 v[28:31], v[138:141], v[202:205], v[28:31]
	v_mfma_f32_16x16x32_bf16 v[24:27], v[150:153], v[202:205], v[24:27]
	v_mfma_f32_16x16x32_bf16 v[12:15], v[138:141], v[210:213], v[12:15]
	v_mfma_f32_16x16x32_bf16 v[8:11], v[150:153], v[210:213], v[8:11]
	v_mfma_f32_16x16x32_bf16 v[60:63], v[142:145], v[190:193], v[60:63]
	v_mfma_f32_16x16x32_bf16 v[56:59], v[154:157], v[190:193], v[56:59]
	v_mfma_f32_16x16x32_bf16 v[44:47], v[142:145], v[198:201], v[44:47]
	v_mfma_f32_16x16x32_bf16 v[40:43], v[154:157], v[198:201], v[40:43]
	v_mfma_f32_16x16x32_bf16 v[28:31], v[142:145], v[206:209], v[28:31]
	v_mfma_f32_16x16x32_bf16 v[24:27], v[154:157], v[206:209], v[24:27]
	v_mfma_f32_16x16x32_bf16 v[12:15], v[142:145], v[214:217], v[12:15]
	v_mfma_f32_16x16x32_bf16 v[8:11], v[154:157], v[214:217], v[8:11]
	v_mfma_f32_16x16x32_bf16 v[52:55], v[170:173], v[186:189], v[52:55]
	v_mfma_f32_16x16x32_bf16 v[48:51], v[178:181], v[186:189], v[48:51]
	v_mfma_f32_16x16x32_bf16 v[36:39], v[170:173], v[194:197], v[36:39]
	v_mfma_f32_16x16x32_bf16 v[32:35], v[178:181], v[194:197], v[32:35]
	v_mfma_f32_16x16x32_bf16 v[20:23], v[170:173], v[202:205], v[20:23]
	v_mfma_f32_16x16x32_bf16 v[16:19], v[178:181], v[202:205], v[16:19]
	v_mfma_f32_16x16x32_bf16 v[4:7], v[170:173], v[210:213], v[4:7]
	v_mfma_f32_16x16x32_bf16 v[0:3], v[178:181], v[210:213], v[0:3]
	v_mfma_f32_16x16x32_bf16 v[52:55], v[174:177], v[190:193], v[52:55]
	v_mfma_f32_16x16x32_bf16 v[48:51], v[182:185], v[190:193], v[48:51]
	v_mfma_f32_16x16x32_bf16 v[36:39], v[174:177], v[198:201], v[36:39]
	v_mfma_f32_16x16x32_bf16 v[32:35], v[182:185], v[198:201], v[32:35]
	v_mfma_f32_16x16x32_bf16 v[20:23], v[174:177], v[206:209], v[20:23]
	v_mfma_f32_16x16x32_bf16 v[16:19], v[182:185], v[206:209], v[16:19]
	v_mfma_f32_16x16x32_bf16 v[4:7], v[174:177], v[214:217], v[4:7]
	v_mfma_f32_16x16x32_bf16 v[0:3], v[182:185], v[214:217], v[0:3]
	s_barrier
	s_add_i32 s53, s53, 2
	s_add_u32 s66, s66, 0x100
	s_addc_u32 s67, s67, 0
	s_add_u32 s44, s44, 0x100
	s_addc_u32 s45, s45, 0
	s_cmp_gt_u32 s53, 13
	s_cbranch_scc0 .LBB0_187
	s_setprio 0
	s_and_b64 vcc, exec, s[18:19]
	s_cbranch_vccz .LBB0_190
	s_barrier

; #define PG8_STAGE(bufoff, gbase, voff) do { _Pragma("unroll") for (int _i = 0; _i < 2; ++_i) \
;         __builtin_amdgcn_global_load_lds((const unsigned*)((const char*)(gbase) + (voff)[_i]), (LAS unsigned*)(lds + (bufoff) + ldsw + _i * 8192), 16, 0, 0); } while (0)
; #define PG8_LDA(dst, b, h) do { _Pragma("unroll") for (int m = 0; m < 4; ++m) _Pragma("unroll") for (int k = 0; k < 2; ++k) dst[m][k] = *(const LAS bf16x8*)(lds + PG8_SA(b, h) + aoff + m * 2048 + k * 1024); } while (0)
; #define PG8_LDB(dst, b, h) do { _Pragma("unroll") for (int n = 0; n < 2; ++n) _Pragma("unroll") for (int k = 0; k < 2; ++k) dst[n][k] = *(const LAS bf16x8*)(lds + PG8_SB(b, h) + boff + n * 2048 + k * 1024); } while (0)
; #define PG8_SCHED __builtin_amdgcn_sched_barrier(0)
; template <class Epi, class Sched, bool ALIGN_EPI = true, bool SP2 = true>
; __device__ __forceinline__ void gemm_phase(LAS unsigned char* lds, const Gemm g, const Sched& S, const Epi& E) {
;     ...
;         const bool has_next = S.next(ui + 1, nxt);
;         const char* nA = has_next ? (const char*)g.A + (size_t)nxt.pm * tstep : cA; const char* nB = has_next ? (const char*)g.Bt + (size_t)nxt.pn * tstep : cB;
;         for (int t = 0; t < nt; t += 2) {
;             const bool last = (t == nt - 2);
;             const char* a1 = cA + (size_t)(t + 1) * kstep;
;             const char* a2 = last ? nA : cA + (size_t)(t + 2) * kstep; const char* b2 = last ? nB : cB + (size_t)(t + 2) * kstep;
;             const char* a3 = a2 + kstep; const char* b3 = b2 + kstep;
;             if constexpr (SP2) {
;             PG8_LDB(B0, 0, 0); PG8_LDB(B1, 0, 1); PG8_SCHED; PG8_LDA(At, 0, 0); PG8_STAGE(PG8_SA(1, 1), a1 + hstep, voffA);
;     ...
; #pragma unroll
;         for (int a = 0; a < 2; ++a)
; #pragma unroll
;             for (int b = 0; b < 2; ++b)
; #pragma unroll
;                 for (int m = 0; m < 4; ++m)
; #pragma unroll
;                     for (int n = 0; n < 2; ++n) acc[a][b][m][n] = (f32x4){0.f, 0.f, 0.f, 0.f};
.LBB0_210:
	s_ashr_i32 s19, s18, 31
	s_lshl_b64 s[2:3], s[18:19], 19
	s_add_u32 s30, s41, s2
	s_addc_u32 s31, s66, s3
	s_and_b64 s[2:3], s[4:5], exec
	s_cselect_b32 s2, s31, s25
	s_cselect_b32 s3, s30, s24
	s_ashr_i32 s17, s16, 31
	s_lshl_b64 s[44:45], s[16:17], 19
	s_add_u32 s52, s67, s44
	s_addc_u32 s53, s72, s45
	s_and_b64 s[44:45], s[4:5], exec
	s_cselect_b32 s17, s53, s63
	s_cselect_b32 s19, s52, s62
	s_add_u32 s60, s24, 0x40080
	s_addc_u32 s61, s25, 0
	s_add_u32 s43, s62, 0x100
	v_mov_b32_e32 v0, 0
	s_addc_u32 s44, s63, 0
	s_mov_b32 s45, -2
	v_mov_b32_e32 v1, v0
	v_mov_b32_e32 v2, v0
	v_mov_b32_e32 v3, v0
	v_mov_b32_e32 v4, v0
	v_mov_b32_e32 v5, v0
	v_mov_b32_e32 v6, v0
	v_mov_b32_e32 v7, v0
	v_mov_b32_e32 v16, v0
	v_mov_b32_e32 v17, v0
	v_mov_b32_e32 v18, v0
	v_mov_b32_e32 v19, v0
	v_mov_b32_e32 v20, v0
	v_mov_b32_e32 v21, v0
	v_mov_b32_e32 v22, v0
	v_mov_b32_e32 v23, v0
	v_mov_b32_e32 v32, v0
	v_mov_b32_e32 v33, v0
	v_mov_b32_e32 v34, v0
	v_mov_b32_e32 v35, v0
	s_waitcnt vmcnt(0)
	v_mov_b32_e32 v36, v0
	v_mov_b32_e32 v37, v0
	v_mov_b32_e32 v38, v0
	v_mov_b32_e32 v39, v0
	s_waitcnt vmcnt(0)
	v_mov_b32_e32 v48, v0
	v_mov_b32_e32 v49, v0
	v_mov_b32_e32 v50, v0
	v_mov_b32_e32 v51, v0
	v_mov_b32_e32 v52, v0
	v_mov_b32_e32 v53, v0
	v_mov_b32_e32 v54, v0
	v_mov_b32_e32 v55, v0
	v_mov_b32_e32 v8, v0
	v_mov_b32_e32 v9, v0
	v_mov_b32_e32 v10, v0
	v_mov_b32_e32 v11, v0
	v_mov_b32_e32 v12, v0
	v_mov_b32_e32 v13, v0
	v_mov_b32_e32 v14, v0
	v_mov_b32_e32 v15, v0
	v_mov_b32_e32 v24, v0
	v_mov_b32_e32 v25, v0
	v_mov_b32_e32 v26, v0
	v_mov_b32_e32 v27, v0
	v_mov_b32_e32 v28, v0
	v_mov_b32_e32 v29, v0
	v_mov_b32_e32 v30, v0
	v_mov_b32_e32 v31, v0
	v_mov_b32_e32 v40, v0
	v_mov_b32_e32 v41, v0
	v_mov_b32_e32 v42, v0
	v_mov_b32_e32 v43, v0
	v_mov_b32_e32 v44, v0
	v_mov_b32_e32 v45, v0
	v_mov_b32_e32 v46, v0
	v_mov_b32_e32 v47, v0
	v_mov_b32_e32 v56, v0
	v_mov_b32_e32 v57, v0
	v_mov_b32_e32 v58, v0
	v_mov_b32_e32 v59, v0
	v_mov_b32_e32 v60, v0
	v_mov_b32_e32 v61, v0
	v_mov_b32_e32 v62, v0
	v_mov_b32_e32 v63, v0
	v_mov_b32_e32 v64, v0
	v_mov_b32_e32 v65, v0
	v_mov_b32_e32 v66, v0
	v_mov_b32_e32 v67, v0
	v_mov_b32_e32 v68, v0
	v_mov_b32_e32 v69, v0
	v_mov_b32_e32 v70, v0
	v_mov_b32_e32 v71, v0
	v_mov_b32_e32 v80, v0
	v_mov_b32_e32 v81, v0
	v_mov_b32_e32 v82, v0
	v_mov_b32_e32 v83, v0
	v_mov_b32_e32 v84, v0
	v_mov_b32_e32 v85, v0
	v_mov_b32_e32 v86, v0
	v_mov_b32_e32 v87, v0
	v_mov_b32_e32 v96, v0
	v_mov_b32_e32 v97, v0
	v_mov_b32_e32 v98, v0
	v_mov_b32_e32 v99, v0
	v_mov_b32_e32 v100, v0
	v_mov_b32_e32 v101, v0
	v_mov_b32_e32 v102, v0
	v_mov_b32_e32 v103, v0
	v_mov_b32_e32 v112, v0
	v_mov_b32_e32 v113, v0
	v_mov_b32_e32 v114, v0
	v_mov_b32_e32 v115, v0
	v_mov_b32_e32 v116, v0
	v_mov_b32_e32 v117, v0
	v_mov_b32_e32 v118, v0
	v_mov_b32_e32 v119, v0
	v_mov_b32_e32 v72, v0
	v_mov_b32_e32 v73, v0
	v_mov_b32_e32 v74, v0
	v_mov_b32_e32 v75, v0
	v_mov_b32_e32 v76, v0
	v_mov_b32_e32 v77, v0
	v_mov_b32_e32 v78, v0
	v_mov_b32_e32 v79, v0
	v_mov_b32_e32 v88, v0
	v_mov_b32_e32 v89, v0
	v_mov_b32_e32 v90, v0
	v_mov_b32_e32 v91, v0
	v_mov_b32_e32 v92, v0
	v_mov_b32_e32 v93, v0
	v_mov_b32_e32 v94, v0
	v_mov_b32_e32 v95, v0
	v_mov_b32_e32 v104, v0
	v_mov_b32_e32 v105, v0
	v_mov_b32_e32 v106, v0
	v_mov_b32_e32 v107, v0
	v_mov_b32_e32 v108, v0
	v_mov_b32_e32 v109, v0
	v_mov_b32_e32 v110, v0
	v_mov_b32_e32 v111, v0
	v_mov_b32_e32 v120, v0
	v_mov_b32_e32 v121, v0
	v_mov_b32_e32 v122, v0
	v_mov_b32_e32 v123, v0
	v_mov_b32_e32 v124, v0
	v_mov_b32_e32 v125, v0
	v_mov_b32_e32 v126, v0
	v_mov_b32_e32 v127, v0
	v_lshrrev_b32_e32 v226, 8, v238
	v_cmp_ne_u32_e64 s[98:99], 0, v226
	s_nop 3
	s_and_b64 s[98:99], s[98:99], exec
	s_cbranch_scc0 .Lprio_skip_211
	s_setprio 1
.Lprio_skip_211:
.LBB0_211:
	s_add_u32 s24, s60, 0xfffc0080
	s_addc_u32 s25, s61, -1
	s_add_i32 s46, 0, 0x10000
	s_cmp_eq_u32 s45, 12
	s_cselect_b32 s63, s2, s25
	s_cselect_b32 s62, s3, s24
	s_cselect_b32 s25, s17, s44
	s_cselect_b32 s24, s19, s43
	s_add_i32 s47, 0, 0x14000
	v_add_u32_e32 v154, s46, v147
	v_add_u32_e32 v158, s47, v147
	ds_read_b128 v[138:141], v154
	ds_read_b128 v[142:145], v154 offset:1024
	ds_read_b128 v[150:153], v154 offset:2048
	ds_read_b128 v[154:157], v154 offset:3072
	ds_read_b128 v[170:173], v158
	ds_read_b128 v[174:177], v158 offset:1024
	ds_read_b128 v[178:181], v158 offset:2048
	ds_read_b128 v[182:185], v158 offset:3072
	s_add_i32 m0, s55, 0xc000
	ds_read_b128 v[186:189], v149
	ds_read_b128 v[190:193], v149 offset:1024
	ds_read_b128 v[194:197], v149 offset:2048
	ds_read_b128 v[198:201], v149 offset:3072
	ds_read_b128 v[202:205], v149 offset:4096
	ds_read_b128 v[206:209], v149 offset:5120
	ds_read_b128 v[210:213], v149 offset:6144
	ds_read_b128 v[214:217], v149 offset:7168
	global_load_lds_dwordx4 v134, s[60:61]
	s_add_i32 m0, s55, 0xe000
	s_nop 0
	global_load_lds_dwordx4 v136, s[60:61]
	s_waitcnt vmcnt(8)
	s_waitcnt lgkmcnt(0)
	s_barrier
; #define PG8_STAGE(bufoff, gbase, voff) do { _Pragma("unroll") for (int _i = 0; _i < 2; ++_i) \
;         __builtin_amdgcn_global_load_lds((const unsigned*)((const char*)(gbase) + (voff)[_i]), (LAS unsigned*)(lds + (bufoff) + ldsw + _i * 8192), 16, 0, 0); } while (0)
; #define PG8_LDA(dst, b, h) do { _Pragma("unroll") for (int m = 0; m < 4; ++m) _Pragma("unroll") for (int k = 0; k < 2; ++k) dst[m][k] = *(const LAS bf16x8*)(lds + PG8_SA(b, h) + aoff + m * 2048 + k * 1024); } while (0)
; #define PG8_MMA(ai, bj, At, Bt) do { __builtin_amdgcn_s_setprio(1); _Pragma("unroll") for (int m = 0; m < 4; ++m) _Pragma("unroll") for (int n = 0; n < 2; ++n) _Pragma("unroll") for (int k = 0; k < 2; ++k) \
;         acc[ai][bj][m][n] = __builtin_amdgcn_mfma_f32_16x16x32_bf16(Bt[n][k], At[m][k], acc[ai][bj][m][n], 0, 0, 0); __builtin_amdgcn_s_setprio(0); } while (0)
; #define PG8_WAIT_V(n) asm volatile("s_waitcnt vmcnt(" #n ")" ::: "memory")
; #define PG8_WAIT_L(n) asm volatile("s_waitcnt lgkmcnt(" #n ")" ::: "memory")
; #define PG8_BAR __builtin_amdgcn_s_barrier()
; #define PG8_SCHED __builtin_amdgcn_sched_barrier(0)
; template <class Epi, class Sched, bool ALIGN_EPI = true, bool SP2 = true>
; __device__ __forceinline__ void gemm_phase(LAS unsigned char* lds, const Gemm g, const Sched& S, const Epi& E) {
;     ...
;             PG8_WAIT_V(8); PG8_WAIT_L(0); PG8_BAR; PG8_MMA(0, 0, At, B0); PG8_MMA(0, 1, At, B1); PG8_BAR; PG8_SCHED;
;             PG8_LDA(At, 0, 1); PG8_STAGE(PG8_SB(0, 0), b2, voffB); PG8_STAGE(PG8_SB(0, 1), b2 + hstep, voffB); PG8_STAGE(PG8_SA(0, 0), a2, voffA);
;             PG8_WAIT_V(8); PG8_WAIT_L(0); PG8_BAR; PG8_MMA(1, 0, At, B0); PG8_MMA(1, 1, At, B1); PG8_BAR; PG8_SCHED;
	s_waitcnt lgkmcnt(0)
	v_mfma_f32_16x16x32_bf16 v[124:127], v[138:141], v[186:189], v[124:127]
	v_mfma_f32_16x16x32_bf16 v[120:123], v[150:153], v[186:189], v[120:123]
	v_mfma_f32_16x16x32_bf16 v[108:111], v[138:141], v[194:197], v[108:111]
	v_mfma_f32_16x16x32_bf16 v[104:107], v[150:153], v[194:197], v[104:107]
	v_mfma_f32_16x16x32_bf16 v[92:95], v[138:141], v[202:205], v[92:95]
	v_mfma_f32_16x16x32_bf16 v[88:91], v[150:153], v[202:205], v[88:91]
	v_mfma_f32_16x16x32_bf16 v[76:79], v[138:141], v[210:213], v[76:79]
	v_mfma_f32_16x16x32_bf16 v[72:75], v[150:153], v[210:213], v[72:75]
	v_mfma_f32_16x16x32_bf16 v[124:127], v[142:145], v[190:193], v[124:127]
	v_mfma_f32_16x16x32_bf16 v[120:123], v[154:157], v[190:193], v[120:123]
	v_mfma_f32_16x16x32_bf16 v[108:111], v[142:145], v[198:201], v[108:111]
	v_mfma_f32_16x16x32_bf16 v[104:107], v[154:157], v[198:201], v[104:107]
	v_mfma_f32_16x16x32_bf16 v[92:95], v[142:145], v[206:209], v[92:95]
	v_mfma_f32_16x16x32_bf16 v[88:91], v[154:157], v[206:209], v[88:91]
	v_mfma_f32_16x16x32_bf16 v[76:79], v[142:145], v[214:217], v[76:79]
	v_mfma_f32_16x16x32_bf16 v[72:75], v[154:157], v[214:217], v[72:75]
	v_mfma_f32_16x16x32_bf16 v[116:119], v[170:173], v[186:189], v[116:119]
	v_mfma_f32_16x16x32_bf16 v[112:115], v[178:181], v[186:189], v[112:115]
	v_mfma_f32_16x16x32_bf16 v[100:103], v[170:173], v[194:197], v[100:103]
	v_mfma_f32_16x16x32_bf16 v[96:99], v[178:181], v[194:197], v[96:99]
	v_mfma_f32_16x16x32_bf16 v[84:87], v[170:173], v[202:205], v[84:87]
	v_mfma_f32_16x16x32_bf16 v[80:83], v[178:181], v[202:205], v[80:83]
	v_mfma_f32_16x16x32_bf16 v[68:71], v[170:173], v[210:213], v[68:71]
	v_mfma_f32_16x16x32_bf16 v[64:67], v[178:181], v[210:213], v[64:67]
	v_mfma_f32_16x16x32_bf16 v[116:119], v[174:177], v[190:193], v[116:119]
	v_mfma_f32_16x16x32_bf16 v[112:115], v[182:185], v[190:193], v[112:115]
	v_mfma_f32_16x16x32_bf16 v[100:103], v[174:177], v[198:201], v[100:103]
	v_mfma_f32_16x16x32_bf16 v[96:99], v[182:185], v[198:201], v[96:99]
	v_mfma_f32_16x16x32_bf16 v[84:87], v[174:177], v[206:209], v[84:87]
	v_mfma_f32_16x16x32_bf16 v[80:83], v[182:185], v[206:209], v[80:83]
	v_mfma_f32_16x16x32_bf16 v[68:71], v[174:177], v[214:217], v[68:71]
	v_mfma_f32_16x16x32_bf16 v[64:67], v[182:185], v[214:217], v[64:67]
	s_barrier
	s_add_i32 s46, s46, s73
	s_mov_b32 m0, s46
	ds_read_b128 v[186:189], v149 offset:16384
	ds_read_b128 v[190:193], v149 offset:17408
	ds_read_b128 v[194:197], v149 offset:18432
	ds_read_b128 v[198:201], v149 offset:19456
	ds_read_b128 v[202:205], v149 offset:20480
	ds_read_b128 v[206:209], v149 offset:21504
	ds_read_b128 v[210:213], v149 offset:22528
	ds_read_b128 v[214:217], v149 offset:23552
	global_load_lds_dwordx4 v160, s[24:25]
	s_add_i32 m0, s46, 0x2000
	s_add_u32 s94, s24, 0x40000
	s_addc_u32 s95, s25, 0
	s_add_i32 s46, s47, s73
	global_load_lds_dwordx4 v132, s[24:25]
	s_mov_b32 m0, s46
	s_nop 0
	global_load_lds_dwordx4 v160, s[94:95]
	s_add_i32 m0, s46, 0x2000
	s_nop 0
	global_load_lds_dwordx4 v132, s[94:95]
	s_mov_b32 m0, s55
	s_nop 0
	global_load_lds_dwordx4 v128, s[62:63]
	s_mov_b32 m0, s79
	s_nop 0
	global_load_lds_dwordx4 v130, s[62:63]
	s_waitcnt vmcnt(8)
	s_waitcnt lgkmcnt(0)
	s_barrier
	s_waitcnt lgkmcnt(0)
	v_mfma_f32_16x16x32_bf16 v[60:63], v[138:141], v[186:189], v[60:63]
	v_mfma_f32_16x16x32_bf16 v[56:59], v[150:153], v[186:189], v[56:59]
	v_mfma_f32_16x16x32_bf16 v[44:47], v[138:141], v[194:197], v[44:47]
	v_mfma_f32_16x16x32_bf16 v[40:43], v[150:153], v[194:197], v[40:43]
	v_mfma_f32_16x16x32_bf16 v[28:31], v[138:141], v[202:205], v[28:31]
	v_mfma_f32_16x16x32_bf16 v[24:27], v[150:153], v[202:205], v[24:27]
	v_mfma_f32_16x16x32_bf16 v[12:15], v[138:141], v[210:213], v[12:15]
	v_mfma_f32_16x16x32_bf16 v[8:11], v[150:153], v[210:213], v[8:11]
	v_mfma_f32_16x16x32_bf16 v[60:63], v[142:145], v[190:193], v[60:63]
	v_mfma_f32_16x16x32_bf16 v[56:59], v[154:157], v[190:193], v[56:59]
	v_mfma_f32_16x16x32_bf16 v[44:47], v[142:145], v[198:201], v[44:47]
	v_mfma_f32_16x16x32_bf16 v[40:43], v[154:157], v[198:201], v[40:43]
	v_mfma_f32_16x16x32_bf16 v[28:31], v[142:145], v[206:209], v[28:31]
	v_mfma_f32_16x16x32_bf16 v[24:27], v[154:157], v[206:209], v[24:27]
	v_mfma_f32_16x16x32_bf16 v[12:15], v[142:145], v[214:217], v[12:15]
	v_mfma_f32_16x16x32_bf16 v[8:11], v[154:157], v[214:217], v[8:11]
	v_mfma_f32_16x16x32_bf16 v[52:55], v[170:173], v[186:189], v[52:55]
	v_mfma_f32_16x16x32_bf16 v[48:51], v[178:181], v[186:189], v[48:51]
	v_mfma_f32_16x16x32_bf16 v[36:39], v[170:173], v[194:197], v[36:39]
	v_mfma_f32_16x16x32_bf16 v[32:35], v[178:181], v[194:197], v[32:35]
	v_mfma_f32_16x16x32_bf16 v[20:23], v[170:173], v[202:205], v[20:23]
	v_mfma_f32_16x16x32_bf16 v[16:19], v[178:181], v[202:205], v[16:19]
	v_mfma_f32_16x16x32_bf16 v[4:7], v[170:173], v[210:213], v[4:7]
	v_mfma_f32_16x16x32_bf16 v[0:3], v[178:181], v[210:213], v[0:3]
	v_mfma_f32_16x16x32_bf16 v[52:55], v[174:177], v[190:193], v[52:55]
	v_mfma_f32_16x16x32_bf16 v[48:51], v[182:185], v[190:193], v[48:51]
	v_mfma_f32_16x16x32_bf16 v[36:39], v[174:177], v[198:201], v[36:39]
	v_mfma_f32_16x16x32_bf16 v[32:35], v[182:185], v[198:201], v[32:35]
	v_mfma_f32_16x16x32_bf16 v[20:23], v[174:177], v[206:209], v[20:23]
	v_mfma_f32_16x16x32_bf16 v[16:19], v[182:185], v[206:209], v[16:19]
	v_mfma_f32_16x16x32_bf16 v[4:7], v[174:177], v[214:217], v[4:7]
	v_mfma_f32_16x16x32_bf16 v[0:3], v[182:185], v[214:217], v[0:3]
	s_barrier
; #define PG8_STAGE(bufoff, gbase, voff) do { _Pragma("unroll") for (int _i = 0; _i < 2; ++_i) \
;         __builtin_amdgcn_global_load_lds((const unsigned*)((const char*)(gbase) + (voff)[_i]), (LAS unsigned*)(lds + (bufoff) + ldsw + _i * 8192), 16, 0, 0); } while (0)
; #define PG8_LDA(dst, b, h) do { _Pragma("unroll") for (int m = 0; m < 4; ++m) _Pragma("unroll") for (int k = 0; k < 2; ++k) dst[m][k] = *(const LAS bf16x8*)(lds + PG8_SA(b, h) + aoff + m * 2048 + k * 1024); } while (0)
; #define PG8_LDB(dst, b, h) do { _Pragma("unroll") for (int n = 0; n < 2; ++n) _Pragma("unroll") for (int k = 0; k < 2; ++k) dst[n][k] = *(const LAS bf16x8*)(lds + PG8_SB(b, h) + boff + n * 2048 + k * 1024); } while (0)
; #define PG8_MMA(ai, bj, At, Bt) do { __builtin_amdgcn_s_setprio(1); _Pragma("unroll") for (int m = 0; m < 4; ++m) _Pragma("unroll") for (int n = 0; n < 2; ++n) _Pragma("unroll") for (int k = 0; k < 2; ++k) \
;         acc[ai][bj][m][n] = __builtin_amdgcn_mfma_f32_16x16x32_bf16(Bt[n][k], At[m][k], acc[ai][bj][m][n], 0, 0, 0); __builtin_amdgcn_s_setprio(0); } while (0)
; #define PG8_WAIT_V(n) asm volatile("s_waitcnt vmcnt(" #n ")" ::: "memory")
; #define PG8_WAIT_L(n) asm volatile("s_waitcnt lgkmcnt(" #n ")" ::: "memory")
; #define PG8_BAR __builtin_amdgcn_s_barrier()
; #define PG8_SCHED __builtin_amdgcn_sched_barrier(0)
; template <class Epi, class Sched, bool ALIGN_EPI = true, bool SP2 = true>
; __device__ __forceinline__ void gemm_phase(LAS unsigned char* lds, const Gemm g, const Sched& S, const Epi& E) {
;     ...
;             PG8_LDB(B0, 1, 0); PG8_LDB(B1, 1, 1); PG8_SCHED; PG8_LDA(At, 1, 0); PG8_STAGE(PG8_SA(0, 1), a2 + hstep, voffA);
;             PG8_WAIT_V(8); PG8_WAIT_L(0); PG8_BAR; PG8_MMA(0, 0, At, B0); PG8_MMA(0, 1, At, B1); PG8_BAR; PG8_SCHED;
;             PG8_LDA(At, 1, 1); PG8_STAGE(PG8_SB(1, 0), b3, voffB); PG8_STAGE(PG8_SB(1, 1), b3 + hstep, voffB); PG8_STAGE(PG8_SA(1, 0), a3, voffA);
;             PG8_WAIT_V(8); PG8_WAIT_L(0); PG8_BAR; PG8_MMA(1, 0, At, B0); PG8_MMA(1, 1, At, B1); PG8_BAR; PG8_SCHED;
	s_add_i32 s46, 0, 0x18000
	s_add_i32 s47, 0, 0x1c000
	v_add_u32_e32 v154, s46, v147
	v_add_u32_e32 v182, s47, v147
	ds_read_b128 v[138:141], v154
	ds_read_b128 v[142:145], v154 offset:1024
	ds_read_b128 v[150:153], v154 offset:2048
	ds_read_b128 v[154:157], v154 offset:3072
	ds_read_b128 v[170:173], v182
	ds_read_b128 v[174:177], v182 offset:1024
	ds_read_b128 v[178:181], v182 offset:2048
	ds_read_b128 v[182:185], v182 offset:3072
	s_add_u32 s62, s62, 0x40000
	s_addc_u32 s63, s63, 0
	s_mov_b32 m0, s82
	ds_read_b128 v[186:189], v149 offset:32768
	ds_read_b128 v[190:193], v149 offset:33792
	ds_read_b128 v[194:197], v149 offset:34816
	ds_read_b128 v[198:201], v149 offset:35840
	ds_read_b128 v[202:205], v149 offset:36864
	ds_read_b128 v[206:209], v149 offset:37888
	ds_read_b128 v[210:213], v149 offset:38912
	ds_read_b128 v[214:217], v149 offset:39936
	global_load_lds_dwordx4 v128, s[62:63]
	s_mov_b32 m0, s83
	s_nop 0
	global_load_lds_dwordx4 v130, s[62:63]
	s_waitcnt vmcnt(8)
	s_waitcnt lgkmcnt(0)
	s_barrier
	s_waitcnt lgkmcnt(0)
	v_mfma_f32_16x16x32_bf16 v[124:127], v[138:141], v[186:189], v[124:127]
	v_mfma_f32_16x16x32_bf16 v[120:123], v[150:153], v[186:189], v[120:123]
	v_mfma_f32_16x16x32_bf16 v[108:111], v[138:141], v[194:197], v[108:111]
	v_mfma_f32_16x16x32_bf16 v[104:107], v[150:153], v[194:197], v[104:107]
	v_mfma_f32_16x16x32_bf16 v[92:95], v[138:141], v[202:205], v[92:95]
	v_mfma_f32_16x16x32_bf16 v[88:91], v[150:153], v[202:205], v[88:91]
	v_mfma_f32_16x16x32_bf16 v[76:79], v[138:141], v[210:213], v[76:79]
	v_mfma_f32_16x16x32_bf16 v[72:75], v[150:153], v[210:213], v[72:75]
	v_mfma_f32_16x16x32_bf16 v[124:127], v[142:145], v[190:193], v[124:127]
	v_mfma_f32_16x16x32_bf16 v[120:123], v[154:157], v[190:193], v[120:123]
	v_mfma_f32_16x16x32_bf16 v[108:111], v[142:145], v[198:201], v[108:111]
	v_mfma_f32_16x16x32_bf16 v[104:107], v[154:157], v[198:201], v[104:107]
	v_mfma_f32_16x16x32_bf16 v[92:95], v[142:145], v[206:209], v[92:95]
	v_mfma_f32_16x16x32_bf16 v[88:91], v[154:157], v[206:209], v[88:91]
	v_mfma_f32_16x16x32_bf16 v[76:79], v[142:145], v[214:217], v[76:79]
	v_mfma_f32_16x16x32_bf16 v[72:75], v[154:157], v[214:217], v[72:75]
	v_mfma_f32_16x16x32_bf16 v[116:119], v[170:173], v[186:189], v[116:119]
	v_mfma_f32_16x16x32_bf16 v[112:115], v[178:181], v[186:189], v[112:115]
	v_mfma_f32_16x16x32_bf16 v[100:103], v[170:173], v[194:197], v[100:103]
	v_mfma_f32_16x16x32_bf16 v[96:99], v[178:181], v[194:197], v[96:99]
	v_mfma_f32_16x16x32_bf16 v[84:87], v[170:173], v[202:205], v[84:87]
	v_mfma_f32_16x16x32_bf16 v[80:83], v[178:181], v[202:205], v[80:83]
	v_mfma_f32_16x16x32_bf16 v[68:71], v[170:173], v[210:213], v[68:71]
	v_mfma_f32_16x16x32_bf16 v[64:67], v[178:181], v[210:213], v[64:67]
	v_mfma_f32_16x16x32_bf16 v[116:119], v[174:177], v[190:193], v[116:119]
	v_mfma_f32_16x16x32_bf16 v[112:115], v[182:185], v[190:193], v[112:115]
	v_mfma_f32_16x16x32_bf16 v[100:103], v[174:177], v[198:201], v[100:103]
	v_mfma_f32_16x16x32_bf16 v[96:99], v[182:185], v[198:201], v[96:99]
	v_mfma_f32_16x16x32_bf16 v[84:87], v[174:177], v[206:209], v[84:87]
	v_mfma_f32_16x16x32_bf16 v[80:83], v[182:185], v[206:209], v[80:83]
	v_mfma_f32_16x16x32_bf16 v[68:71], v[174:177], v[214:217], v[68:71]
	v_mfma_f32_16x16x32_bf16 v[64:67], v[182:185], v[214:217], v[64:67]
	s_barrier
	s_add_i32 s46, s46, s73
	s_mov_b32 m0, s46
	ds_read_b128 v[186:189], v149 offset:49152
	ds_read_b128 v[190:193], v149 offset:50176
	ds_read_b128 v[194:197], v149 offset:51200
	ds_read_b128 v[198:201], v149 offset:52224
	ds_read_b128 v[202:205], v149 offset:53248
	ds_read_b128 v[206:209], v149 offset:54272
	ds_read_b128 v[210:213], v149 offset:55296
	ds_read_b128 v[214:217], v149 offset:56320
	s_add_u32 s98, s24, 0x80
	s_addc_u32 s99, s25, 0
	global_load_lds_dwordx4 v160, s[98:99]
	s_add_i32 m0, s46, 0x2000
	s_add_u32 s24, s24, 0x40080
	s_addc_u32 s25, s25, 0
	s_add_i32 s46, s47, s73
	global_load_lds_dwordx4 v132, s[98:99]
	s_mov_b32 m0, s46
	s_nop 0
	global_load_lds_dwordx4 v160, s[24:25]
	s_add_i32 m0, s46, 0x2000
	s_nop 0
	global_load_lds_dwordx4 v132, s[24:25]
	s_mov_b32 m0, s90
	s_nop 0
	s_add_u32 s98, s62, 0xfffc0080
	s_addc_u32 s99, s63, -1
	global_load_lds_dwordx4 v128, s[98:99]
	s_mov_b32 m0, s91
	s_nop 0
	global_load_lds_dwordx4 v130, s[98:99]
	s_waitcnt vmcnt(8)
	s_waitcnt lgkmcnt(0)
	s_barrier
	s_waitcnt lgkmcnt(0)
	v_mfma_f32_16x16x32_bf16 v[60:63], v[138:141], v[186:189], v[60:63]
	v_mfma_f32_16x16x32_bf16 v[56:59], v[150:153], v[186:189], v[56:59]
	v_mfma_f32_16x16x32_bf16 v[44:47], v[138:141], v[194:197], v[44:47]
	v_mfma_f32_16x16x32_bf16 v[40:43], v[150:153], v[194:197], v[40:43]
	v_mfma_f32_16x16x32_bf16 v[28:31], v[138:141], v[202:205], v[28:31]
	v_mfma_f32_16x16x32_bf16 v[24:27], v[150:153], v[202:205], v[24:27]
	v_mfma_f32_16x16x32_bf16 v[12:15], v[138:141], v[210:213], v[12:15]
	v_mfma_f32_16x16x32_bf16 v[8:11], v[150:153], v[210:213], v[8:11]
	v_mfma_f32_16x16x32_bf16 v[60:63], v[142:145], v[190:193], v[60:63]
	v_mfma_f32_16x16x32_bf16 v[56:59], v[154:157], v[190:193], v[56:59]
	v_mfma_f32_16x16x32_bf16 v[44:47], v[142:145], v[198:201], v[44:47]
	v_mfma_f32_16x16x32_bf16 v[40:43], v[154:157], v[198:201], v[40:43]
	v_mfma_f32_16x16x32_bf16 v[28:31], v[142:145], v[206:209], v[28:31]
	v_mfma_f32_16x16x32_bf16 v[24:27], v[154:157], v[206:209], v[24:27]
	v_mfma_f32_16x16x32_bf16 v[12:15], v[142:145], v[214:217], v[12:15]
	v_mfma_f32_16x16x32_bf16 v[8:11], v[154:157], v[214:217], v[8:11]
	v_mfma_f32_16x16x32_bf16 v[52:55], v[170:173], v[186:189], v[52:55]
	v_mfma_f32_16x16x32_bf16 v[48:51], v[178:181], v[186:189], v[48:51]
	v_mfma_f32_16x16x32_bf16 v[36:39], v[170:173], v[194:197], v[36:39]
	v_mfma_f32_16x16x32_bf16 v[32:35], v[178:181], v[194:197], v[32:35]
	v_mfma_f32_16x16x32_bf16 v[20:23], v[170:173], v[202:205], v[20:23]
	v_mfma_f32_16x16x32_bf16 v[16:19], v[178:181], v[202:205], v[16:19]
	v_mfma_f32_16x16x32_bf16 v[4:7], v[170:173], v[210:213], v[4:7]
	v_mfma_f32_16x16x32_bf16 v[0:3], v[178:181], v[210:213], v[0:3]
	v_mfma_f32_16x16x32_bf16 v[52:55], v[174:177], v[190:193], v[52:55]
	v_mfma_f32_16x16x32_bf16 v[48:51], v[182:185], v[190:193], v[48:51]
	v_mfma_f32_16x16x32_bf16 v[36:39], v[174:177], v[198:201], v[36:39]
	v_mfma_f32_16x16x32_bf16 v[32:35], v[182:185], v[198:201], v[32:35]
	v_mfma_f32_16x16x32_bf16 v[20:23], v[174:177], v[206:209], v[20:23]
	v_mfma_f32_16x16x32_bf16 v[16:19], v[182:185], v[206:209], v[16:19]
	v_mfma_f32_16x16x32_bf16 v[4:7], v[174:177], v[214:217], v[4:7]
	v_mfma_f32_16x16x32_bf16 v[0:3], v[182:185], v[214:217], v[0:3]
	s_barrier
	s_add_i32 s45, s45, 2
	s_add_u32 s60, s60, 0x100
	s_addc_u32 s61, s61, 0
	s_add_u32 s43, s43, 0x100
	s_addc_u32 s44, s44, 0
	s_cmp_gt_u32 s45, 13
	s_cbranch_scc0 .LBB0_211
	s_setprio 0
	s_and_b64 vcc, exec, s[14:15]
	s_cbranch_vccz .LBB0_214
	s_barrier

; #define PG8_STAGE(bufoff, gbase, voff) do { _Pragma("unroll") for (int _i = 0; _i < 2; ++_i) \
;         __builtin_amdgcn_global_load_lds((const unsigned*)((const char*)(gbase) + (voff)[_i]), (LAS unsigned*)(lds + (bufoff) + ldsw + _i * 8192), 16, 0, 0); } while (0)
; #define PG8_LDA(dst, b, h) do { _Pragma("unroll") for (int m = 0; m < 4; ++m) _Pragma("unroll") for (int k = 0; k < 2; ++k) dst[m][k] = *(const LAS bf16x8*)(lds + PG8_SA(b, h) + aoff + m * 2048 + k * 1024); } while (0)
; #define PG8_LDB(dst, b, h) do { _Pragma("unroll") for (int n = 0; n < 2; ++n) _Pragma("unroll") for (int k = 0; k < 2; ++k) dst[n][k] = *(const LAS bf16x8*)(lds + PG8_SB(b, h) + boff + n * 2048 + k * 1024); } while (0)
; #define PG8_SCHED __builtin_amdgcn_sched_barrier(0)
; template <class Epi, class Sched, bool ALIGN_EPI = true, bool SP2 = true>
; __device__ __forceinline__ void gemm_phase(LAS unsigned char* lds, const Gemm g, const Sched& S, const Epi& E) {
;     ...
;         const bool has_next = S.next(ui + 1, nxt);
;         const char* nA = has_next ? (const char*)g.A + (size_t)nxt.pm * tstep : cA; const char* nB = has_next ? (const char*)g.Bt + (size_t)nxt.pn * tstep : cB;
;         for (int t = 0; t < nt; t += 2) {
;             const bool last = (t == nt - 2);
;             const char* a1 = cA + (size_t)(t + 1) * kstep;
;             const char* a2 = last ? nA : cA + (size_t)(t + 2) * kstep; const char* b2 = last ? nB : cB + (size_t)(t + 2) * kstep;
;             const char* a3 = a2 + kstep; const char* b3 = b2 + kstep;
;             if constexpr (SP2) {
;             PG8_LDB(B0, 0, 0); PG8_LDB(B1, 0, 1); PG8_SCHED; PG8_LDA(At, 0, 0); PG8_STAGE(PG8_SA(1, 1), a1 + hstep, voffA);
;     ...
; #pragma unroll
;         for (int a = 0; a < 2; ++a)
; #pragma unroll
;             for (int b = 0; b < 2; ++b)
; #pragma unroll
;                 for (int m = 0; m < 4; ++m)
; #pragma unroll
;                     for (int n = 0; n < 2; ++n) acc[a][b][m][n] = (f32x4){0.f, 0.f, 0.f, 0.f};
.LBB0_236:
	s_ashr_i32 s19, s18, 31
	s_lshl_b64 s[2:3], s[18:19], 19
	s_add_u32 s30, s64, s2
	s_addc_u32 s31, s65, s3
	s_and_b64 s[2:3], s[4:5], exec
	s_cselect_b32 s2, s31, s25
	s_cselect_b32 s3, s30, s24
	s_ashr_i32 s17, s16, 31
	s_lshl_b64 s[52:53], s[16:17], 19
	s_add_u32 s52, s41, s52
	s_addc_u32 s53, s42, s53
	s_and_b64 s[54:55], s[4:5], exec
	s_cselect_b32 s17, s53, s61
	s_cselect_b32 s19, s52, s60
	s_add_u32 s54, s24, 0x40080
	s_addc_u32 s55, s25, 0
	s_add_u32 s90, s60, 0x100
	v_mov_b32_e32 v0, 0
	s_addc_u32 s91, s61, 0
	s_mov_b32 s92, -2
	v_mov_b32_e32 v1, v0
	v_mov_b32_e32 v2, v0
	v_mov_b32_e32 v3, v0
	v_mov_b32_e32 v4, v0
	v_mov_b32_e32 v5, v0
	v_mov_b32_e32 v6, v0
	v_mov_b32_e32 v7, v0
	v_mov_b32_e32 v16, v0
	v_mov_b32_e32 v17, v0
	v_mov_b32_e32 v18, v0
	v_mov_b32_e32 v19, v0
	v_mov_b32_e32 v20, v0
	v_mov_b32_e32 v21, v0
	v_mov_b32_e32 v22, v0
	v_mov_b32_e32 v23, v0
	v_mov_b32_e32 v32, v0
	v_mov_b32_e32 v33, v0
	v_mov_b32_e32 v34, v0
	v_mov_b32_e32 v35, v0
	s_waitcnt vmcnt(0)
	v_mov_b32_e32 v36, v0
	v_mov_b32_e32 v37, v0
	v_mov_b32_e32 v38, v0
	v_mov_b32_e32 v39, v0
	s_waitcnt vmcnt(0)
	v_mov_b32_e32 v48, v0
	v_mov_b32_e32 v49, v0
	v_mov_b32_e32 v50, v0
	v_mov_b32_e32 v51, v0
	v_mov_b32_e32 v52, v0
	v_mov_b32_e32 v53, v0
	v_mov_b32_e32 v54, v0
	v_mov_b32_e32 v55, v0
	v_mov_b32_e32 v8, v0
	v_mov_b32_e32 v9, v0
	v_mov_b32_e32 v10, v0
	v_mov_b32_e32 v11, v0
	v_mov_b32_e32 v12, v0
	v_mov_b32_e32 v13, v0
	v_mov_b32_e32 v14, v0
	v_mov_b32_e32 v15, v0
	v_mov_b32_e32 v24, v0
	v_mov_b32_e32 v25, v0
	v_mov_b32_e32 v26, v0
	v_mov_b32_e32 v27, v0
	v_mov_b32_e32 v28, v0
	v_mov_b32_e32 v29, v0
	v_mov_b32_e32 v30, v0
	v_mov_b32_e32 v31, v0
	v_mov_b32_e32 v40, v0
	v_mov_b32_e32 v41, v0
	v_mov_b32_e32 v42, v0
	v_mov_b32_e32 v43, v0
	v_mov_b32_e32 v44, v0
	v_mov_b32_e32 v45, v0
	v_mov_b32_e32 v46, v0
	v_mov_b32_e32 v47, v0
	v_mov_b32_e32 v56, v0
	v_mov_b32_e32 v57, v0
	v_mov_b32_e32 v58, v0
	v_mov_b32_e32 v59, v0
	v_mov_b32_e32 v60, v0
	v_mov_b32_e32 v61, v0
	v_mov_b32_e32 v62, v0
	v_mov_b32_e32 v63, v0
	v_mov_b32_e32 v64, v0
	v_mov_b32_e32 v65, v0
	v_mov_b32_e32 v66, v0
	v_mov_b32_e32 v67, v0
	v_mov_b32_e32 v68, v0
	v_mov_b32_e32 v69, v0
	v_mov_b32_e32 v70, v0
	v_mov_b32_e32 v71, v0
	v_mov_b32_e32 v80, v0
	v_mov_b32_e32 v81, v0
	v_mov_b32_e32 v82, v0
	v_mov_b32_e32 v83, v0
	v_mov_b32_e32 v84, v0
	v_mov_b32_e32 v85, v0
	v_mov_b32_e32 v86, v0
	v_mov_b32_e32 v87, v0
	v_mov_b32_e32 v96, v0
	v_mov_b32_e32 v97, v0
	v_mov_b32_e32 v98, v0
	v_mov_b32_e32 v99, v0
	v_mov_b32_e32 v100, v0
	v_mov_b32_e32 v101, v0
	v_mov_b32_e32 v102, v0
	v_mov_b32_e32 v103, v0
	v_mov_b32_e32 v112, v0
	v_mov_b32_e32 v113, v0
	v_mov_b32_e32 v114, v0
	v_mov_b32_e32 v115, v0
	v_mov_b32_e32 v116, v0
	v_mov_b32_e32 v117, v0
	v_mov_b32_e32 v118, v0
	v_mov_b32_e32 v119, v0
	v_mov_b32_e32 v72, v0
	v_mov_b32_e32 v73, v0
	v_mov_b32_e32 v74, v0
	v_mov_b32_e32 v75, v0
	v_mov_b32_e32 v76, v0
	v_mov_b32_e32 v77, v0
	v_mov_b32_e32 v78, v0
	v_mov_b32_e32 v79, v0
	v_mov_b32_e32 v88, v0
	v_mov_b32_e32 v89, v0
	v_mov_b32_e32 v90, v0
	v_mov_b32_e32 v91, v0
	v_mov_b32_e32 v92, v0
	v_mov_b32_e32 v93, v0
	v_mov_b32_e32 v94, v0
	v_mov_b32_e32 v95, v0
	v_mov_b32_e32 v104, v0
	v_mov_b32_e32 v105, v0
	v_mov_b32_e32 v106, v0
	v_mov_b32_e32 v107, v0
	v_mov_b32_e32 v108, v0
	v_mov_b32_e32 v109, v0
	v_mov_b32_e32 v110, v0
	v_mov_b32_e32 v111, v0
	v_mov_b32_e32 v120, v0
	v_mov_b32_e32 v121, v0
	v_mov_b32_e32 v122, v0
	v_mov_b32_e32 v123, v0
	v_mov_b32_e32 v124, v0
	v_mov_b32_e32 v125, v0
	v_mov_b32_e32 v126, v0
	v_mov_b32_e32 v127, v0
	v_lshrrev_b32_e32 v226, 8, v238
	v_cmp_ne_u32_e64 s[98:99], 0, v226
	s_nop 3
	s_and_b64 s[98:99], s[98:99], exec
	s_cbranch_scc0 .Lprio_skip_237
	s_setprio 1
.Lprio_skip_237:
.LBB0_237:
	s_add_u32 s24, s54, 0xfffc0080
	s_addc_u32 s25, s55, -1
	s_add_i32 s46, 0, 0x10000
	s_cmp_eq_u32 s92, 12
	s_cselect_b32 s61, s2, s25
	s_cselect_b32 s60, s3, s24
	v_add_u32_e32 v142, s46, v145
	s_cselect_b32 s25, s17, s91
	s_cselect_b32 s24, s19, s90
	s_add_i32 s47, 0, 0x14000
	ds_read_b128 v[138:141], v142
	ds_read_b128 v[148:151], v142 offset:1024
	ds_read_b128 v[152:155], v142 offset:2048
	ds_read_b128 v[156:159], v142 offset:3072
	v_add_u32_e32 v142, s47, v145
	ds_read_b128 v[170:173], v142
	ds_read_b128 v[174:177], v142 offset:1024
	ds_read_b128 v[178:181], v142 offset:2048
	ds_read_b128 v[182:185], v142 offset:3072
	s_add_i32 m0, s44, 0xc000
	ds_read_b128 v[186:189], v147
	ds_read_b128 v[190:193], v147 offset:1024
	ds_read_b128 v[194:197], v147 offset:2048
	ds_read_b128 v[198:201], v147 offset:3072
	ds_read_b128 v[202:205], v147 offset:4096
	ds_read_b128 v[206:209], v147 offset:5120
	ds_read_b128 v[210:213], v147 offset:6144
	ds_read_b128 v[214:217], v147 offset:7168
	global_load_lds_dwordx4 v134, s[54:55]
	s_add_i32 m0, s44, 0xe000
	s_nop 0
	global_load_lds_dwordx4 v136, s[54:55]
	s_waitcnt vmcnt(8)
	s_waitcnt lgkmcnt(0)
	s_barrier
; #define PG8_STAGE(bufoff, gbase, voff) do { _Pragma("unroll") for (int _i = 0; _i < 2; ++_i) \
;         __builtin_amdgcn_global_load_lds((const unsigned*)((const char*)(gbase) + (voff)[_i]), (LAS unsigned*)(lds + (bufoff) + ldsw + _i * 8192), 16, 0, 0); } while (0)
; #define PG8_LDA(dst, b, h) do { _Pragma("unroll") for (int m = 0; m < 4; ++m) _Pragma("unroll") for (int k = 0; k < 2; ++k) dst[m][k] = *(const LAS bf16x8*)(lds + PG8_SA(b, h) + aoff + m * 2048 + k * 1024); } while (0)
; #define PG8_MMA(ai, bj, At, Bt) do { __builtin_amdgcn_s_setprio(1); _Pragma("unroll") for (int m = 0; m < 4; ++m) _Pragma("unroll") for (int n = 0; n < 2; ++n) _Pragma("unroll") for (int k = 0; k < 2; ++k) \
;         acc[ai][bj][m][n] = __builtin_amdgcn_mfma_f32_16x16x32_bf16(Bt[n][k], At[m][k], acc[ai][bj][m][n], 0, 0, 0); __builtin_amdgcn_s_setprio(0); } while (0)
; #define PG8_WAIT_V(n) asm volatile("s_waitcnt vmcnt(" #n ")" ::: "memory")
; #define PG8_WAIT_L(n) asm volatile("s_waitcnt lgkmcnt(" #n ")" ::: "memory")
; #define PG8_BAR __builtin_amdgcn_s_barrier()
; #define PG8_SCHED __builtin_amdgcn_sched_barrier(0)
; template <class Epi, class Sched, bool ALIGN_EPI = true, bool SP2 = true>
; __device__ __forceinline__ void gemm_phase(LAS unsigned char* lds, const Gemm g, const Sched& S, const Epi& E) {
;     ...
;             PG8_WAIT_V(8); PG8_WAIT_L(0); PG8_BAR; PG8_MMA(0, 0, At, B0); PG8_MMA(0, 1, At, B1); PG8_BAR; PG8_SCHED;
;             PG8_LDA(At, 0, 1); PG8_STAGE(PG8_SB(0, 0), b2, voffB); PG8_STAGE(PG8_SB(0, 1), b2 + hstep, voffB); PG8_STAGE(PG8_SA(0, 0), a2, voffA);
;             PG8_WAIT_V(8); PG8_WAIT_L(0); PG8_BAR; PG8_MMA(1, 0, At, B0); PG8_MMA(1, 1, At, B1); PG8_BAR; PG8_SCHED;
	s_waitcnt lgkmcnt(0)
	v_mfma_f32_16x16x32_bf16 v[124:127], v[138:141], v[186:189], v[124:127]
	v_mfma_f32_16x16x32_bf16 v[120:123], v[152:155], v[186:189], v[120:123]
	v_mfma_f32_16x16x32_bf16 v[108:111], v[138:141], v[194:197], v[108:111]
	v_mfma_f32_16x16x32_bf16 v[104:107], v[152:155], v[194:197], v[104:107]
	v_mfma_f32_16x16x32_bf16 v[92:95], v[138:141], v[202:205], v[92:95]
	v_mfma_f32_16x16x32_bf16 v[88:91], v[152:155], v[202:205], v[88:91]
	v_mfma_f32_16x16x32_bf16 v[76:79], v[138:141], v[210:213], v[76:79]
	v_mfma_f32_16x16x32_bf16 v[72:75], v[152:155], v[210:213], v[72:75]
	v_mfma_f32_16x16x32_bf16 v[124:127], v[148:151], v[190:193], v[124:127]
	v_mfma_f32_16x16x32_bf16 v[120:123], v[156:159], v[190:193], v[120:123]
	v_mfma_f32_16x16x32_bf16 v[108:111], v[148:151], v[198:201], v[108:111]
	v_mfma_f32_16x16x32_bf16 v[104:107], v[156:159], v[198:201], v[104:107]
	v_mfma_f32_16x16x32_bf16 v[92:95], v[148:151], v[206:209], v[92:95]
	v_mfma_f32_16x16x32_bf16 v[88:91], v[156:159], v[206:209], v[88:91]
	v_mfma_f32_16x16x32_bf16 v[76:79], v[148:151], v[214:217], v[76:79]
	v_mfma_f32_16x16x32_bf16 v[72:75], v[156:159], v[214:217], v[72:75]
	v_mfma_f32_16x16x32_bf16 v[116:119], v[170:173], v[186:189], v[116:119]
	v_mfma_f32_16x16x32_bf16 v[112:115], v[178:181], v[186:189], v[112:115]
	v_mfma_f32_16x16x32_bf16 v[100:103], v[170:173], v[194:197], v[100:103]
	v_mfma_f32_16x16x32_bf16 v[96:99], v[178:181], v[194:197], v[96:99]
	v_mfma_f32_16x16x32_bf16 v[84:87], v[170:173], v[202:205], v[84:87]
	v_mfma_f32_16x16x32_bf16 v[80:83], v[178:181], v[202:205], v[80:83]
	v_mfma_f32_16x16x32_bf16 v[68:71], v[170:173], v[210:213], v[68:71]
	v_mfma_f32_16x16x32_bf16 v[64:67], v[178:181], v[210:213], v[64:67]
	v_mfma_f32_16x16x32_bf16 v[116:119], v[174:177], v[190:193], v[116:119]
	v_mfma_f32_16x16x32_bf16 v[112:115], v[182:185], v[190:193], v[112:115]
	v_mfma_f32_16x16x32_bf16 v[100:103], v[174:177], v[198:201], v[100:103]
	v_mfma_f32_16x16x32_bf16 v[96:99], v[182:185], v[198:201], v[96:99]
	v_mfma_f32_16x16x32_bf16 v[84:87], v[174:177], v[206:209], v[84:87]
	v_mfma_f32_16x16x32_bf16 v[80:83], v[182:185], v[206:209], v[80:83]
	v_mfma_f32_16x16x32_bf16 v[68:71], v[174:177], v[214:217], v[68:71]
	v_mfma_f32_16x16x32_bf16 v[64:67], v[182:185], v[214:217], v[64:67]
	s_barrier
	s_add_i32 s46, s46, s43
	s_mov_b32 m0, s46
	ds_read_b128 v[186:189], v147 offset:16384
	ds_read_b128 v[190:193], v147 offset:17408
	ds_read_b128 v[194:197], v147 offset:18432
	ds_read_b128 v[198:201], v147 offset:19456
	ds_read_b128 v[202:205], v147 offset:20480
	ds_read_b128 v[206:209], v147 offset:21504
	ds_read_b128 v[210:213], v147 offset:22528
	ds_read_b128 v[214:217], v147 offset:23552
	global_load_lds_dwordx4 v160, s[24:25]
	s_add_i32 m0, s46, 0x2000
	s_add_u32 s94, s24, 0x40000
	s_addc_u32 s95, s25, 0
	s_add_i32 s46, s47, s43
	global_load_lds_dwordx4 v128, s[24:25]
	s_mov_b32 m0, s46
	s_nop 0
	global_load_lds_dwordx4 v160, s[94:95]
	s_add_i32 m0, s46, 0x2000
	s_nop 0
	global_load_lds_dwordx4 v128, s[94:95]
	s_mov_b32 m0, s44
	s_nop 0
	global_load_lds_dwordx4 v132, s[60:61]
	s_mov_b32 m0, s45
	s_nop 0
	global_load_lds_dwordx4 v130, s[60:61]
	s_waitcnt vmcnt(8)
	s_waitcnt lgkmcnt(0)
	s_barrier
	s_waitcnt lgkmcnt(0)
	v_mfma_f32_16x16x32_bf16 v[60:63], v[138:141], v[186:189], v[60:63]
	v_mfma_f32_16x16x32_bf16 v[56:59], v[152:155], v[186:189], v[56:59]
	v_mfma_f32_16x16x32_bf16 v[44:47], v[138:141], v[194:197], v[44:47]
	v_mfma_f32_16x16x32_bf16 v[40:43], v[152:155], v[194:197], v[40:43]
	v_mfma_f32_16x16x32_bf16 v[28:31], v[138:141], v[202:205], v[28:31]
	v_mfma_f32_16x16x32_bf16 v[24:27], v[152:155], v[202:205], v[24:27]
	v_mfma_f32_16x16x32_bf16 v[12:15], v[138:141], v[210:213], v[12:15]
	v_mfma_f32_16x16x32_bf16 v[8:11], v[152:155], v[210:213], v[8:11]
	v_mfma_f32_16x16x32_bf16 v[60:63], v[148:151], v[190:193], v[60:63]
	v_mfma_f32_16x16x32_bf16 v[56:59], v[156:159], v[190:193], v[56:59]
	v_mfma_f32_16x16x32_bf16 v[44:47], v[148:151], v[198:201], v[44:47]
	v_mfma_f32_16x16x32_bf16 v[40:43], v[156:159], v[198:201], v[40:43]
	v_mfma_f32_16x16x32_bf16 v[28:31], v[148:151], v[206:209], v[28:31]
	v_mfma_f32_16x16x32_bf16 v[24:27], v[156:159], v[206:209], v[24:27]
	v_mfma_f32_16x16x32_bf16 v[12:15], v[148:151], v[214:217], v[12:15]
	v_mfma_f32_16x16x32_bf16 v[8:11], v[156:159], v[214:217], v[8:11]
	v_mfma_f32_16x16x32_bf16 v[52:55], v[170:173], v[186:189], v[52:55]
	v_mfma_f32_16x16x32_bf16 v[48:51], v[178:181], v[186:189], v[48:51]
	v_mfma_f32_16x16x32_bf16 v[36:39], v[170:173], v[194:197], v[36:39]
	v_mfma_f32_16x16x32_bf16 v[32:35], v[178:181], v[194:197], v[32:35]
	v_mfma_f32_16x16x32_bf16 v[20:23], v[170:173], v[202:205], v[20:23]
	v_mfma_f32_16x16x32_bf16 v[16:19], v[178:181], v[202:205], v[16:19]
	v_mfma_f32_16x16x32_bf16 v[4:7], v[170:173], v[210:213], v[4:7]
	v_mfma_f32_16x16x32_bf16 v[0:3], v[178:181], v[210:213], v[0:3]
	v_mfma_f32_16x16x32_bf16 v[52:55], v[174:177], v[190:193], v[52:55]
	v_mfma_f32_16x16x32_bf16 v[48:51], v[182:185], v[190:193], v[48:51]
	v_mfma_f32_16x16x32_bf16 v[36:39], v[174:177], v[198:201], v[36:39]
	v_mfma_f32_16x16x32_bf16 v[32:35], v[182:185], v[198:201], v[32:35]
	v_mfma_f32_16x16x32_bf16 v[20:23], v[174:177], v[206:209], v[20:23]
	v_mfma_f32_16x16x32_bf16 v[16:19], v[182:185], v[206:209], v[16:19]
	v_mfma_f32_16x16x32_bf16 v[4:7], v[174:177], v[214:217], v[4:7]
	v_mfma_f32_16x16x32_bf16 v[0:3], v[182:185], v[214:217], v[0:3]
	s_barrier
; #define PG8_STAGE(bufoff, gbase, voff) do { _Pragma("unroll") for (int _i = 0; _i < 2; ++_i) \
;         __builtin_amdgcn_global_load_lds((const unsigned*)((const char*)(gbase) + (voff)[_i]), (LAS unsigned*)(lds + (bufoff) + ldsw + _i * 8192), 16, 0, 0); } while (0)
; #define PG8_LDA(dst, b, h) do { _Pragma("unroll") for (int m = 0; m < 4; ++m) _Pragma("unroll") for (int k = 0; k < 2; ++k) dst[m][k] = *(const LAS bf16x8*)(lds + PG8_SA(b, h) + aoff + m * 2048 + k * 1024); } while (0)
; #define PG8_LDB(dst, b, h) do { _Pragma("unroll") for (int n = 0; n < 2; ++n) _Pragma("unroll") for (int k = 0; k < 2; ++k) dst[n][k] = *(const LAS bf16x8*)(lds + PG8_SB(b, h) + boff + n * 2048 + k * 1024); } while (0)
; #define PG8_MMA(ai, bj, At, Bt) do { __builtin_amdgcn_s_setprio(1); _Pragma("unroll") for (int m = 0; m < 4; ++m) _Pragma("unroll") for (int n = 0; n < 2; ++n) _Pragma("unroll") for (int k = 0; k < 2; ++k) \
;         acc[ai][bj][m][n] = __builtin_amdgcn_mfma_f32_16x16x32_bf16(Bt[n][k], At[m][k], acc[ai][bj][m][n], 0, 0, 0); __builtin_amdgcn_s_setprio(0); } while (0)
; #define PG8_WAIT_V(n) asm volatile("s_waitcnt vmcnt(" #n ")" ::: "memory")
; #define PG8_WAIT_L(n) asm volatile("s_waitcnt lgkmcnt(" #n ")" ::: "memory")
; #define PG8_BAR __builtin_amdgcn_s_barrier()
; #define PG8_SCHED __builtin_amdgcn_sched_barrier(0)
; template <class Epi, class Sched, bool ALIGN_EPI = true, bool SP2 = true>
; __device__ __forceinline__ void gemm_phase(LAS unsigned char* lds, const Gemm g, const Sched& S, const Epi& E) {
;     ...
;             PG8_LDB(B0, 1, 0); PG8_LDB(B1, 1, 1); PG8_SCHED; PG8_LDA(At, 1, 0); PG8_STAGE(PG8_SA(0, 1), a2 + hstep, voffA);
;             PG8_WAIT_V(8); PG8_WAIT_L(0); PG8_BAR; PG8_MMA(0, 0, At, B0); PG8_MMA(0, 1, At, B1); PG8_BAR; PG8_SCHED;
;             PG8_LDA(At, 1, 1); PG8_STAGE(PG8_SB(1, 0), b3, voffB); PG8_STAGE(PG8_SB(1, 1), b3 + hstep, voffB); PG8_STAGE(PG8_SA(1, 0), a3, voffA);
;             PG8_WAIT_V(8); PG8_WAIT_L(0); PG8_BAR; PG8_MMA(1, 0, At, B0); PG8_MMA(1, 1, At, B1); PG8_BAR; PG8_SCHED;
	s_add_i32 s46, 0, 0x18000
	s_add_i32 s47, 0, 0x1c000
	v_add_u32_e32 v156, s46, v145
	v_add_u32_e32 v182, s47, v145
	ds_read_b128 v[138:141], v156
	ds_read_b128 v[148:151], v156 offset:1024
	ds_read_b128 v[152:155], v156 offset:2048
	ds_read_b128 v[156:159], v156 offset:3072
	ds_read_b128 v[170:173], v182
	ds_read_b128 v[174:177], v182 offset:1024
	ds_read_b128 v[178:181], v182 offset:2048
	ds_read_b128 v[182:185], v182 offset:3072
	s_add_u32 s60, s60, 0x40000
	s_addc_u32 s61, s61, 0
	s_mov_b32 m0, s62
	ds_read_b128 v[186:189], v147 offset:32768
	ds_read_b128 v[190:193], v147 offset:33792
	ds_read_b128 v[194:197], v147 offset:34816
	ds_read_b128 v[198:201], v147 offset:35840
	ds_read_b128 v[202:205], v147 offset:36864
	ds_read_b128 v[206:209], v147 offset:37888
	ds_read_b128 v[210:213], v147 offset:38912
	ds_read_b128 v[214:217], v147 offset:39936
	global_load_lds_dwordx4 v132, s[60:61]
	s_mov_b32 m0, s63
	s_nop 0
	global_load_lds_dwordx4 v130, s[60:61]
	s_waitcnt vmcnt(8)
	s_waitcnt lgkmcnt(0)
	s_barrier
	s_waitcnt lgkmcnt(0)
	v_mfma_f32_16x16x32_bf16 v[124:127], v[138:141], v[186:189], v[124:127]
	v_mfma_f32_16x16x32_bf16 v[120:123], v[152:155], v[186:189], v[120:123]
	v_mfma_f32_16x16x32_bf16 v[108:111], v[138:141], v[194:197], v[108:111]
	v_mfma_f32_16x16x32_bf16 v[104:107], v[152:155], v[194:197], v[104:107]
	v_mfma_f32_16x16x32_bf16 v[92:95], v[138:141], v[202:205], v[92:95]
	v_mfma_f32_16x16x32_bf16 v[88:91], v[152:155], v[202:205], v[88:91]
	v_mfma_f32_16x16x32_bf16 v[76:79], v[138:141], v[210:213], v[76:79]
	v_mfma_f32_16x16x32_bf16 v[72:75], v[152:155], v[210:213], v[72:75]
	v_mfma_f32_16x16x32_bf16 v[124:127], v[148:151], v[190:193], v[124:127]
	v_mfma_f32_16x16x32_bf16 v[120:123], v[156:159], v[190:193], v[120:123]
	v_mfma_f32_16x16x32_bf16 v[108:111], v[148:151], v[198:201], v[108:111]
	v_mfma_f32_16x16x32_bf16 v[104:107], v[156:159], v[198:201], v[104:107]
	v_mfma_f32_16x16x32_bf16 v[92:95], v[148:151], v[206:209], v[92:95]
	v_mfma_f32_16x16x32_bf16 v[88:91], v[156:159], v[206:209], v[88:91]
	v_mfma_f32_16x16x32_bf16 v[76:79], v[148:151], v[214:217], v[76:79]
	v_mfma_f32_16x16x32_bf16 v[72:75], v[156:159], v[214:217], v[72:75]
	v_mfma_f32_16x16x32_bf16 v[116:119], v[170:173], v[186:189], v[116:119]
	v_mfma_f32_16x16x32_bf16 v[112:115], v[178:181], v[186:189], v[112:115]
	v_mfma_f32_16x16x32_bf16 v[100:103], v[170:173], v[194:197], v[100:103]
	v_mfma_f32_16x16x32_bf16 v[96:99], v[178:181], v[194:197], v[96:99]
	v_mfma_f32_16x16x32_bf16 v[84:87], v[170:173], v[202:205], v[84:87]
	v_mfma_f32_16x16x32_bf16 v[80:83], v[178:181], v[202:205], v[80:83]
	v_mfma_f32_16x16x32_bf16 v[68:71], v[170:173], v[210:213], v[68:71]
	v_mfma_f32_16x16x32_bf16 v[64:67], v[178:181], v[210:213], v[64:67]
	v_mfma_f32_16x16x32_bf16 v[116:119], v[174:177], v[190:193], v[116:119]
	v_mfma_f32_16x16x32_bf16 v[112:115], v[182:185], v[190:193], v[112:115]
	v_mfma_f32_16x16x32_bf16 v[100:103], v[174:177], v[198:201], v[100:103]
	v_mfma_f32_16x16x32_bf16 v[96:99], v[182:185], v[198:201], v[96:99]
	v_mfma_f32_16x16x32_bf16 v[84:87], v[174:177], v[206:209], v[84:87]
	v_mfma_f32_16x16x32_bf16 v[80:83], v[182:185], v[206:209], v[80:83]
	v_mfma_f32_16x16x32_bf16 v[68:71], v[174:177], v[214:217], v[68:71]
	v_mfma_f32_16x16x32_bf16 v[64:67], v[182:185], v[214:217], v[64:67]
	s_barrier
	s_add_i32 s46, s46, s43
	s_mov_b32 m0, s46
	ds_read_b128 v[186:189], v147 offset:49152
	ds_read_b128 v[190:193], v147 offset:50176
	ds_read_b128 v[194:197], v147 offset:51200
	ds_read_b128 v[198:201], v147 offset:52224
	ds_read_b128 v[202:205], v147 offset:53248
	ds_read_b128 v[206:209], v147 offset:54272
	ds_read_b128 v[210:213], v147 offset:55296
	ds_read_b128 v[214:217], v147 offset:56320
	s_add_u32 s98, s24, 0x80
	s_addc_u32 s99, s25, 0
	global_load_lds_dwordx4 v160, s[98:99]
	s_add_i32 m0, s46, 0x2000
	s_add_u32 s24, s24, 0x40080
	s_addc_u32 s25, s25, 0
	s_add_i32 s46, s47, s43
	global_load_lds_dwordx4 v128, s[98:99]
	s_mov_b32 m0, s46
	s_nop 0
	global_load_lds_dwordx4 v160, s[24:25]
	s_add_i32 m0, s46, 0x2000
	s_nop 0
	global_load_lds_dwordx4 v128, s[24:25]
	s_mov_b32 m0, s67
	s_nop 0
	s_add_u32 s98, s60, 0xfffc0080
	s_addc_u32 s99, s61, -1
	global_load_lds_dwordx4 v132, s[98:99]
	s_mov_b32 m0, s72
	s_nop 0
	global_load_lds_dwordx4 v130, s[98:99]
	s_waitcnt vmcnt(8)
	s_waitcnt lgkmcnt(0)
	s_barrier
	s_waitcnt lgkmcnt(0)
	v_mfma_f32_16x16x32_bf16 v[60:63], v[138:141], v[186:189], v[60:63]
	v_mfma_f32_16x16x32_bf16 v[56:59], v[152:155], v[186:189], v[56:59]
	v_mfma_f32_16x16x32_bf16 v[44:47], v[138:141], v[194:197], v[44:47]
	v_mfma_f32_16x16x32_bf16 v[40:43], v[152:155], v[194:197], v[40:43]
	v_mfma_f32_16x16x32_bf16 v[28:31], v[138:141], v[202:205], v[28:31]
	v_mfma_f32_16x16x32_bf16 v[24:27], v[152:155], v[202:205], v[24:27]
	v_mfma_f32_16x16x32_bf16 v[12:15], v[138:141], v[210:213], v[12:15]
	v_mfma_f32_16x16x32_bf16 v[8:11], v[152:155], v[210:213], v[8:11]
	v_mfma_f32_16x16x32_bf16 v[60:63], v[148:151], v[190:193], v[60:63]
	v_mfma_f32_16x16x32_bf16 v[56:59], v[156:159], v[190:193], v[56:59]
	v_mfma_f32_16x16x32_bf16 v[44:47], v[148:151], v[198:201], v[44:47]
	v_mfma_f32_16x16x32_bf16 v[40:43], v[156:159], v[198:201], v[40:43]
	v_mfma_f32_16x16x32_bf16 v[28:31], v[148:151], v[206:209], v[28:31]
	v_mfma_f32_16x16x32_bf16 v[24:27], v[156:159], v[206:209], v[24:27]
	v_mfma_f32_16x16x32_bf16 v[12:15], v[148:151], v[214:217], v[12:15]
	v_mfma_f32_16x16x32_bf16 v[8:11], v[156:159], v[214:217], v[8:11]
	v_mfma_f32_16x16x32_bf16 v[52:55], v[170:173], v[186:189], v[52:55]
	v_mfma_f32_16x16x32_bf16 v[48:51], v[178:181], v[186:189], v[48:51]
	v_mfma_f32_16x16x32_bf16 v[36:39], v[170:173], v[194:197], v[36:39]
	v_mfma_f32_16x16x32_bf16 v[32:35], v[178:181], v[194:197], v[32:35]
	v_mfma_f32_16x16x32_bf16 v[20:23], v[170:173], v[202:205], v[20:23]
	v_mfma_f32_16x16x32_bf16 v[16:19], v[178:181], v[202:205], v[16:19]
	v_mfma_f32_16x16x32_bf16 v[4:7], v[170:173], v[210:213], v[4:7]
	v_mfma_f32_16x16x32_bf16 v[0:3], v[178:181], v[210:213], v[0:3]
	v_mfma_f32_16x16x32_bf16 v[52:55], v[174:177], v[190:193], v[52:55]
	v_mfma_f32_16x16x32_bf16 v[48:51], v[182:185], v[190:193], v[48:51]
	v_mfma_f32_16x16x32_bf16 v[36:39], v[174:177], v[198:201], v[36:39]
	v_mfma_f32_16x16x32_bf16 v[32:35], v[182:185], v[198:201], v[32:35]
	v_mfma_f32_16x16x32_bf16 v[20:23], v[174:177], v[206:209], v[20:23]
	v_mfma_f32_16x16x32_bf16 v[16:19], v[182:185], v[206:209], v[16:19]
	v_mfma_f32_16x16x32_bf16 v[4:7], v[174:177], v[214:217], v[4:7]
	v_mfma_f32_16x16x32_bf16 v[0:3], v[182:185], v[214:217], v[0:3]
	s_barrier
	s_add_i32 s92, s92, 2
	s_add_u32 s54, s54, 0x100
	s_addc_u32 s55, s55, 0
	s_add_u32 s90, s90, 0x100
	s_addc_u32 s91, s91, 0
	s_cmp_gt_u32 s92, 13
	s_cbranch_scc0 .LBB0_237
	s_setprio 0
	s_and_b64 vcc, exec, s[14:15]
	s_cbranch_vccz .LBB0_240
	s_barrier

; #define PG8_STAGE(bufoff, gbase, voff) do { _Pragma("unroll") for (int _i = 0; _i < 2; ++_i) \
;         __builtin_amdgcn_global_load_lds((const unsigned*)((const char*)(gbase) + (voff)[_i]), (LAS unsigned*)(lds + (bufoff) + ldsw + _i * 8192), 16, 0, 0); } while (0)
; #define PG8_LDA(dst, b, h) do { _Pragma("unroll") for (int m = 0; m < 4; ++m) _Pragma("unroll") for (int k = 0; k < 2; ++k) dst[m][k] = *(const LAS bf16x8*)(lds + PG8_SA(b, h) + aoff + m * 2048 + k * 1024); } while (0)
; #define PG8_LDB(dst, b, h) do { _Pragma("unroll") for (int n = 0; n < 2; ++n) _Pragma("unroll") for (int k = 0; k < 2; ++k) dst[n][k] = *(const LAS bf16x8*)(lds + PG8_SB(b, h) + boff + n * 2048 + k * 1024); } while (0)
; #define PG8_SCHED __builtin_amdgcn_sched_barrier(0)
; template <class Epi, class Sched, bool ALIGN_EPI = true, bool SP2 = true>
; __device__ __forceinline__ void gemm_phase(LAS unsigned char* lds, const Gemm g, const Sched& S, const Epi& E) {
;     ...
;         const bool has_next = S.next(ui + 1, nxt);
;         const char* nA = has_next ? (const char*)g.A + (size_t)nxt.pm * tstep : cA; const char* nB = has_next ? (const char*)g.Bt + (size_t)nxt.pn * tstep : cB;
;         for (int t = 0; t < nt; t += 2) {
;             const bool last = (t == nt - 2);
;             const char* a1 = cA + (size_t)(t + 1) * kstep;
;             const char* a2 = last ? nA : cA + (size_t)(t + 2) * kstep; const char* b2 = last ? nB : cB + (size_t)(t + 2) * kstep;
;             const char* a3 = a2 + kstep; const char* b3 = b2 + kstep;
;             if constexpr (SP2) {
;             PG8_LDB(B0, 0, 0); PG8_LDB(B1, 0, 1); PG8_SCHED; PG8_LDA(At, 0, 0); PG8_STAGE(PG8_SA(1, 1), a1 + hstep, voffA);
;     ...
; #pragma unroll
;         for (int a = 0; a < 2; ++a)
; #pragma unroll
;             for (int b = 0; b < 2; ++b)
; #pragma unroll
;                 for (int m = 0; m < 4; ++m)
; #pragma unroll
;                     for (int n = 0; n < 2; ++n) acc[a][b][m][n] = (f32x4){0.f, 0.f, 0.f, 0.f};
.LBB0_353:
	s_ashr_i32 s97, s96, 31
	s_lshl_b64 s[2:3], s[96:97], 20
	s_add_u32 s54, s80, s2
	s_addc_u32 s55, s81, s3
	s_and_b64 s[2:3], s[4:5], exec
	s_cselect_b32 s2, s55, s25
	s_cselect_b32 s3, s54, s24
	s_ashr_i32 s95, s94, 31
	s_lshl_b64 s[18:19], s[94:95], 20
	s_add_u32 s52, s28, s18
	s_addc_u32 s53, s79, s19
	s_and_b64 s[18:19], s[4:5], exec
	s_cselect_b32 s7, s53, s83
	s_cselect_b32 s9, s52, s82
	s_add_u32 s62, s24, 0x80080
	s_addc_u32 s63, s25, 0
	s_add_u32 s18, s82, 0x100
	v_mov_b32_e32 v0, 0
	s_addc_u32 s19, s83, 0
	s_mov_b32 s42, -2
	v_mov_b32_e32 v1, v0
	v_mov_b32_e32 v2, v0
	v_mov_b32_e32 v3, v0
	v_mov_b32_e32 v4, v0
	v_mov_b32_e32 v5, v0
	v_mov_b32_e32 v6, v0
	v_mov_b32_e32 v7, v0
	v_mov_b32_e32 v16, v0
	v_mov_b32_e32 v17, v0
	v_mov_b32_e32 v18, v0
	v_mov_b32_e32 v19, v0
	v_mov_b32_e32 v20, v0
	v_mov_b32_e32 v21, v0
	v_mov_b32_e32 v22, v0
	v_mov_b32_e32 v23, v0
	v_mov_b32_e32 v32, v0
	v_mov_b32_e32 v33, v0
	v_mov_b32_e32 v34, v0
	v_mov_b32_e32 v35, v0
	s_waitcnt vmcnt(0)
	v_mov_b32_e32 v36, v0
	v_mov_b32_e32 v37, v0
	v_mov_b32_e32 v38, v0
	v_mov_b32_e32 v39, v0
	v_mov_b32_e32 v48, v0
	v_mov_b32_e32 v49, v0
	v_mov_b32_e32 v50, v0
	v_mov_b32_e32 v51, v0
	v_mov_b32_e32 v52, v0
	v_mov_b32_e32 v53, v0
	v_mov_b32_e32 v54, v0
	v_mov_b32_e32 v55, v0
	v_mov_b32_e32 v8, v0
	v_mov_b32_e32 v9, v0
	v_mov_b32_e32 v10, v0
	v_mov_b32_e32 v11, v0
	v_mov_b32_e32 v12, v0
	v_mov_b32_e32 v13, v0
	v_mov_b32_e32 v14, v0
	v_mov_b32_e32 v15, v0
	v_mov_b32_e32 v24, v0
	v_mov_b32_e32 v25, v0
	v_mov_b32_e32 v26, v0
	v_mov_b32_e32 v27, v0
	v_mov_b32_e32 v28, v0
	v_mov_b32_e32 v29, v0
	v_mov_b32_e32 v30, v0
	v_mov_b32_e32 v31, v0
	v_mov_b32_e32 v40, v0
	v_mov_b32_e32 v41, v0
	v_mov_b32_e32 v42, v0
	v_mov_b32_e32 v43, v0
	v_mov_b32_e32 v44, v0
	v_mov_b32_e32 v45, v0
	v_mov_b32_e32 v46, v0
	v_mov_b32_e32 v47, v0
	v_mov_b32_e32 v56, v0
	v_mov_b32_e32 v57, v0
	v_mov_b32_e32 v58, v0
	v_mov_b32_e32 v59, v0
	v_mov_b32_e32 v60, v0
	v_mov_b32_e32 v61, v0
	v_mov_b32_e32 v62, v0
	v_mov_b32_e32 v63, v0
	v_mov_b32_e32 v64, v0
	v_mov_b32_e32 v65, v0
	v_mov_b32_e32 v66, v0
	v_mov_b32_e32 v67, v0
	v_mov_b32_e32 v68, v0
	v_mov_b32_e32 v69, v0
	v_mov_b32_e32 v70, v0
	v_mov_b32_e32 v71, v0
	v_mov_b32_e32 v80, v0
	v_mov_b32_e32 v81, v0
	v_mov_b32_e32 v82, v0
	v_mov_b32_e32 v83, v0
	v_mov_b32_e32 v84, v0
	v_mov_b32_e32 v85, v0
	v_mov_b32_e32 v86, v0
	v_mov_b32_e32 v87, v0
	v_mov_b32_e32 v96, v0
	v_mov_b32_e32 v97, v0
	v_mov_b32_e32 v98, v0
	v_mov_b32_e32 v99, v0
	v_mov_b32_e32 v100, v0
	v_mov_b32_e32 v101, v0
	v_mov_b32_e32 v102, v0
	v_mov_b32_e32 v103, v0
	v_mov_b32_e32 v112, v0
	v_mov_b32_e32 v113, v0
	v_mov_b32_e32 v114, v0
	v_mov_b32_e32 v115, v0
	v_mov_b32_e32 v116, v0
	v_mov_b32_e32 v117, v0
	v_mov_b32_e32 v118, v0
	v_mov_b32_e32 v119, v0
	v_mov_b32_e32 v72, v0
	v_mov_b32_e32 v73, v0
	v_mov_b32_e32 v74, v0
	v_mov_b32_e32 v75, v0
	v_mov_b32_e32 v76, v0
	v_mov_b32_e32 v77, v0
	v_mov_b32_e32 v78, v0
	v_mov_b32_e32 v79, v0
	v_mov_b32_e32 v88, v0
	v_mov_b32_e32 v89, v0
	v_mov_b32_e32 v90, v0
	v_mov_b32_e32 v91, v0
	v_mov_b32_e32 v92, v0
	v_mov_b32_e32 v93, v0
	v_mov_b32_e32 v94, v0
	v_mov_b32_e32 v95, v0
	v_mov_b32_e32 v104, v0
	v_mov_b32_e32 v105, v0
	v_mov_b32_e32 v106, v0
	v_mov_b32_e32 v107, v0
	v_mov_b32_e32 v108, v0
	v_mov_b32_e32 v109, v0
	v_mov_b32_e32 v110, v0
	v_mov_b32_e32 v111, v0
	v_mov_b32_e32 v120, v0
	v_mov_b32_e32 v121, v0
	v_mov_b32_e32 v122, v0
	v_mov_b32_e32 v123, v0
	v_mov_b32_e32 v124, v0
	v_mov_b32_e32 v125, v0
	v_mov_b32_e32 v126, v0
	v_mov_b32_e32 v127, v0
	v_lshrrev_b32_e32 v226, 8, v238
	v_cmp_ne_u32_e64 s[98:99], 0, v226
	s_nop 3
	s_and_b64 s[98:99], s[98:99], exec
	s_cbranch_scc0 .Lprio_skip_354
	s_setprio 1
.Lprio_skip_354:
.LBB0_354:
	s_add_u32 s24, s62, 0xfff80080
	s_addc_u32 s25, s63, -1
	s_add_i32 s43, 0, 0x10000
	s_cmp_eq_u32 s42, 28
	s_cselect_b32 s83, s2, s25
	s_cselect_b32 s82, s3, s24
	s_cselect_b32 s25, s7, s19
	s_cselect_b32 s24, s9, s18
	s_add_i32 s46, 0, 0x14000
	v_add_u32_e32 v150, s43, v155
	v_add_u32_e32 v158, s46, v155
	ds_read_b128 v[138:141], v150
	ds_read_b128 v[142:145], v150 offset:1024
	ds_read_b128 v[146:149], v150 offset:2048
	ds_read_b128 v[150:153], v150 offset:3072
	ds_read_b128 v[170:173], v158
	ds_read_b128 v[174:177], v158 offset:1024
	ds_read_b128 v[178:181], v158 offset:2048
	ds_read_b128 v[182:185], v158 offset:3072
	s_add_i32 m0, s16, 0xc000
	ds_read_b128 v[186:189], v157
	ds_read_b128 v[190:193], v157 offset:1024
	ds_read_b128 v[194:197], v157 offset:2048
	ds_read_b128 v[198:201], v157 offset:3072
	ds_read_b128 v[202:205], v157 offset:4096
	ds_read_b128 v[206:209], v157 offset:5120
	ds_read_b128 v[210:213], v157 offset:6144
	ds_read_b128 v[214:217], v157 offset:7168
	global_load_lds_dwordx4 v134, s[62:63]
	s_add_i32 m0, s16, 0xe000
	s_nop 0
	global_load_lds_dwordx4 v136, s[62:63]
	s_waitcnt vmcnt(8)
	s_waitcnt lgkmcnt(0)
	s_barrier
; #define PG8_STAGE(bufoff, gbase, voff) do { _Pragma("unroll") for (int _i = 0; _i < 2; ++_i) \
;         __builtin_amdgcn_global_load_lds((const unsigned*)((const char*)(gbase) + (voff)[_i]), (LAS unsigned*)(lds + (bufoff) + ldsw + _i * 8192), 16, 0, 0); } while (0)
; #define PG8_LDA(dst, b, h) do { _Pragma("unroll") for (int m = 0; m < 4; ++m) _Pragma("unroll") for (int k = 0; k < 2; ++k) dst[m][k] = *(const LAS bf16x8*)(lds + PG8_SA(b, h) + aoff + m * 2048 + k * 1024); } while (0)
; #define PG8_MMA(ai, bj, At, Bt) do { __builtin_amdgcn_s_setprio(1); _Pragma("unroll") for (int m = 0; m < 4; ++m) _Pragma("unroll") for (int n = 0; n < 2; ++n) _Pragma("unroll") for (int k = 0; k < 2; ++k) \
;         acc[ai][bj][m][n] = __builtin_amdgcn_mfma_f32_16x16x32_bf16(Bt[n][k], At[m][k], acc[ai][bj][m][n], 0, 0, 0); __builtin_amdgcn_s_setprio(0); } while (0)
; #define PG8_WAIT_V(n) asm volatile("s_waitcnt vmcnt(" #n ")" ::: "memory")
; #define PG8_WAIT_L(n) asm volatile("s_waitcnt lgkmcnt(" #n ")" ::: "memory")
; #define PG8_BAR __builtin_amdgcn_s_barrier()
; #define PG8_SCHED __builtin_amdgcn_sched_barrier(0)
; template <class Epi, class Sched, bool ALIGN_EPI = true, bool SP2 = true>
; __device__ __forceinline__ void gemm_phase(LAS unsigned char* lds, const Gemm g, const Sched& S, const Epi& E) {
;     ...
;             PG8_WAIT_V(8); PG8_WAIT_L(0); PG8_BAR; PG8_MMA(0, 0, At, B0); PG8_MMA(0, 1, At, B1); PG8_BAR; PG8_SCHED;
;             PG8_LDA(At, 0, 1); PG8_STAGE(PG8_SB(0, 0), b2, voffB); PG8_STAGE(PG8_SB(0, 1), b2 + hstep, voffB); PG8_STAGE(PG8_SA(0, 0), a2, voffA);
;             PG8_WAIT_V(8); PG8_WAIT_L(0); PG8_BAR; PG8_MMA(1, 0, At, B0); PG8_MMA(1, 1, At, B1); PG8_BAR; PG8_SCHED;
	s_waitcnt lgkmcnt(0)
	v_mfma_f32_16x16x32_bf16 v[124:127], v[138:141], v[186:189], v[124:127]
	v_mfma_f32_16x16x32_bf16 v[120:123], v[146:149], v[186:189], v[120:123]
	v_mfma_f32_16x16x32_bf16 v[108:111], v[138:141], v[194:197], v[108:111]
	v_mfma_f32_16x16x32_bf16 v[104:107], v[146:149], v[194:197], v[104:107]
	v_mfma_f32_16x16x32_bf16 v[92:95], v[138:141], v[202:205], v[92:95]
	v_mfma_f32_16x16x32_bf16 v[88:91], v[146:149], v[202:205], v[88:91]
	v_mfma_f32_16x16x32_bf16 v[76:79], v[138:141], v[210:213], v[76:79]
	v_mfma_f32_16x16x32_bf16 v[72:75], v[146:149], v[210:213], v[72:75]
	v_mfma_f32_16x16x32_bf16 v[124:127], v[142:145], v[190:193], v[124:127]
	v_mfma_f32_16x16x32_bf16 v[120:123], v[150:153], v[190:193], v[120:123]
	v_mfma_f32_16x16x32_bf16 v[108:111], v[142:145], v[198:201], v[108:111]
	v_mfma_f32_16x16x32_bf16 v[104:107], v[150:153], v[198:201], v[104:107]
	v_mfma_f32_16x16x32_bf16 v[92:95], v[142:145], v[206:209], v[92:95]
	v_mfma_f32_16x16x32_bf16 v[88:91], v[150:153], v[206:209], v[88:91]
	v_mfma_f32_16x16x32_bf16 v[76:79], v[142:145], v[214:217], v[76:79]
	v_mfma_f32_16x16x32_bf16 v[72:75], v[150:153], v[214:217], v[72:75]
	v_mfma_f32_16x16x32_bf16 v[116:119], v[170:173], v[186:189], v[116:119]
	v_mfma_f32_16x16x32_bf16 v[112:115], v[178:181], v[186:189], v[112:115]
	v_mfma_f32_16x16x32_bf16 v[100:103], v[170:173], v[194:197], v[100:103]
	v_mfma_f32_16x16x32_bf16 v[96:99], v[178:181], v[194:197], v[96:99]
	v_mfma_f32_16x16x32_bf16 v[84:87], v[170:173], v[202:205], v[84:87]
	v_mfma_f32_16x16x32_bf16 v[80:83], v[178:181], v[202:205], v[80:83]
	v_mfma_f32_16x16x32_bf16 v[68:71], v[170:173], v[210:213], v[68:71]
	v_mfma_f32_16x16x32_bf16 v[64:67], v[178:181], v[210:213], v[64:67]
	v_mfma_f32_16x16x32_bf16 v[116:119], v[174:177], v[190:193], v[116:119]
	v_mfma_f32_16x16x32_bf16 v[112:115], v[182:185], v[190:193], v[112:115]
	v_mfma_f32_16x16x32_bf16 v[100:103], v[174:177], v[198:201], v[100:103]
	v_mfma_f32_16x16x32_bf16 v[96:99], v[182:185], v[198:201], v[96:99]
	v_mfma_f32_16x16x32_bf16 v[84:87], v[174:177], v[206:209], v[84:87]
	v_mfma_f32_16x16x32_bf16 v[80:83], v[182:185], v[206:209], v[80:83]
	v_mfma_f32_16x16x32_bf16 v[68:71], v[174:177], v[214:217], v[68:71]
	v_mfma_f32_16x16x32_bf16 v[64:67], v[182:185], v[214:217], v[64:67]
	s_barrier
	s_add_i32 s43, s43, s41
	s_mov_b32 m0, s43
	ds_read_b128 v[186:189], v157 offset:16384
	ds_read_b128 v[190:193], v157 offset:17408
	ds_read_b128 v[194:197], v157 offset:18432
	ds_read_b128 v[198:201], v157 offset:19456
	ds_read_b128 v[202:205], v157 offset:20480
	ds_read_b128 v[206:209], v157 offset:21504
	ds_read_b128 v[210:213], v157 offset:22528
	ds_read_b128 v[214:217], v157 offset:23552
	global_load_lds_dwordx4 v160, s[24:25]
	s_add_i32 m0, s43, 0x2000
	s_add_u32 s44, s24, 0x80000
	s_addc_u32 s45, s25, 0
	s_add_i32 s43, s46, s41
	global_load_lds_dwordx4 v132, s[24:25]
	s_mov_b32 m0, s43
	s_nop 0
	global_load_lds_dwordx4 v160, s[44:45]
	s_add_i32 m0, s43, 0x2000
	s_nop 0
	global_load_lds_dwordx4 v132, s[44:45]
	s_mov_b32 m0, s16
	s_nop 0
	global_load_lds_dwordx4 v128, s[82:83]
	s_mov_b32 m0, s17
	s_nop 0
	global_load_lds_dwordx4 v130, s[82:83]
	s_waitcnt vmcnt(8)
	s_waitcnt lgkmcnt(0)
	s_barrier
	s_waitcnt lgkmcnt(0)
	v_mfma_f32_16x16x32_bf16 v[60:63], v[138:141], v[186:189], v[60:63]
	v_mfma_f32_16x16x32_bf16 v[56:59], v[146:149], v[186:189], v[56:59]
	v_mfma_f32_16x16x32_bf16 v[44:47], v[138:141], v[194:197], v[44:47]
	v_mfma_f32_16x16x32_bf16 v[40:43], v[146:149], v[194:197], v[40:43]
	v_mfma_f32_16x16x32_bf16 v[28:31], v[138:141], v[202:205], v[28:31]
	v_mfma_f32_16x16x32_bf16 v[24:27], v[146:149], v[202:205], v[24:27]
	v_mfma_f32_16x16x32_bf16 v[12:15], v[138:141], v[210:213], v[12:15]
	v_mfma_f32_16x16x32_bf16 v[8:11], v[146:149], v[210:213], v[8:11]
	v_mfma_f32_16x16x32_bf16 v[60:63], v[142:145], v[190:193], v[60:63]
	v_mfma_f32_16x16x32_bf16 v[56:59], v[150:153], v[190:193], v[56:59]
	v_mfma_f32_16x16x32_bf16 v[44:47], v[142:145], v[198:201], v[44:47]
	v_mfma_f32_16x16x32_bf16 v[40:43], v[150:153], v[198:201], v[40:43]
	v_mfma_f32_16x16x32_bf16 v[28:31], v[142:145], v[206:209], v[28:31]
	v_mfma_f32_16x16x32_bf16 v[24:27], v[150:153], v[206:209], v[24:27]
	v_mfma_f32_16x16x32_bf16 v[12:15], v[142:145], v[214:217], v[12:15]
	v_mfma_f32_16x16x32_bf16 v[8:11], v[150:153], v[214:217], v[8:11]
	v_mfma_f32_16x16x32_bf16 v[52:55], v[170:173], v[186:189], v[52:55]
	v_mfma_f32_16x16x32_bf16 v[48:51], v[178:181], v[186:189], v[48:51]
	v_mfma_f32_16x16x32_bf16 v[36:39], v[170:173], v[194:197], v[36:39]
	v_mfma_f32_16x16x32_bf16 v[32:35], v[178:181], v[194:197], v[32:35]
	v_mfma_f32_16x16x32_bf16 v[20:23], v[170:173], v[202:205], v[20:23]
	v_mfma_f32_16x16x32_bf16 v[16:19], v[178:181], v[202:205], v[16:19]
	v_mfma_f32_16x16x32_bf16 v[4:7], v[170:173], v[210:213], v[4:7]
	v_mfma_f32_16x16x32_bf16 v[0:3], v[178:181], v[210:213], v[0:3]
	v_mfma_f32_16x16x32_bf16 v[52:55], v[174:177], v[190:193], v[52:55]
	v_mfma_f32_16x16x32_bf16 v[48:51], v[182:185], v[190:193], v[48:51]
	v_mfma_f32_16x16x32_bf16 v[36:39], v[174:177], v[198:201], v[36:39]
	v_mfma_f32_16x16x32_bf16 v[32:35], v[182:185], v[198:201], v[32:35]
	v_mfma_f32_16x16x32_bf16 v[20:23], v[174:177], v[206:209], v[20:23]
	v_mfma_f32_16x16x32_bf16 v[16:19], v[182:185], v[206:209], v[16:19]
	v_mfma_f32_16x16x32_bf16 v[4:7], v[174:177], v[214:217], v[4:7]
	v_mfma_f32_16x16x32_bf16 v[0:3], v[182:185], v[214:217], v[0:3]
	s_barrier
; #define PG8_STAGE(bufoff, gbase, voff) do { _Pragma("unroll") for (int _i = 0; _i < 2; ++_i) \
;         __builtin_amdgcn_global_load_lds((const unsigned*)((const char*)(gbase) + (voff)[_i]), (LAS unsigned*)(lds + (bufoff) + ldsw + _i * 8192), 16, 0, 0); } while (0)
; #define PG8_LDA(dst, b, h) do { _Pragma("unroll") for (int m = 0; m < 4; ++m) _Pragma("unroll") for (int k = 0; k < 2; ++k) dst[m][k] = *(const LAS bf16x8*)(lds + PG8_SA(b, h) + aoff + m * 2048 + k * 1024); } while (0)
; #define PG8_LDB(dst, b, h) do { _Pragma("unroll") for (int n = 0; n < 2; ++n) _Pragma("unroll") for (int k = 0; k < 2; ++k) dst[n][k] = *(const LAS bf16x8*)(lds + PG8_SB(b, h) + boff + n * 2048 + k * 1024); } while (0)
; #define PG8_MMA(ai, bj, At, Bt) do { __builtin_amdgcn_s_setprio(1); _Pragma("unroll") for (int m = 0; m < 4; ++m) _Pragma("unroll") for (int n = 0; n < 2; ++n) _Pragma("unroll") for (int k = 0; k < 2; ++k) \
;         acc[ai][bj][m][n] = __builtin_amdgcn_mfma_f32_16x16x32_bf16(Bt[n][k], At[m][k], acc[ai][bj][m][n], 0, 0, 0); __builtin_amdgcn_s_setprio(0); } while (0)
; #define PG8_WAIT_V(n) asm volatile("s_waitcnt vmcnt(" #n ")" ::: "memory")
; #define PG8_WAIT_L(n) asm volatile("s_waitcnt lgkmcnt(" #n ")" ::: "memory")
; #define PG8_BAR __builtin_amdgcn_s_barrier()
; #define PG8_SCHED __builtin_amdgcn_sched_barrier(0)
; template <class Epi, class Sched, bool ALIGN_EPI = true, bool SP2 = true>
; __device__ __forceinline__ void gemm_phase(LAS unsigned char* lds, const Gemm g, const Sched& S, const Epi& E) {
;     ...
;             PG8_LDB(B0, 1, 0); PG8_LDB(B1, 1, 1); PG8_SCHED; PG8_LDA(At, 1, 0); PG8_STAGE(PG8_SA(0, 1), a2 + hstep, voffA);
;             PG8_WAIT_V(8); PG8_WAIT_L(0); PG8_BAR; PG8_MMA(0, 0, At, B0); PG8_MMA(0, 1, At, B1); PG8_BAR; PG8_SCHED;
;             PG8_LDA(At, 1, 1); PG8_STAGE(PG8_SB(1, 0), b3, voffB); PG8_STAGE(PG8_SB(1, 1), b3 + hstep, voffB); PG8_STAGE(PG8_SA(1, 0), a3, voffA);
;             PG8_WAIT_V(8); PG8_WAIT_L(0); PG8_BAR; PG8_MMA(1, 0, At, B0); PG8_MMA(1, 1, At, B1); PG8_BAR; PG8_SCHED;
	s_add_i32 s43, 0, 0x18000
	s_add_i32 s46, 0, 0x1c000
	v_add_u32_e32 v150, s43, v155
	v_add_u32_e32 v166, s46, v155
	ds_read_b128 v[138:141], v150
	ds_read_b128 v[142:145], v150 offset:1024
	ds_read_b128 v[146:149], v150 offset:2048
	ds_read_b128 v[150:153], v150 offset:3072
	ds_read_b128 v[170:173], v166
	ds_read_b128 v[174:177], v166 offset:1024
	ds_read_b128 v[178:181], v166 offset:2048
	ds_read_b128 v[182:185], v166 offset:3072
	s_add_u32 s44, s82, 0x80000
	s_addc_u32 s45, s83, 0
	s_mov_b32 m0, s30
	ds_read_b128 v[186:189], v157 offset:32768
	ds_read_b128 v[190:193], v157 offset:33792
	ds_read_b128 v[194:197], v157 offset:34816
	ds_read_b128 v[198:201], v157 offset:35840
	ds_read_b128 v[202:205], v157 offset:36864
	ds_read_b128 v[206:209], v157 offset:37888
	ds_read_b128 v[210:213], v157 offset:38912
	ds_read_b128 v[214:217], v157 offset:39936
	global_load_lds_dwordx4 v128, s[44:45]
	s_mov_b32 m0, s31
	s_nop 0
	global_load_lds_dwordx4 v130, s[44:45]
	s_waitcnt vmcnt(8)
	s_waitcnt lgkmcnt(0)
	s_barrier
	s_waitcnt lgkmcnt(0)
	v_mfma_f32_16x16x32_bf16 v[124:127], v[138:141], v[186:189], v[124:127]
	v_mfma_f32_16x16x32_bf16 v[120:123], v[146:149], v[186:189], v[120:123]
	v_mfma_f32_16x16x32_bf16 v[108:111], v[138:141], v[194:197], v[108:111]
	v_mfma_f32_16x16x32_bf16 v[104:107], v[146:149], v[194:197], v[104:107]
	v_mfma_f32_16x16x32_bf16 v[92:95], v[138:141], v[202:205], v[92:95]
	v_mfma_f32_16x16x32_bf16 v[88:91], v[146:149], v[202:205], v[88:91]
	v_mfma_f32_16x16x32_bf16 v[76:79], v[138:141], v[210:213], v[76:79]
	v_mfma_f32_16x16x32_bf16 v[72:75], v[146:149], v[210:213], v[72:75]
	v_mfma_f32_16x16x32_bf16 v[124:127], v[142:145], v[190:193], v[124:127]
	v_mfma_f32_16x16x32_bf16 v[120:123], v[150:153], v[190:193], v[120:123]
	v_mfma_f32_16x16x32_bf16 v[108:111], v[142:145], v[198:201], v[108:111]
	v_mfma_f32_16x16x32_bf16 v[104:107], v[150:153], v[198:201], v[104:107]
	v_mfma_f32_16x16x32_bf16 v[92:95], v[142:145], v[206:209], v[92:95]
	v_mfma_f32_16x16x32_bf16 v[88:91], v[150:153], v[206:209], v[88:91]
	v_mfma_f32_16x16x32_bf16 v[76:79], v[142:145], v[214:217], v[76:79]
	v_mfma_f32_16x16x32_bf16 v[72:75], v[150:153], v[214:217], v[72:75]
	v_mfma_f32_16x16x32_bf16 v[116:119], v[170:173], v[186:189], v[116:119]
	v_mfma_f32_16x16x32_bf16 v[112:115], v[178:181], v[186:189], v[112:115]
	v_mfma_f32_16x16x32_bf16 v[100:103], v[170:173], v[194:197], v[100:103]
	v_mfma_f32_16x16x32_bf16 v[96:99], v[178:181], v[194:197], v[96:99]
	v_mfma_f32_16x16x32_bf16 v[84:87], v[170:173], v[202:205], v[84:87]
	v_mfma_f32_16x16x32_bf16 v[80:83], v[178:181], v[202:205], v[80:83]
	v_mfma_f32_16x16x32_bf16 v[68:71], v[170:173], v[210:213], v[68:71]
	v_mfma_f32_16x16x32_bf16 v[64:67], v[178:181], v[210:213], v[64:67]
	v_mfma_f32_16x16x32_bf16 v[116:119], v[174:177], v[190:193], v[116:119]
	v_mfma_f32_16x16x32_bf16 v[112:115], v[182:185], v[190:193], v[112:115]
	v_mfma_f32_16x16x32_bf16 v[100:103], v[174:177], v[198:201], v[100:103]
	v_mfma_f32_16x16x32_bf16 v[96:99], v[182:185], v[198:201], v[96:99]
	v_mfma_f32_16x16x32_bf16 v[84:87], v[174:177], v[206:209], v[84:87]
	v_mfma_f32_16x16x32_bf16 v[80:83], v[182:185], v[206:209], v[80:83]
	v_mfma_f32_16x16x32_bf16 v[68:71], v[174:177], v[214:217], v[68:71]
	v_mfma_f32_16x16x32_bf16 v[64:67], v[182:185], v[214:217], v[64:67]
	s_barrier
	s_add_i32 s43, s43, s41
	s_mov_b32 m0, s43
	ds_read_b128 v[186:189], v157 offset:49152
	ds_read_b128 v[190:193], v157 offset:50176
	ds_read_b128 v[194:197], v157 offset:51200
	ds_read_b128 v[198:201], v157 offset:52224
	ds_read_b128 v[202:205], v157 offset:53248
	ds_read_b128 v[206:209], v157 offset:54272
	ds_read_b128 v[210:213], v157 offset:55296
	ds_read_b128 v[214:217], v157 offset:56320
	s_add_u32 s98, s24, 0x80
	s_addc_u32 s99, s25, 0
	global_load_lds_dwordx4 v160, s[98:99]
	s_add_i32 m0, s43, 0x2000
	s_add_u32 s24, s24, 0x80080
	s_addc_u32 s25, s25, 0
	s_add_i32 s43, s46, s41
	global_load_lds_dwordx4 v132, s[98:99]
	s_mov_b32 m0, s43
	s_nop 0
	global_load_lds_dwordx4 v160, s[24:25]
	s_add_i32 m0, s43, 0x2000
	s_nop 0
	global_load_lds_dwordx4 v132, s[24:25]
	s_mov_b32 m0, s60
	s_nop 0
	s_add_u32 s98, s82, 0x80
	s_addc_u32 s99, s83, 0
	global_load_lds_dwordx4 v128, s[98:99]
	s_mov_b32 m0, s61
	s_nop 0
	global_load_lds_dwordx4 v130, s[98:99]
	s_waitcnt vmcnt(8)
	s_waitcnt lgkmcnt(0)
	s_barrier
	s_waitcnt lgkmcnt(0)
	v_mfma_f32_16x16x32_bf16 v[60:63], v[138:141], v[186:189], v[60:63]
	v_mfma_f32_16x16x32_bf16 v[56:59], v[146:149], v[186:189], v[56:59]
	v_mfma_f32_16x16x32_bf16 v[44:47], v[138:141], v[194:197], v[44:47]
	v_mfma_f32_16x16x32_bf16 v[40:43], v[146:149], v[194:197], v[40:43]
	v_mfma_f32_16x16x32_bf16 v[28:31], v[138:141], v[202:205], v[28:31]
	v_mfma_f32_16x16x32_bf16 v[24:27], v[146:149], v[202:205], v[24:27]
	v_mfma_f32_16x16x32_bf16 v[12:15], v[138:141], v[210:213], v[12:15]
	v_mfma_f32_16x16x32_bf16 v[8:11], v[146:149], v[210:213], v[8:11]
	v_mfma_f32_16x16x32_bf16 v[60:63], v[142:145], v[190:193], v[60:63]
	v_mfma_f32_16x16x32_bf16 v[56:59], v[150:153], v[190:193], v[56:59]
	v_mfma_f32_16x16x32_bf16 v[44:47], v[142:145], v[198:201], v[44:47]
	v_mfma_f32_16x16x32_bf16 v[40:43], v[150:153], v[198:201], v[40:43]
	v_mfma_f32_16x16x32_bf16 v[28:31], v[142:145], v[206:209], v[28:31]
	v_mfma_f32_16x16x32_bf16 v[24:27], v[150:153], v[206:209], v[24:27]
	v_mfma_f32_16x16x32_bf16 v[12:15], v[142:145], v[214:217], v[12:15]
	v_mfma_f32_16x16x32_bf16 v[8:11], v[150:153], v[214:217], v[8:11]
	v_mfma_f32_16x16x32_bf16 v[52:55], v[170:173], v[186:189], v[52:55]
	v_mfma_f32_16x16x32_bf16 v[48:51], v[178:181], v[186:189], v[48:51]
	v_mfma_f32_16x16x32_bf16 v[36:39], v[170:173], v[194:197], v[36:39]
	v_mfma_f32_16x16x32_bf16 v[32:35], v[178:181], v[194:197], v[32:35]
	v_mfma_f32_16x16x32_bf16 v[20:23], v[170:173], v[202:205], v[20:23]
	v_mfma_f32_16x16x32_bf16 v[16:19], v[178:181], v[202:205], v[16:19]
	v_mfma_f32_16x16x32_bf16 v[4:7], v[170:173], v[210:213], v[4:7]
	v_mfma_f32_16x16x32_bf16 v[0:3], v[178:181], v[210:213], v[0:3]
	v_mfma_f32_16x16x32_bf16 v[52:55], v[174:177], v[190:193], v[52:55]
	v_mfma_f32_16x16x32_bf16 v[48:51], v[182:185], v[190:193], v[48:51]
	v_mfma_f32_16x16x32_bf16 v[36:39], v[174:177], v[198:201], v[36:39]
	v_mfma_f32_16x16x32_bf16 v[32:35], v[182:185], v[198:201], v[32:35]
	v_mfma_f32_16x16x32_bf16 v[20:23], v[174:177], v[206:209], v[20:23]
	v_mfma_f32_16x16x32_bf16 v[16:19], v[182:185], v[206:209], v[16:19]
	v_mfma_f32_16x16x32_bf16 v[4:7], v[174:177], v[214:217], v[4:7]
	v_mfma_f32_16x16x32_bf16 v[0:3], v[182:185], v[214:217], v[0:3]
	s_barrier
	s_add_i32 s42, s42, 2
	s_add_u32 s62, s62, 0x100
	s_addc_u32 s63, s63, 0
	s_add_u32 s18, s18, 0x100
	s_addc_u32 s19, s19, 0
	s_cmp_gt_u32 s42, 29
	s_cbranch_scc0 .LBB0_354
	s_setprio 0
	s_and_b64 vcc, exec, s[14:15]
	s_cbranch_vccz .LBB0_357
	s_barrier

; #define PG8_STAGE(bufoff, gbase, voff) do { _Pragma("unroll") for (int _i = 0; _i < 2; ++_i) \
;         __builtin_amdgcn_global_load_lds((const unsigned*)((const char*)(gbase) + (voff)[_i]), (LAS unsigned*)(lds + (bufoff) + ldsw + _i * 8192), 16, 0, 0); } while (0)
; #define PG8_LDA(dst, b, h) do { _Pragma("unroll") for (int m = 0; m < 4; ++m) _Pragma("unroll") for (int k = 0; k < 2; ++k) dst[m][k] = *(const LAS bf16x8*)(lds + PG8_SA(b, h) + aoff + m * 2048 + k * 1024); } while (0)
; #define PG8_LDB(dst, b, h) do { _Pragma("unroll") for (int n = 0; n < 2; ++n) _Pragma("unroll") for (int k = 0; k < 2; ++k) dst[n][k] = *(const LAS bf16x8*)(lds + PG8_SB(b, h) + boff + n * 2048 + k * 1024); } while (0)
; #define PG8_MMA(ai, bj, At, Bt) do { __builtin_amdgcn_s_setprio(1); _Pragma("unroll") for (int m = 0; m < 4; ++m) _Pragma("unroll") for (int n = 0; n < 2; ++n) _Pragma("unroll") for (int k = 0; k < 2; ++k) \
;         acc[ai][bj][m][n] = __builtin_amdgcn_mfma_f32_16x16x32_bf16(Bt[n][k], At[m][k], acc[ai][bj][m][n], 0, 0, 0); __builtin_amdgcn_s_setprio(0); } while (0)
; #define PG8_WAIT_V(n) asm volatile("s_waitcnt vmcnt(" #n ")" ::: "memory")
; #define PG8_WAIT_L(n) asm volatile("s_waitcnt lgkmcnt(" #n ")" ::: "memory")
; #define PG8_BAR __builtin_amdgcn_s_barrier()
; #define PG8_SCHED __builtin_amdgcn_sched_barrier(0)
; template <class Epi, class Sched, bool ALIGN_EPI = true, bool SP2 = true>
; __device__ __forceinline__ void gemm_phase(LAS unsigned char* lds, const Gemm g, const Sched& S, const Epi& E) {
;     ...
;             const char* a1 = cA + (size_t)(t + 1) * kstep;
;             const char* a2 = last ? nA : cA + (size_t)(t + 2) * kstep; const char* b2 = last ? nB : cB + (size_t)(t + 2) * kstep;
;             const char* a3 = a2 + kstep; const char* b3 = b2 + kstep;
;             if constexpr (SP2) {
;             PG8_LDB(B0, 0, 0); PG8_LDB(B1, 0, 1); PG8_SCHED; PG8_LDA(At, 0, 0); PG8_STAGE(PG8_SA(1, 1), a1 + hstep, voffA);
;             PG8_WAIT_V(8); PG8_WAIT_L(0); PG8_BAR; PG8_MMA(0, 0, At, B0); PG8_MMA(0, 1, At, B1); PG8_BAR; PG8_SCHED;
;     ...
; #pragma unroll
;         for (int a = 0; a < 2; ++a)
; #pragma unroll
;             for (int b = 0; b < 2; ++b)
; #pragma unroll
;                 for (int m = 0; m < 4; ++m)
; #pragma unroll
;                     for (int n = 0; n < 2; ++n) acc[a][b][m][n] = (f32x4){0.f, 0.f, 0.f, 0.f};
.LBB0_565:
	s_add_u32 s2, s54, 0x100
	v_mov_b32_e32 v0, 0
	s_addc_u32 s3, s55, 0
	s_mov_b32 s89, -2
	s_waitcnt lgkmcnt(0)
	v_mov_b32_e32 v1, v0
	v_mov_b32_e32 v2, v0
	v_mov_b32_e32 v3, v0
	v_mov_b32_e32 v4, v0
	v_mov_b32_e32 v5, v0
	v_mov_b32_e32 v6, v0
	v_mov_b32_e32 v7, v0
	v_mov_b32_e32 v16, v0
	v_mov_b32_e32 v17, v0
	v_mov_b32_e32 v18, v0
	v_mov_b32_e32 v19, v0
	v_mov_b32_e32 v20, v0
	v_mov_b32_e32 v21, v0
	v_mov_b32_e32 v22, v0
	v_mov_b32_e32 v23, v0
	v_mov_b32_e32 v32, v0
	v_mov_b32_e32 v33, v0
	v_mov_b32_e32 v34, v0
	v_mov_b32_e32 v35, v0
	s_waitcnt vmcnt(0)
	v_mov_b32_e32 v36, v0
	v_mov_b32_e32 v37, v0
	v_mov_b32_e32 v38, v0
	v_mov_b32_e32 v39, v0
	v_mov_b32_e32 v48, v0
	v_mov_b32_e32 v49, v0
	v_mov_b32_e32 v50, v0
	v_mov_b32_e32 v51, v0
	v_mov_b32_e32 v52, v0
	v_mov_b32_e32 v53, v0
	v_mov_b32_e32 v54, v0
	v_mov_b32_e32 v55, v0
	v_mov_b32_e32 v8, v0
	v_mov_b32_e32 v9, v0
	v_mov_b32_e32 v10, v0
	v_mov_b32_e32 v11, v0
	v_mov_b32_e32 v12, v0
	v_mov_b32_e32 v13, v0
	v_mov_b32_e32 v14, v0
	v_mov_b32_e32 v15, v0
	v_mov_b32_e32 v24, v0
	v_mov_b32_e32 v25, v0
	v_mov_b32_e32 v26, v0
	v_mov_b32_e32 v27, v0
	v_mov_b32_e32 v28, v0
	v_mov_b32_e32 v29, v0
	v_mov_b32_e32 v30, v0
	v_mov_b32_e32 v31, v0
	v_mov_b32_e32 v40, v0
	v_mov_b32_e32 v41, v0
	v_mov_b32_e32 v42, v0
	v_mov_b32_e32 v43, v0
	v_mov_b32_e32 v44, v0
	v_mov_b32_e32 v45, v0
	v_mov_b32_e32 v46, v0
	v_mov_b32_e32 v47, v0
	v_mov_b32_e32 v56, v0
	v_mov_b32_e32 v57, v0
	v_mov_b32_e32 v58, v0
	v_mov_b32_e32 v59, v0
	v_mov_b32_e32 v60, v0
	v_mov_b32_e32 v61, v0
	v_mov_b32_e32 v62, v0
	v_mov_b32_e32 v63, v0
	v_mov_b32_e32 v64, v0
	v_mov_b32_e32 v65, v0
	v_mov_b32_e32 v66, v0
	v_mov_b32_e32 v67, v0
	v_mov_b32_e32 v68, v0
	v_mov_b32_e32 v69, v0
	v_mov_b32_e32 v70, v0
	v_mov_b32_e32 v71, v0
	v_mov_b32_e32 v80, v0
	v_mov_b32_e32 v81, v0
	v_mov_b32_e32 v82, v0
	v_mov_b32_e32 v83, v0
	v_mov_b32_e32 v84, v0
	v_mov_b32_e32 v85, v0
	v_mov_b32_e32 v86, v0
	v_mov_b32_e32 v87, v0
	v_mov_b32_e32 v96, v0
	v_mov_b32_e32 v97, v0
	v_mov_b32_e32 v98, v0
	v_mov_b32_e32 v99, v0
	v_mov_b32_e32 v100, v0
	v_mov_b32_e32 v101, v0
	v_mov_b32_e32 v102, v0
	v_mov_b32_e32 v103, v0
	v_mov_b32_e32 v112, v0
	v_mov_b32_e32 v113, v0
	v_mov_b32_e32 v114, v0
	v_mov_b32_e32 v115, v0
	v_mov_b32_e32 v116, v0
	v_mov_b32_e32 v117, v0
	v_mov_b32_e32 v118, v0
	v_mov_b32_e32 v119, v0
	v_mov_b32_e32 v72, v0
	v_mov_b32_e32 v73, v0
	v_mov_b32_e32 v74, v0
	v_mov_b32_e32 v75, v0
	v_mov_b32_e32 v76, v0
	v_mov_b32_e32 v77, v0
	v_mov_b32_e32 v78, v0
	v_mov_b32_e32 v79, v0
	v_mov_b32_e32 v88, v0
	v_mov_b32_e32 v89, v0
	v_mov_b32_e32 v90, v0
	v_mov_b32_e32 v91, v0
	v_mov_b32_e32 v92, v0
	v_mov_b32_e32 v93, v0
	v_mov_b32_e32 v94, v0
	v_mov_b32_e32 v95, v0
	v_mov_b32_e32 v104, v0
	v_mov_b32_e32 v105, v0
	v_mov_b32_e32 v106, v0
	v_mov_b32_e32 v107, v0
	v_mov_b32_e32 v108, v0
	v_mov_b32_e32 v109, v0
	v_mov_b32_e32 v110, v0
	v_mov_b32_e32 v111, v0
	v_mov_b32_e32 v120, v0
	v_mov_b32_e32 v121, v0
	v_mov_b32_e32 v122, v0
	v_mov_b32_e32 v123, v0
	v_mov_b32_e32 v124, v0
	v_mov_b32_e32 v125, v0
	v_mov_b32_e32 v126, v0
	v_mov_b32_e32 v127, v0
	v_lshrrev_b32_e32 v226, 8, v238
	v_cmp_ne_u32_e64 s[98:99], 0, v226
	s_nop 3
	s_and_b64 s[98:99], s[98:99], exec
	s_cbranch_scc0 .Lprio_skip_566
	s_setprio 1
.Lprio_skip_566:
.LBB0_566:
	s_add_u32 s54, s52, 0x100
	s_addc_u32 s55, s53, 0
	s_add_i32 s46, 0, 0x10000
	s_cmpk_eq_i32 s89, 0x54
	s_cselect_b32 s61, s9, s55
	s_cselect_b32 s60, s8, s54
	v_add_u32_e32 v142, s46, v145
	s_cselect_b32 s25, s31, s3
	s_cselect_b32 s24, s30, s2
	s_add_i32 s47, 0, 0x14000
	ds_read_b128 v[138:141], v142
	ds_read_b128 v[148:151], v142 offset:1024
	ds_read_b128 v[152:155], v142 offset:2048
	ds_read_b128 v[156:159], v142 offset:3072
	v_add_u32_e32 v142, s47, v145
	ds_read_b128 v[170:173], v142
	ds_read_b128 v[174:177], v142 offset:1024
	ds_read_b128 v[178:181], v142 offset:2048
	ds_read_b128 v[182:185], v142 offset:3072
	s_add_i32 m0, s63, 0xc000
	ds_read_b128 v[186:189], v147
	ds_read_b128 v[190:193], v147 offset:1024
	ds_read_b128 v[194:197], v147 offset:2048
	ds_read_b128 v[198:201], v147 offset:3072
	ds_read_b128 v[202:205], v147 offset:4096
	ds_read_b128 v[206:209], v147 offset:5120
	ds_read_b128 v[210:213], v147 offset:6144
	ds_read_b128 v[214:217], v147 offset:7168
	global_load_lds_dwordx4 v134, s[52:53]
	s_add_i32 m0, s63, 0xe000
	s_nop 0
	global_load_lds_dwordx4 v136, s[52:53]
	s_waitcnt vmcnt(8)
	s_waitcnt lgkmcnt(0)
	s_barrier
	s_waitcnt lgkmcnt(0)
	v_mfma_f32_16x16x32_bf16 v[124:127], v[138:141], v[186:189], v[124:127]
	v_mfma_f32_16x16x32_bf16 v[120:123], v[152:155], v[186:189], v[120:123]
	v_mfma_f32_16x16x32_bf16 v[108:111], v[138:141], v[194:197], v[108:111]
	v_mfma_f32_16x16x32_bf16 v[104:107], v[152:155], v[194:197], v[104:107]
	v_mfma_f32_16x16x32_bf16 v[92:95], v[138:141], v[202:205], v[92:95]
	v_mfma_f32_16x16x32_bf16 v[88:91], v[152:155], v[202:205], v[88:91]
	v_mfma_f32_16x16x32_bf16 v[76:79], v[138:141], v[210:213], v[76:79]
	v_mfma_f32_16x16x32_bf16 v[72:75], v[152:155], v[210:213], v[72:75]
	v_mfma_f32_16x16x32_bf16 v[124:127], v[148:151], v[190:193], v[124:127]
	v_mfma_f32_16x16x32_bf16 v[120:123], v[156:159], v[190:193], v[120:123]
	v_mfma_f32_16x16x32_bf16 v[108:111], v[148:151], v[198:201], v[108:111]
	v_mfma_f32_16x16x32_bf16 v[104:107], v[156:159], v[198:201], v[104:107]
	v_mfma_f32_16x16x32_bf16 v[92:95], v[148:151], v[206:209], v[92:95]
	v_mfma_f32_16x16x32_bf16 v[88:91], v[156:159], v[206:209], v[88:91]
	v_mfma_f32_16x16x32_bf16 v[76:79], v[148:151], v[214:217], v[76:79]
	v_mfma_f32_16x16x32_bf16 v[72:75], v[156:159], v[214:217], v[72:75]
	v_mfma_f32_16x16x32_bf16 v[116:119], v[170:173], v[186:189], v[116:119]
	v_mfma_f32_16x16x32_bf16 v[112:115], v[178:181], v[186:189], v[112:115]
	v_mfma_f32_16x16x32_bf16 v[100:103], v[170:173], v[194:197], v[100:103]
	v_mfma_f32_16x16x32_bf16 v[96:99], v[178:181], v[194:197], v[96:99]
	v_mfma_f32_16x16x32_bf16 v[84:87], v[170:173], v[202:205], v[84:87]
	v_mfma_f32_16x16x32_bf16 v[80:83], v[178:181], v[202:205], v[80:83]
	v_mfma_f32_16x16x32_bf16 v[68:71], v[170:173], v[210:213], v[68:71]
	v_mfma_f32_16x16x32_bf16 v[64:67], v[178:181], v[210:213], v[64:67]
	v_mfma_f32_16x16x32_bf16 v[116:119], v[174:177], v[190:193], v[116:119]
	v_mfma_f32_16x16x32_bf16 v[112:115], v[182:185], v[190:193], v[112:115]
	v_mfma_f32_16x16x32_bf16 v[100:103], v[174:177], v[198:201], v[100:103]
	v_mfma_f32_16x16x32_bf16 v[96:99], v[182:185], v[198:201], v[96:99]
	v_mfma_f32_16x16x32_bf16 v[84:87], v[174:177], v[206:209], v[84:87]
	v_mfma_f32_16x16x32_bf16 v[80:83], v[182:185], v[206:209], v[80:83]
	v_mfma_f32_16x16x32_bf16 v[68:71], v[174:177], v[214:217], v[68:71]
	v_mfma_f32_16x16x32_bf16 v[64:67], v[182:185], v[214:217], v[64:67]
	s_barrier
; #define PG8_STAGE(bufoff, gbase, voff) do { _Pragma("unroll") for (int _i = 0; _i < 2; ++_i) \
;         __builtin_amdgcn_global_load_lds((const unsigned*)((const char*)(gbase) + (voff)[_i]), (LAS unsigned*)(lds + (bufoff) + ldsw + _i * 8192), 16, 0, 0); } while (0)
; #define PG8_LDA(dst, b, h) do { _Pragma("unroll") for (int m = 0; m < 4; ++m) _Pragma("unroll") for (int k = 0; k < 2; ++k) dst[m][k] = *(const LAS bf16x8*)(lds + PG8_SA(b, h) + aoff + m * 2048 + k * 1024); } while (0)
; #define PG8_LDB(dst, b, h) do { _Pragma("unroll") for (int n = 0; n < 2; ++n) _Pragma("unroll") for (int k = 0; k < 2; ++k) dst[n][k] = *(const LAS bf16x8*)(lds + PG8_SB(b, h) + boff + n * 2048 + k * 1024); } while (0)
; #define PG8_MMA(ai, bj, At, Bt) do { __builtin_amdgcn_s_setprio(1); _Pragma("unroll") for (int m = 0; m < 4; ++m) _Pragma("unroll") for (int n = 0; n < 2; ++n) _Pragma("unroll") for (int k = 0; k < 2; ++k) \
;         acc[ai][bj][m][n] = __builtin_amdgcn_mfma_f32_16x16x32_bf16(Bt[n][k], At[m][k], acc[ai][bj][m][n], 0, 0, 0); __builtin_amdgcn_s_setprio(0); } while (0)
; #define PG8_WAIT_V(n) asm volatile("s_waitcnt vmcnt(" #n ")" ::: "memory")
; #define PG8_WAIT_L(n) asm volatile("s_waitcnt lgkmcnt(" #n ")" ::: "memory")
; #define PG8_BAR __builtin_amdgcn_s_barrier()
; #define PG8_SCHED __builtin_amdgcn_sched_barrier(0)
; template <class Epi, class Sched, bool ALIGN_EPI = true, bool SP2 = true>
; __device__ __forceinline__ void gemm_phase(LAS unsigned char* lds, const Gemm g, const Sched& S, const Epi& E) {
;     ...
;             PG8_LDA(At, 0, 1); PG8_STAGE(PG8_SB(0, 0), b2, voffB); PG8_STAGE(PG8_SB(0, 1), b2 + hstep, voffB); PG8_STAGE(PG8_SA(0, 0), a2, voffA);
;             PG8_WAIT_V(8); PG8_WAIT_L(0); PG8_BAR; PG8_MMA(1, 0, At, B0); PG8_MMA(1, 1, At, B1); PG8_BAR; PG8_SCHED;
;             PG8_LDB(B0, 1, 0); PG8_LDB(B1, 1, 1); PG8_SCHED; PG8_LDA(At, 1, 0); PG8_STAGE(PG8_SA(0, 1), a2 + hstep, voffA);
	s_add_i32 s46, s46, s62
	s_mov_b32 m0, s46
	ds_read_b128 v[186:189], v147 offset:16384
	ds_read_b128 v[190:193], v147 offset:17408
	ds_read_b128 v[194:197], v147 offset:18432
	ds_read_b128 v[198:201], v147 offset:19456
	ds_read_b128 v[202:205], v147 offset:20480
	ds_read_b128 v[206:209], v147 offset:21504
	ds_read_b128 v[210:213], v147 offset:22528
	ds_read_b128 v[214:217], v147 offset:23552
	global_load_lds_dwordx4 v160, s[24:25]
	s_add_i32 m0, s46, 0x2000
	s_add_u32 s52, s24, 0x160000
	s_addc_u32 s53, s25, 0
	s_add_i32 s46, s47, s62
	global_load_lds_dwordx4 v132, s[24:25]
	s_mov_b32 m0, s46
	s_nop 0
	global_load_lds_dwordx4 v160, s[52:53]
	s_add_i32 m0, s46, 0x2000
	s_nop 0
	global_load_lds_dwordx4 v132, s[52:53]
	s_mov_b32 m0, s63
	s_nop 0
	global_load_lds_dwordx4 v128, s[60:61]
	s_mov_b32 m0, s66
	s_nop 0
	global_load_lds_dwordx4 v130, s[60:61]
	s_waitcnt vmcnt(8)
	s_waitcnt lgkmcnt(0)
	s_barrier
	s_waitcnt lgkmcnt(0)
	v_mfma_f32_16x16x32_bf16 v[60:63], v[138:141], v[186:189], v[60:63]
	v_mfma_f32_16x16x32_bf16 v[56:59], v[152:155], v[186:189], v[56:59]
	v_mfma_f32_16x16x32_bf16 v[44:47], v[138:141], v[194:197], v[44:47]
	v_mfma_f32_16x16x32_bf16 v[40:43], v[152:155], v[194:197], v[40:43]
	v_mfma_f32_16x16x32_bf16 v[28:31], v[138:141], v[202:205], v[28:31]
	v_mfma_f32_16x16x32_bf16 v[24:27], v[152:155], v[202:205], v[24:27]
	v_mfma_f32_16x16x32_bf16 v[12:15], v[138:141], v[210:213], v[12:15]
	v_mfma_f32_16x16x32_bf16 v[8:11], v[152:155], v[210:213], v[8:11]
	v_mfma_f32_16x16x32_bf16 v[60:63], v[148:151], v[190:193], v[60:63]
	v_mfma_f32_16x16x32_bf16 v[56:59], v[156:159], v[190:193], v[56:59]
	v_mfma_f32_16x16x32_bf16 v[44:47], v[148:151], v[198:201], v[44:47]
	v_mfma_f32_16x16x32_bf16 v[40:43], v[156:159], v[198:201], v[40:43]
	v_mfma_f32_16x16x32_bf16 v[28:31], v[148:151], v[206:209], v[28:31]
	v_mfma_f32_16x16x32_bf16 v[24:27], v[156:159], v[206:209], v[24:27]
	v_mfma_f32_16x16x32_bf16 v[12:15], v[148:151], v[214:217], v[12:15]
	v_mfma_f32_16x16x32_bf16 v[8:11], v[156:159], v[214:217], v[8:11]
	v_mfma_f32_16x16x32_bf16 v[52:55], v[170:173], v[186:189], v[52:55]
	v_mfma_f32_16x16x32_bf16 v[48:51], v[178:181], v[186:189], v[48:51]
	v_mfma_f32_16x16x32_bf16 v[36:39], v[170:173], v[194:197], v[36:39]
	v_mfma_f32_16x16x32_bf16 v[32:35], v[178:181], v[194:197], v[32:35]
	v_mfma_f32_16x16x32_bf16 v[20:23], v[170:173], v[202:205], v[20:23]
	v_mfma_f32_16x16x32_bf16 v[16:19], v[178:181], v[202:205], v[16:19]
	v_mfma_f32_16x16x32_bf16 v[4:7], v[170:173], v[210:213], v[4:7]
	v_mfma_f32_16x16x32_bf16 v[0:3], v[178:181], v[210:213], v[0:3]
	v_mfma_f32_16x16x32_bf16 v[52:55], v[174:177], v[190:193], v[52:55]
	v_mfma_f32_16x16x32_bf16 v[48:51], v[182:185], v[190:193], v[48:51]
	v_mfma_f32_16x16x32_bf16 v[36:39], v[174:177], v[198:201], v[36:39]
	v_mfma_f32_16x16x32_bf16 v[32:35], v[182:185], v[198:201], v[32:35]
	v_mfma_f32_16x16x32_bf16 v[20:23], v[174:177], v[206:209], v[20:23]
	v_mfma_f32_16x16x32_bf16 v[16:19], v[182:185], v[206:209], v[16:19]
	v_mfma_f32_16x16x32_bf16 v[4:7], v[174:177], v[214:217], v[4:7]
	v_mfma_f32_16x16x32_bf16 v[0:3], v[182:185], v[214:217], v[0:3]
	s_barrier
	s_add_i32 s46, 0, 0x18000
	s_add_i32 s47, 0, 0x1c000
	v_add_u32_e32 v156, s46, v145
	v_add_u32_e32 v166, s47, v145
	ds_read_b128 v[138:141], v156
	ds_read_b128 v[148:151], v156 offset:1024
	ds_read_b128 v[152:155], v156 offset:2048
	ds_read_b128 v[156:159], v156 offset:3072
	ds_read_b128 v[170:173], v166
	ds_read_b128 v[174:177], v166 offset:1024
	ds_read_b128 v[178:181], v166 offset:2048
	ds_read_b128 v[182:185], v166 offset:3072
	s_add_u32 s52, s60, 0x160000
	s_addc_u32 s53, s61, 0
	s_mov_b32 m0, s67
	ds_read_b128 v[186:189], v147 offset:32768
	ds_read_b128 v[190:193], v147 offset:33792
	ds_read_b128 v[194:197], v147 offset:34816
	ds_read_b128 v[198:201], v147 offset:35840
	ds_read_b128 v[202:205], v147 offset:36864
	ds_read_b128 v[206:209], v147 offset:37888
	ds_read_b128 v[210:213], v147 offset:38912
	ds_read_b128 v[214:217], v147 offset:39936
	global_load_lds_dwordx4 v128, s[52:53]
	s_mov_b32 m0, s72
	s_nop 0
	global_load_lds_dwordx4 v130, s[52:53]
	s_waitcnt vmcnt(8)
	s_waitcnt lgkmcnt(0)
	s_barrier
; #define PG8_STAGE(bufoff, gbase, voff) do { _Pragma("unroll") for (int _i = 0; _i < 2; ++_i) \
;         __builtin_amdgcn_global_load_lds((const unsigned*)((const char*)(gbase) + (voff)[_i]), (LAS unsigned*)(lds + (bufoff) + ldsw + _i * 8192), 16, 0, 0); } while (0)
; #define PG8_LDA(dst, b, h) do { _Pragma("unroll") for (int m = 0; m < 4; ++m) _Pragma("unroll") for (int k = 0; k < 2; ++k) dst[m][k] = *(const LAS bf16x8*)(lds + PG8_SA(b, h) + aoff + m * 2048 + k * 1024); } while (0)
; #define PG8_MMA(ai, bj, At, Bt) do { __builtin_amdgcn_s_setprio(1); _Pragma("unroll") for (int m = 0; m < 4; ++m) _Pragma("unroll") for (int n = 0; n < 2; ++n) _Pragma("unroll") for (int k = 0; k < 2; ++k) \
;         acc[ai][bj][m][n] = __builtin_amdgcn_mfma_f32_16x16x32_bf16(Bt[n][k], At[m][k], acc[ai][bj][m][n], 0, 0, 0); __builtin_amdgcn_s_setprio(0); } while (0)
; #define PG8_WAIT_V(n) asm volatile("s_waitcnt vmcnt(" #n ")" ::: "memory")
; #define PG8_WAIT_L(n) asm volatile("s_waitcnt lgkmcnt(" #n ")" ::: "memory")
; #define PG8_BAR __builtin_amdgcn_s_barrier()
; #define PG8_SCHED __builtin_amdgcn_sched_barrier(0)
; template <class Epi, class Sched, bool ALIGN_EPI = true, bool SP2 = true>
; __device__ __forceinline__ void gemm_phase(LAS unsigned char* lds, const Gemm g, const Sched& S, const Epi& E) {
;     ...
;             PG8_WAIT_V(8); PG8_WAIT_L(0); PG8_BAR; PG8_MMA(0, 0, At, B0); PG8_MMA(0, 1, At, B1); PG8_BAR; PG8_SCHED;
;             PG8_LDA(At, 1, 1); PG8_STAGE(PG8_SB(1, 0), b3, voffB); PG8_STAGE(PG8_SB(1, 1), b3 + hstep, voffB); PG8_STAGE(PG8_SA(1, 0), a3, voffA);
;             PG8_WAIT_V(8); PG8_WAIT_L(0); PG8_BAR; PG8_MMA(1, 0, At, B0); PG8_MMA(1, 1, At, B1); PG8_BAR; PG8_SCHED;
	s_waitcnt lgkmcnt(0)
	v_mfma_f32_16x16x32_bf16 v[124:127], v[138:141], v[186:189], v[124:127]
	v_mfma_f32_16x16x32_bf16 v[120:123], v[152:155], v[186:189], v[120:123]
	v_mfma_f32_16x16x32_bf16 v[108:111], v[138:141], v[194:197], v[108:111]
	v_mfma_f32_16x16x32_bf16 v[104:107], v[152:155], v[194:197], v[104:107]
	v_mfma_f32_16x16x32_bf16 v[92:95], v[138:141], v[202:205], v[92:95]
	v_mfma_f32_16x16x32_bf16 v[88:91], v[152:155], v[202:205], v[88:91]
	v_mfma_f32_16x16x32_bf16 v[76:79], v[138:141], v[210:213], v[76:79]
	v_mfma_f32_16x16x32_bf16 v[72:75], v[152:155], v[210:213], v[72:75]
	v_mfma_f32_16x16x32_bf16 v[124:127], v[148:151], v[190:193], v[124:127]
	v_mfma_f32_16x16x32_bf16 v[120:123], v[156:159], v[190:193], v[120:123]
	v_mfma_f32_16x16x32_bf16 v[108:111], v[148:151], v[198:201], v[108:111]
	v_mfma_f32_16x16x32_bf16 v[104:107], v[156:159], v[198:201], v[104:107]
	v_mfma_f32_16x16x32_bf16 v[92:95], v[148:151], v[206:209], v[92:95]
	v_mfma_f32_16x16x32_bf16 v[88:91], v[156:159], v[206:209], v[88:91]
	v_mfma_f32_16x16x32_bf16 v[76:79], v[148:151], v[214:217], v[76:79]
	v_mfma_f32_16x16x32_bf16 v[72:75], v[156:159], v[214:217], v[72:75]
	v_mfma_f32_16x16x32_bf16 v[116:119], v[170:173], v[186:189], v[116:119]
	v_mfma_f32_16x16x32_bf16 v[112:115], v[178:181], v[186:189], v[112:115]
	v_mfma_f32_16x16x32_bf16 v[100:103], v[170:173], v[194:197], v[100:103]
	v_mfma_f32_16x16x32_bf16 v[96:99], v[178:181], v[194:197], v[96:99]
	v_mfma_f32_16x16x32_bf16 v[84:87], v[170:173], v[202:205], v[84:87]
	v_mfma_f32_16x16x32_bf16 v[80:83], v[178:181], v[202:205], v[80:83]
	v_mfma_f32_16x16x32_bf16 v[68:71], v[170:173], v[210:213], v[68:71]
	v_mfma_f32_16x16x32_bf16 v[64:67], v[178:181], v[210:213], v[64:67]
	v_mfma_f32_16x16x32_bf16 v[116:119], v[174:177], v[190:193], v[116:119]
	v_mfma_f32_16x16x32_bf16 v[112:115], v[182:185], v[190:193], v[112:115]
	v_mfma_f32_16x16x32_bf16 v[100:103], v[174:177], v[198:201], v[100:103]
	v_mfma_f32_16x16x32_bf16 v[96:99], v[182:185], v[198:201], v[96:99]
	v_mfma_f32_16x16x32_bf16 v[84:87], v[174:177], v[206:209], v[84:87]
	v_mfma_f32_16x16x32_bf16 v[80:83], v[182:185], v[206:209], v[80:83]
	v_mfma_f32_16x16x32_bf16 v[68:71], v[174:177], v[214:217], v[68:71]
	v_mfma_f32_16x16x32_bf16 v[64:67], v[182:185], v[214:217], v[64:67]
	s_barrier
	s_add_i32 s46, s46, s62
	s_mov_b32 m0, s46
	ds_read_b128 v[186:189], v147 offset:49152
	ds_read_b128 v[190:193], v147 offset:50176
	ds_read_b128 v[194:197], v147 offset:51200
	ds_read_b128 v[198:201], v147 offset:52224
	ds_read_b128 v[202:205], v147 offset:53248
	ds_read_b128 v[206:209], v147 offset:54272
	ds_read_b128 v[210:213], v147 offset:55296
	ds_read_b128 v[214:217], v147 offset:56320
	s_add_u32 s98, s24, 0x80
	s_addc_u32 s99, s25, 0
	global_load_lds_dwordx4 v160, s[98:99]
	s_add_i32 m0, s46, 0x2000
	s_add_u32 s24, s24, 0x160080
	s_addc_u32 s25, s25, 0
	s_add_i32 s46, s47, s62
	global_load_lds_dwordx4 v132, s[98:99]
	s_mov_b32 m0, s46
	s_nop 0
	global_load_lds_dwordx4 v160, s[24:25]
	s_add_i32 m0, s46, 0x2000
	s_nop 0
	global_load_lds_dwordx4 v132, s[24:25]
	s_mov_b32 m0, s73
	s_nop 0
	s_add_u32 s98, s52, 0xffea0080
	s_addc_u32 s99, s53, -1
	global_load_lds_dwordx4 v128, s[98:99]
	s_mov_b32 m0, s79
	s_nop 0
	global_load_lds_dwordx4 v130, s[98:99]
	s_waitcnt vmcnt(8)
	s_waitcnt lgkmcnt(0)
	s_barrier
	s_waitcnt lgkmcnt(0)
	v_mfma_f32_16x16x32_bf16 v[60:63], v[138:141], v[186:189], v[60:63]
	v_mfma_f32_16x16x32_bf16 v[56:59], v[152:155], v[186:189], v[56:59]
	v_mfma_f32_16x16x32_bf16 v[44:47], v[138:141], v[194:197], v[44:47]
	v_mfma_f32_16x16x32_bf16 v[40:43], v[152:155], v[194:197], v[40:43]
	v_mfma_f32_16x16x32_bf16 v[28:31], v[138:141], v[202:205], v[28:31]
	v_mfma_f32_16x16x32_bf16 v[24:27], v[152:155], v[202:205], v[24:27]
	v_mfma_f32_16x16x32_bf16 v[12:15], v[138:141], v[210:213], v[12:15]
	v_mfma_f32_16x16x32_bf16 v[8:11], v[152:155], v[210:213], v[8:11]
	v_mfma_f32_16x16x32_bf16 v[60:63], v[148:151], v[190:193], v[60:63]
	v_mfma_f32_16x16x32_bf16 v[56:59], v[156:159], v[190:193], v[56:59]
	v_mfma_f32_16x16x32_bf16 v[44:47], v[148:151], v[198:201], v[44:47]
	v_mfma_f32_16x16x32_bf16 v[40:43], v[156:159], v[198:201], v[40:43]
	v_mfma_f32_16x16x32_bf16 v[28:31], v[148:151], v[206:209], v[28:31]
	v_mfma_f32_16x16x32_bf16 v[24:27], v[156:159], v[206:209], v[24:27]
	v_mfma_f32_16x16x32_bf16 v[12:15], v[148:151], v[214:217], v[12:15]
	v_mfma_f32_16x16x32_bf16 v[8:11], v[156:159], v[214:217], v[8:11]
	v_mfma_f32_16x16x32_bf16 v[52:55], v[170:173], v[186:189], v[52:55]
	v_mfma_f32_16x16x32_bf16 v[48:51], v[178:181], v[186:189], v[48:51]
	v_mfma_f32_16x16x32_bf16 v[36:39], v[170:173], v[194:197], v[36:39]
	v_mfma_f32_16x16x32_bf16 v[32:35], v[178:181], v[194:197], v[32:35]
	v_mfma_f32_16x16x32_bf16 v[20:23], v[170:173], v[202:205], v[20:23]
	v_mfma_f32_16x16x32_bf16 v[16:19], v[178:181], v[202:205], v[16:19]
	v_mfma_f32_16x16x32_bf16 v[4:7], v[170:173], v[210:213], v[4:7]
	v_mfma_f32_16x16x32_bf16 v[0:3], v[178:181], v[210:213], v[0:3]
	v_mfma_f32_16x16x32_bf16 v[52:55], v[174:177], v[190:193], v[52:55]
	v_mfma_f32_16x16x32_bf16 v[48:51], v[182:185], v[190:193], v[48:51]
	v_mfma_f32_16x16x32_bf16 v[36:39], v[174:177], v[198:201], v[36:39]
	v_mfma_f32_16x16x32_bf16 v[32:35], v[182:185], v[198:201], v[32:35]
	v_mfma_f32_16x16x32_bf16 v[20:23], v[174:177], v[206:209], v[20:23]
	v_mfma_f32_16x16x32_bf16 v[16:19], v[182:185], v[206:209], v[16:19]
	v_mfma_f32_16x16x32_bf16 v[4:7], v[174:177], v[214:217], v[4:7]
	v_mfma_f32_16x16x32_bf16 v[0:3], v[182:185], v[214:217], v[0:3]
	s_barrier
	s_add_i32 s89, s89, 2
	s_add_u32 s2, s2, 0x100
	s_addc_u32 s3, s3, 0
	s_cmpk_gt_u32 s89, 0x55
	s_mov_b64 s[52:53], s[54:55]
	s_cbranch_scc0 .LBB0_566
	s_setprio 0
	s_and_b64 vcc, exec, s[18:19]
	s_cbranch_vccz .LBB0_569
	s_barrier

; #define PG8_STAGE(bufoff, gbase, voff) do { _Pragma("unroll") for (int _i = 0; _i < 2; ++_i) \
;         __builtin_amdgcn_global_load_lds((const unsigned*)((const char*)(gbase) + (voff)[_i]), (LAS unsigned*)(lds + (bufoff) + ldsw + _i * 8192), 16, 0, 0); } while (0)
; #define PG8_LDA(dst, b, h) do { _Pragma("unroll") for (int m = 0; m < 4; ++m) _Pragma("unroll") for (int k = 0; k < 2; ++k) dst[m][k] = *(const LAS bf16x8*)(lds + PG8_SA(b, h) + aoff + m * 2048 + k * 1024); } while (0)
; #define PG8_LDB(dst, b, h) do { _Pragma("unroll") for (int n = 0; n < 2; ++n) _Pragma("unroll") for (int k = 0; k < 2; ++k) dst[n][k] = *(const LAS bf16x8*)(lds + PG8_SB(b, h) + boff + n * 2048 + k * 1024); } while (0)
; #define PG8_SCHED __builtin_amdgcn_sched_barrier(0)
; template <class Epi, class Sched, bool ALIGN_EPI = true, bool SP2 = true>
; __device__ __forceinline__ void gemm_phase(LAS unsigned char* lds, const Gemm g, const Sched& S, const Epi& E) {
;     ...
;         const bool has_next = S.next(ui + 1, nxt);
;         const char* nA = has_next ? (const char*)g.A + (size_t)nxt.pm * tstep : cA; const char* nB = has_next ? (const char*)g.Bt + (size_t)nxt.pn * tstep : cB;
;         for (int t = 0; t < nt; t += 2) {
;             const bool last = (t == nt - 2);
;             const char* a1 = cA + (size_t)(t + 1) * kstep;
;             const char* a2 = last ? nA : cA + (size_t)(t + 2) * kstep; const char* b2 = last ? nB : cB + (size_t)(t + 2) * kstep;
;             const char* a3 = a2 + kstep; const char* b3 = b2 + kstep;
;             if constexpr (SP2) {
;             PG8_LDB(B0, 0, 0); PG8_LDB(B1, 0, 1); PG8_SCHED; PG8_LDA(At, 0, 0); PG8_STAGE(PG8_SA(1, 1), a1 + hstep, voffA);
;     ...
; #pragma unroll
;         for (int a = 0; a < 2; ++a)
; #pragma unroll
;             for (int b = 0; b < 2; ++b)
; #pragma unroll
;                 for (int m = 0; m < 4; ++m)
; #pragma unroll
;                     for (int n = 0; n < 2; ++n) acc[a][b][m][n] = (f32x4){0.f, 0.f, 0.f, 0.f};
.LBB0_599:
	s_ashr_i32 s17, s16, 31
	s_lshl_b64 s[2:3], s[16:17], 20
	s_add_u32 s18, s80, s2
	s_addc_u32 s19, s81, s3
	s_and_b64 s[2:3], s[4:5], exec
	s_cselect_b32 s2, s19, s55
	s_cselect_b32 s3, s18, s54
	s_ashr_i32 s15, s14, 31
	s_lshl_b64 s[30:31], s[14:15], 20
	s_add_u32 s30, s28, s30
	s_addc_u32 s31, s41, s31
	s_and_b64 s[60:61], s[4:5], exec
	s_cselect_b32 s15, s31, s25
	s_cselect_b32 s17, s30, s24
	s_add_u32 s54, s54, 0x80080
	s_addc_u32 s55, s55, 0
	s_add_u32 s79, s24, 0x100
	v_mov_b32_e32 v0, 0
	s_addc_u32 s82, s25, 0
	s_mov_b32 s83, -2
	v_mov_b32_e32 v1, v0
	v_mov_b32_e32 v2, v0
	v_mov_b32_e32 v3, v0
	v_mov_b32_e32 v8, v0
	v_mov_b32_e32 v9, v0
	v_mov_b32_e32 v10, v0
	v_mov_b32_e32 v11, v0
	v_mov_b32_e32 v16, v0
	v_mov_b32_e32 v17, v0
	v_mov_b32_e32 v18, v0
	v_mov_b32_e32 v19, v0
	v_mov_b32_e32 v24, v0
	v_mov_b32_e32 v25, v0
	v_mov_b32_e32 v26, v0
	v_mov_b32_e32 v27, v0
	v_mov_b32_e32 v32, v0
	v_mov_b32_e32 v33, v0
	v_mov_b32_e32 v34, v0
	v_mov_b32_e32 v35, v0
	s_waitcnt vmcnt(0)
	v_mov_b32_e32 v40, v0
	v_mov_b32_e32 v41, v0
	v_mov_b32_e32 v42, v0
	v_mov_b32_e32 v43, v0
	v_mov_b32_e32 v48, v0
	v_mov_b32_e32 v49, v0
	v_mov_b32_e32 v50, v0
	v_mov_b32_e32 v51, v0
	v_mov_b32_e32 v56, v0
	v_mov_b32_e32 v57, v0
	v_mov_b32_e32 v58, v0
	v_mov_b32_e32 v59, v0
	v_mov_b32_e32 v4, v0
	v_mov_b32_e32 v5, v0
	v_mov_b32_e32 v6, v0
	v_mov_b32_e32 v7, v0
	v_mov_b32_e32 v12, v0
	v_mov_b32_e32 v13, v0
	v_mov_b32_e32 v14, v0
	v_mov_b32_e32 v15, v0
	v_mov_b32_e32 v20, v0
	v_mov_b32_e32 v21, v0
	v_mov_b32_e32 v22, v0
	v_mov_b32_e32 v23, v0
	v_mov_b32_e32 v28, v0
	v_mov_b32_e32 v29, v0
	v_mov_b32_e32 v30, v0
	v_mov_b32_e32 v31, v0
	v_mov_b32_e32 v36, v0
	v_mov_b32_e32 v37, v0
	v_mov_b32_e32 v38, v0
	v_mov_b32_e32 v39, v0
	v_mov_b32_e32 v44, v0
	v_mov_b32_e32 v45, v0
	v_mov_b32_e32 v46, v0
	v_mov_b32_e32 v47, v0
	v_mov_b32_e32 v52, v0
	v_mov_b32_e32 v53, v0
	v_mov_b32_e32 v54, v0
	v_mov_b32_e32 v55, v0
	v_mov_b32_e32 v60, v0
	v_mov_b32_e32 v61, v0
	v_mov_b32_e32 v62, v0
	v_mov_b32_e32 v63, v0
	v_mov_b32_e32 v64, v0
	v_mov_b32_e32 v65, v0
	v_mov_b32_e32 v66, v0
	v_mov_b32_e32 v67, v0
	v_mov_b32_e32 v72, v0
	v_mov_b32_e32 v73, v0
	v_mov_b32_e32 v74, v0
	v_mov_b32_e32 v75, v0
	v_mov_b32_e32 v80, v0
	v_mov_b32_e32 v81, v0
	v_mov_b32_e32 v82, v0
	v_mov_b32_e32 v83, v0
	v_mov_b32_e32 v88, v0
	v_mov_b32_e32 v89, v0
	v_mov_b32_e32 v90, v0
	v_mov_b32_e32 v91, v0
	v_mov_b32_e32 v96, v0
	v_mov_b32_e32 v97, v0
	v_mov_b32_e32 v98, v0
	v_mov_b32_e32 v99, v0
	v_mov_b32_e32 v104, v0
	v_mov_b32_e32 v105, v0
	v_mov_b32_e32 v106, v0
	v_mov_b32_e32 v107, v0
	v_mov_b32_e32 v112, v0
	v_mov_b32_e32 v113, v0
	v_mov_b32_e32 v114, v0
	v_mov_b32_e32 v115, v0
	v_mov_b32_e32 v120, v0
	v_mov_b32_e32 v121, v0
	v_mov_b32_e32 v122, v0
	v_mov_b32_e32 v123, v0
	v_mov_b32_e32 v68, v0
	v_mov_b32_e32 v69, v0
	v_mov_b32_e32 v70, v0
	v_mov_b32_e32 v71, v0
	v_mov_b32_e32 v76, v0
	v_mov_b32_e32 v77, v0
	v_mov_b32_e32 v78, v0
	v_mov_b32_e32 v79, v0
	v_mov_b32_e32 v84, v0
	v_mov_b32_e32 v85, v0
	v_mov_b32_e32 v86, v0
	v_mov_b32_e32 v87, v0
	v_mov_b32_e32 v92, v0
	v_mov_b32_e32 v93, v0
	v_mov_b32_e32 v94, v0
	v_mov_b32_e32 v95, v0
	v_mov_b32_e32 v100, v0
	v_mov_b32_e32 v101, v0
	v_mov_b32_e32 v102, v0
	v_mov_b32_e32 v103, v0
	v_mov_b32_e32 v108, v0
	v_mov_b32_e32 v109, v0
	v_mov_b32_e32 v110, v0
	v_mov_b32_e32 v111, v0
	v_mov_b32_e32 v116, v0
	v_mov_b32_e32 v117, v0
	v_mov_b32_e32 v118, v0
	v_mov_b32_e32 v119, v0
	v_mov_b32_e32 v124, v0
	v_mov_b32_e32 v125, v0
	v_mov_b32_e32 v126, v0
	v_mov_b32_e32 v127, v0
	v_lshrrev_b32_e32 v226, 8, v238
	v_cmp_ne_u32_e64 s[98:99], 0, v226
	s_nop 3
	s_and_b64 s[98:99], s[98:99], exec
	s_cbranch_scc0 .Lprio_skip_600
	s_setprio 1
.Lprio_skip_600:
.LBB0_600:
	s_add_u32 s24, s54, 0xfff80080
	s_addc_u32 s25, s55, -1
	s_add_i32 s46, 0, 0x10000
	s_cmp_eq_u32 s83, 28
	s_cselect_b32 s61, s2, s25
	s_cselect_b32 s60, s3, s24
	v_add_u32_e32 v142, s46, v145
	s_cselect_b32 s25, s15, s82
	s_cselect_b32 s24, s17, s79
	s_add_i32 s47, 0, 0x14000
	ds_read_b128 v[138:141], v142
	ds_read_b128 v[148:151], v142 offset:1024
	ds_read_b128 v[152:155], v142 offset:2048
	ds_read_b128 v[156:159], v142 offset:3072
	v_add_u32_e32 v142, s47, v145
	ds_read_b128 v[170:173], v142
	ds_read_b128 v[174:177], v142 offset:1024
	ds_read_b128 v[178:181], v142 offset:2048
	ds_read_b128 v[182:185], v142 offset:3072
	s_add_i32 m0, s43, 0xc000
	ds_read_b128 v[186:189], v147
	ds_read_b128 v[190:193], v147 offset:1024
	ds_read_b128 v[194:197], v147 offset:2048
	ds_read_b128 v[198:201], v147 offset:3072
	ds_read_b128 v[202:205], v147 offset:4096
	ds_read_b128 v[206:209], v147 offset:5120
	ds_read_b128 v[210:213], v147 offset:6144
	ds_read_b128 v[214:217], v147 offset:7168
	global_load_lds_dwordx4 v134, s[54:55]
	s_add_i32 m0, s43, 0xe000
	s_nop 0
	global_load_lds_dwordx4 v136, s[54:55]
	s_waitcnt vmcnt(8)
	s_waitcnt lgkmcnt(0)
	s_barrier
; #define PG8_STAGE(bufoff, gbase, voff) do { _Pragma("unroll") for (int _i = 0; _i < 2; ++_i) \
;         __builtin_amdgcn_global_load_lds((const unsigned*)((const char*)(gbase) + (voff)[_i]), (LAS unsigned*)(lds + (bufoff) + ldsw + _i * 8192), 16, 0, 0); } while (0)
; #define PG8_LDA(dst, b, h) do { _Pragma("unroll") for (int m = 0; m < 4; ++m) _Pragma("unroll") for (int k = 0; k < 2; ++k) dst[m][k] = *(const LAS bf16x8*)(lds + PG8_SA(b, h) + aoff + m * 2048 + k * 1024); } while (0)
; #define PG8_MMA(ai, bj, At, Bt) do { __builtin_amdgcn_s_setprio(1); _Pragma("unroll") for (int m = 0; m < 4; ++m) _Pragma("unroll") for (int n = 0; n < 2; ++n) _Pragma("unroll") for (int k = 0; k < 2; ++k) \
;         acc[ai][bj][m][n] = __builtin_amdgcn_mfma_f32_16x16x32_bf16(Bt[n][k], At[m][k], acc[ai][bj][m][n], 0, 0, 0); __builtin_amdgcn_s_setprio(0); } while (0)
; #define PG8_WAIT_V(n) asm volatile("s_waitcnt vmcnt(" #n ")" ::: "memory")
; #define PG8_WAIT_L(n) asm volatile("s_waitcnt lgkmcnt(" #n ")" ::: "memory")
; #define PG8_BAR __builtin_amdgcn_s_barrier()
; #define PG8_SCHED __builtin_amdgcn_sched_barrier(0)
; template <class Epi, class Sched, bool ALIGN_EPI = true, bool SP2 = true>
; __device__ __forceinline__ void gemm_phase(LAS unsigned char* lds, const Gemm g, const Sched& S, const Epi& E) {
;     ...
;             PG8_WAIT_V(8); PG8_WAIT_L(0); PG8_BAR; PG8_MMA(0, 0, At, B0); PG8_MMA(0, 1, At, B1); PG8_BAR; PG8_SCHED;
;             PG8_LDA(At, 0, 1); PG8_STAGE(PG8_SB(0, 0), b2, voffB); PG8_STAGE(PG8_SB(0, 1), b2 + hstep, voffB); PG8_STAGE(PG8_SA(0, 0), a2, voffA);
;             PG8_WAIT_V(8); PG8_WAIT_L(0); PG8_BAR; PG8_MMA(1, 0, At, B0); PG8_MMA(1, 1, At, B1); PG8_BAR; PG8_SCHED;
	s_waitcnt lgkmcnt(0)
	v_mfma_f32_16x16x32_bf16 v[124:127], v[138:141], v[186:189], v[124:127]
	v_mfma_f32_16x16x32_bf16 v[116:119], v[152:155], v[186:189], v[116:119]
	v_mfma_f32_16x16x32_bf16 v[108:111], v[138:141], v[194:197], v[108:111]
	v_mfma_f32_16x16x32_bf16 v[100:103], v[152:155], v[194:197], v[100:103]
	v_mfma_f32_16x16x32_bf16 v[92:95], v[138:141], v[202:205], v[92:95]
	v_mfma_f32_16x16x32_bf16 v[84:87], v[152:155], v[202:205], v[84:87]
	v_mfma_f32_16x16x32_bf16 v[76:79], v[138:141], v[210:213], v[76:79]
	v_mfma_f32_16x16x32_bf16 v[68:71], v[152:155], v[210:213], v[68:71]
	v_mfma_f32_16x16x32_bf16 v[124:127], v[148:151], v[190:193], v[124:127]
	v_mfma_f32_16x16x32_bf16 v[116:119], v[156:159], v[190:193], v[116:119]
	v_mfma_f32_16x16x32_bf16 v[108:111], v[148:151], v[198:201], v[108:111]
	v_mfma_f32_16x16x32_bf16 v[100:103], v[156:159], v[198:201], v[100:103]
	v_mfma_f32_16x16x32_bf16 v[92:95], v[148:151], v[206:209], v[92:95]
	v_mfma_f32_16x16x32_bf16 v[84:87], v[156:159], v[206:209], v[84:87]
	v_mfma_f32_16x16x32_bf16 v[76:79], v[148:151], v[214:217], v[76:79]
	v_mfma_f32_16x16x32_bf16 v[68:71], v[156:159], v[214:217], v[68:71]
	v_mfma_f32_16x16x32_bf16 v[120:123], v[170:173], v[186:189], v[120:123]
	v_mfma_f32_16x16x32_bf16 v[112:115], v[178:181], v[186:189], v[112:115]
	v_mfma_f32_16x16x32_bf16 v[104:107], v[170:173], v[194:197], v[104:107]
	v_mfma_f32_16x16x32_bf16 v[96:99], v[178:181], v[194:197], v[96:99]
	v_mfma_f32_16x16x32_bf16 v[88:91], v[170:173], v[202:205], v[88:91]
	v_mfma_f32_16x16x32_bf16 v[80:83], v[178:181], v[202:205], v[80:83]
	v_mfma_f32_16x16x32_bf16 v[72:75], v[170:173], v[210:213], v[72:75]
	v_mfma_f32_16x16x32_bf16 v[64:67], v[178:181], v[210:213], v[64:67]
	v_mfma_f32_16x16x32_bf16 v[120:123], v[174:177], v[190:193], v[120:123]
	v_mfma_f32_16x16x32_bf16 v[112:115], v[182:185], v[190:193], v[112:115]
	v_mfma_f32_16x16x32_bf16 v[104:107], v[174:177], v[198:201], v[104:107]
	v_mfma_f32_16x16x32_bf16 v[96:99], v[182:185], v[198:201], v[96:99]
	v_mfma_f32_16x16x32_bf16 v[88:91], v[174:177], v[206:209], v[88:91]
	v_mfma_f32_16x16x32_bf16 v[80:83], v[182:185], v[206:209], v[80:83]
	v_mfma_f32_16x16x32_bf16 v[72:75], v[174:177], v[214:217], v[72:75]
	v_mfma_f32_16x16x32_bf16 v[64:67], v[182:185], v[214:217], v[64:67]
	s_barrier
	s_add_i32 s46, s46, s62
	s_mov_b32 m0, s46
	ds_read_b128 v[186:189], v147 offset:16384
	ds_read_b128 v[190:193], v147 offset:17408
	ds_read_b128 v[194:197], v147 offset:18432
	ds_read_b128 v[198:201], v147 offset:19456
	ds_read_b128 v[202:205], v147 offset:20480
	ds_read_b128 v[206:209], v147 offset:21504
	ds_read_b128 v[210:213], v147 offset:22528
	ds_read_b128 v[214:217], v147 offset:23552
	global_load_lds_dwordx4 v160, s[24:25]
	s_add_i32 m0, s46, 0x2000
	s_add_u32 s88, s24, 0x80000
	s_addc_u32 s89, s25, 0
	s_add_i32 s46, s47, s62
	global_load_lds_dwordx4 v128, s[24:25]
	s_mov_b32 m0, s46
	s_nop 0
	global_load_lds_dwordx4 v160, s[88:89]
	s_add_i32 m0, s46, 0x2000
	s_nop 0
	global_load_lds_dwordx4 v128, s[88:89]
	s_mov_b32 m0, s43
	s_nop 0
	global_load_lds_dwordx4 v132, s[60:61]
	s_mov_b32 m0, s44
	s_nop 0
	global_load_lds_dwordx4 v130, s[60:61]
	s_waitcnt vmcnt(8)
	s_waitcnt lgkmcnt(0)
	s_barrier
	s_waitcnt lgkmcnt(0)
	v_mfma_f32_16x16x32_bf16 v[60:63], v[138:141], v[186:189], v[60:63]
	v_mfma_f32_16x16x32_bf16 v[52:55], v[152:155], v[186:189], v[52:55]
	v_mfma_f32_16x16x32_bf16 v[44:47], v[138:141], v[194:197], v[44:47]
	v_mfma_f32_16x16x32_bf16 v[36:39], v[152:155], v[194:197], v[36:39]
	v_mfma_f32_16x16x32_bf16 v[28:31], v[138:141], v[202:205], v[28:31]
	v_mfma_f32_16x16x32_bf16 v[20:23], v[152:155], v[202:205], v[20:23]
	v_mfma_f32_16x16x32_bf16 v[12:15], v[138:141], v[210:213], v[12:15]
	v_mfma_f32_16x16x32_bf16 v[4:7], v[152:155], v[210:213], v[4:7]
	v_mfma_f32_16x16x32_bf16 v[60:63], v[148:151], v[190:193], v[60:63]
	v_mfma_f32_16x16x32_bf16 v[52:55], v[156:159], v[190:193], v[52:55]
	v_mfma_f32_16x16x32_bf16 v[44:47], v[148:151], v[198:201], v[44:47]
	v_mfma_f32_16x16x32_bf16 v[36:39], v[156:159], v[198:201], v[36:39]
	v_mfma_f32_16x16x32_bf16 v[28:31], v[148:151], v[206:209], v[28:31]
	v_mfma_f32_16x16x32_bf16 v[20:23], v[156:159], v[206:209], v[20:23]
	v_mfma_f32_16x16x32_bf16 v[12:15], v[148:151], v[214:217], v[12:15]
	v_mfma_f32_16x16x32_bf16 v[4:7], v[156:159], v[214:217], v[4:7]
	v_mfma_f32_16x16x32_bf16 v[56:59], v[170:173], v[186:189], v[56:59]
	v_mfma_f32_16x16x32_bf16 v[48:51], v[178:181], v[186:189], v[48:51]
	v_mfma_f32_16x16x32_bf16 v[40:43], v[170:173], v[194:197], v[40:43]
	v_mfma_f32_16x16x32_bf16 v[32:35], v[178:181], v[194:197], v[32:35]
	v_mfma_f32_16x16x32_bf16 v[24:27], v[170:173], v[202:205], v[24:27]
	v_mfma_f32_16x16x32_bf16 v[16:19], v[178:181], v[202:205], v[16:19]
	v_mfma_f32_16x16x32_bf16 v[8:11], v[170:173], v[210:213], v[8:11]
	v_mfma_f32_16x16x32_bf16 v[0:3], v[178:181], v[210:213], v[0:3]
	v_mfma_f32_16x16x32_bf16 v[56:59], v[174:177], v[190:193], v[56:59]
	v_mfma_f32_16x16x32_bf16 v[48:51], v[182:185], v[190:193], v[48:51]
	v_mfma_f32_16x16x32_bf16 v[40:43], v[174:177], v[198:201], v[40:43]
	v_mfma_f32_16x16x32_bf16 v[32:35], v[182:185], v[198:201], v[32:35]
	v_mfma_f32_16x16x32_bf16 v[24:27], v[174:177], v[206:209], v[24:27]
	v_mfma_f32_16x16x32_bf16 v[16:19], v[182:185], v[206:209], v[16:19]
	v_mfma_f32_16x16x32_bf16 v[8:11], v[174:177], v[214:217], v[8:11]
	v_mfma_f32_16x16x32_bf16 v[0:3], v[182:185], v[214:217], v[0:3]
	s_barrier
; #define PG8_STAGE(bufoff, gbase, voff) do { _Pragma("unroll") for (int _i = 0; _i < 2; ++_i) \
;         __builtin_amdgcn_global_load_lds((const unsigned*)((const char*)(gbase) + (voff)[_i]), (LAS unsigned*)(lds + (bufoff) + ldsw + _i * 8192), 16, 0, 0); } while (0)
; #define PG8_LDA(dst, b, h) do { _Pragma("unroll") for (int m = 0; m < 4; ++m) _Pragma("unroll") for (int k = 0; k < 2; ++k) dst[m][k] = *(const LAS bf16x8*)(lds + PG8_SA(b, h) + aoff + m * 2048 + k * 1024); } while (0)
; #define PG8_LDB(dst, b, h) do { _Pragma("unroll") for (int n = 0; n < 2; ++n) _Pragma("unroll") for (int k = 0; k < 2; ++k) dst[n][k] = *(const LAS bf16x8*)(lds + PG8_SB(b, h) + boff + n * 2048 + k * 1024); } while (0)
; #define PG8_MMA(ai, bj, At, Bt) do { __builtin_amdgcn_s_setprio(1); _Pragma("unroll") for (int m = 0; m < 4; ++m) _Pragma("unroll") for (int n = 0; n < 2; ++n) _Pragma("unroll") for (int k = 0; k < 2; ++k) \
;         acc[ai][bj][m][n] = __builtin_amdgcn_mfma_f32_16x16x32_bf16(Bt[n][k], At[m][k], acc[ai][bj][m][n], 0, 0, 0); __builtin_amdgcn_s_setprio(0); } while (0)
; #define PG8_WAIT_V(n) asm volatile("s_waitcnt vmcnt(" #n ")" ::: "memory")
; #define PG8_WAIT_L(n) asm volatile("s_waitcnt lgkmcnt(" #n ")" ::: "memory")
; #define PG8_BAR __builtin_amdgcn_s_barrier()
; #define PG8_SCHED __builtin_amdgcn_sched_barrier(0)
; template <class Epi, class Sched, bool ALIGN_EPI = true, bool SP2 = true>
; __device__ __forceinline__ void gemm_phase(LAS unsigned char* lds, const Gemm g, const Sched& S, const Epi& E) {
;     ...
;             PG8_LDB(B0, 1, 0); PG8_LDB(B1, 1, 1); PG8_SCHED; PG8_LDA(At, 1, 0); PG8_STAGE(PG8_SA(0, 1), a2 + hstep, voffA);
;             PG8_WAIT_V(8); PG8_WAIT_L(0); PG8_BAR; PG8_MMA(0, 0, At, B0); PG8_MMA(0, 1, At, B1); PG8_BAR; PG8_SCHED;
;             PG8_LDA(At, 1, 1); PG8_STAGE(PG8_SB(1, 0), b3, voffB); PG8_STAGE(PG8_SB(1, 1), b3 + hstep, voffB); PG8_STAGE(PG8_SA(1, 0), a3, voffA);
;             PG8_WAIT_V(8); PG8_WAIT_L(0); PG8_BAR; PG8_MMA(1, 0, At, B0); PG8_MMA(1, 1, At, B1); PG8_BAR; PG8_SCHED;
	s_add_i32 s46, 0, 0x18000
	s_add_i32 s47, 0, 0x1c000
	v_add_u32_e32 v156, s46, v145
	v_add_u32_e32 v166, s47, v145
	ds_read_b128 v[138:141], v156
	ds_read_b128 v[148:151], v156 offset:1024
	ds_read_b128 v[152:155], v156 offset:2048
	ds_read_b128 v[156:159], v156 offset:3072
	ds_read_b128 v[170:173], v166
	ds_read_b128 v[174:177], v166 offset:1024
	ds_read_b128 v[178:181], v166 offset:2048
	ds_read_b128 v[182:185], v166 offset:3072
	s_add_u32 s60, s60, 0x80000
	s_addc_u32 s61, s61, 0
	s_mov_b32 m0, s45
	ds_read_b128 v[186:189], v147 offset:32768
	ds_read_b128 v[190:193], v147 offset:33792
	ds_read_b128 v[194:197], v147 offset:34816
	ds_read_b128 v[198:201], v147 offset:35840
	ds_read_b128 v[202:205], v147 offset:36864
	ds_read_b128 v[206:209], v147 offset:37888
	ds_read_b128 v[210:213], v147 offset:38912
	ds_read_b128 v[214:217], v147 offset:39936
	global_load_lds_dwordx4 v132, s[60:61]
	s_mov_b32 m0, s53
	s_nop 0
	global_load_lds_dwordx4 v130, s[60:61]
	s_waitcnt vmcnt(8)
	s_waitcnt lgkmcnt(0)
	s_barrier
	s_waitcnt lgkmcnt(0)
	v_mfma_f32_16x16x32_bf16 v[124:127], v[138:141], v[186:189], v[124:127]
	v_mfma_f32_16x16x32_bf16 v[116:119], v[152:155], v[186:189], v[116:119]
	v_mfma_f32_16x16x32_bf16 v[108:111], v[138:141], v[194:197], v[108:111]
	v_mfma_f32_16x16x32_bf16 v[100:103], v[152:155], v[194:197], v[100:103]
	v_mfma_f32_16x16x32_bf16 v[92:95], v[138:141], v[202:205], v[92:95]
	v_mfma_f32_16x16x32_bf16 v[84:87], v[152:155], v[202:205], v[84:87]
	v_mfma_f32_16x16x32_bf16 v[76:79], v[138:141], v[210:213], v[76:79]
	v_mfma_f32_16x16x32_bf16 v[68:71], v[152:155], v[210:213], v[68:71]
	v_mfma_f32_16x16x32_bf16 v[124:127], v[148:151], v[190:193], v[124:127]
	v_mfma_f32_16x16x32_bf16 v[116:119], v[156:159], v[190:193], v[116:119]
	v_mfma_f32_16x16x32_bf16 v[108:111], v[148:151], v[198:201], v[108:111]
	v_mfma_f32_16x16x32_bf16 v[100:103], v[156:159], v[198:201], v[100:103]
	v_mfma_f32_16x16x32_bf16 v[92:95], v[148:151], v[206:209], v[92:95]
	v_mfma_f32_16x16x32_bf16 v[84:87], v[156:159], v[206:209], v[84:87]
	v_mfma_f32_16x16x32_bf16 v[76:79], v[148:151], v[214:217], v[76:79]
	v_mfma_f32_16x16x32_bf16 v[68:71], v[156:159], v[214:217], v[68:71]
	v_mfma_f32_16x16x32_bf16 v[120:123], v[170:173], v[186:189], v[120:123]
	v_mfma_f32_16x16x32_bf16 v[112:115], v[178:181], v[186:189], v[112:115]
	v_mfma_f32_16x16x32_bf16 v[104:107], v[170:173], v[194:197], v[104:107]
	v_mfma_f32_16x16x32_bf16 v[96:99], v[178:181], v[194:197], v[96:99]
	v_mfma_f32_16x16x32_bf16 v[88:91], v[170:173], v[202:205], v[88:91]
	v_mfma_f32_16x16x32_bf16 v[80:83], v[178:181], v[202:205], v[80:83]
	v_mfma_f32_16x16x32_bf16 v[72:75], v[170:173], v[210:213], v[72:75]
	v_mfma_f32_16x16x32_bf16 v[64:67], v[178:181], v[210:213], v[64:67]
	v_mfma_f32_16x16x32_bf16 v[120:123], v[174:177], v[190:193], v[120:123]
	v_mfma_f32_16x16x32_bf16 v[112:115], v[182:185], v[190:193], v[112:115]
	v_mfma_f32_16x16x32_bf16 v[104:107], v[174:177], v[198:201], v[104:107]
	v_mfma_f32_16x16x32_bf16 v[96:99], v[182:185], v[198:201], v[96:99]
	v_mfma_f32_16x16x32_bf16 v[88:91], v[174:177], v[206:209], v[88:91]
	v_mfma_f32_16x16x32_bf16 v[80:83], v[182:185], v[206:209], v[80:83]
	v_mfma_f32_16x16x32_bf16 v[72:75], v[174:177], v[214:217], v[72:75]
	v_mfma_f32_16x16x32_bf16 v[64:67], v[182:185], v[214:217], v[64:67]
	s_barrier
	s_add_i32 s46, s46, s62
	s_mov_b32 m0, s46
	ds_read_b128 v[186:189], v147 offset:49152
	ds_read_b128 v[190:193], v147 offset:50176
	ds_read_b128 v[194:197], v147 offset:51200
	ds_read_b128 v[198:201], v147 offset:52224
	ds_read_b128 v[202:205], v147 offset:53248
	ds_read_b128 v[206:209], v147 offset:54272
	ds_read_b128 v[210:213], v147 offset:55296
	ds_read_b128 v[214:217], v147 offset:56320
	s_add_u32 s98, s24, 0x80
	s_addc_u32 s99, s25, 0
	global_load_lds_dwordx4 v160, s[98:99]
	s_add_i32 m0, s46, 0x2000
	s_add_u32 s24, s24, 0x80080
	s_addc_u32 s25, s25, 0
	s_add_i32 s46, s47, s62
	global_load_lds_dwordx4 v128, s[98:99]
	s_mov_b32 m0, s46
	s_nop 0
	global_load_lds_dwordx4 v160, s[24:25]
	s_add_i32 m0, s46, 0x2000
	s_nop 0
	global_load_lds_dwordx4 v128, s[24:25]
	s_mov_b32 m0, s63
	s_nop 0
	s_add_u32 s98, s60, 0xfff80080
	s_addc_u32 s99, s61, -1
	global_load_lds_dwordx4 v132, s[98:99]
	s_mov_b32 m0, s66
	s_nop 0
	global_load_lds_dwordx4 v130, s[98:99]
	s_waitcnt vmcnt(8)
	s_waitcnt lgkmcnt(0)
	s_barrier
	s_waitcnt lgkmcnt(0)
	v_mfma_f32_16x16x32_bf16 v[60:63], v[138:141], v[186:189], v[60:63]
	v_mfma_f32_16x16x32_bf16 v[52:55], v[152:155], v[186:189], v[52:55]
	v_mfma_f32_16x16x32_bf16 v[44:47], v[138:141], v[194:197], v[44:47]
	v_mfma_f32_16x16x32_bf16 v[36:39], v[152:155], v[194:197], v[36:39]
	v_mfma_f32_16x16x32_bf16 v[28:31], v[138:141], v[202:205], v[28:31]
	v_mfma_f32_16x16x32_bf16 v[20:23], v[152:155], v[202:205], v[20:23]
	v_mfma_f32_16x16x32_bf16 v[12:15], v[138:141], v[210:213], v[12:15]
	v_mfma_f32_16x16x32_bf16 v[4:7], v[152:155], v[210:213], v[4:7]
	v_mfma_f32_16x16x32_bf16 v[60:63], v[148:151], v[190:193], v[60:63]
	v_mfma_f32_16x16x32_bf16 v[52:55], v[156:159], v[190:193], v[52:55]
	v_mfma_f32_16x16x32_bf16 v[44:47], v[148:151], v[198:201], v[44:47]
	v_mfma_f32_16x16x32_bf16 v[36:39], v[156:159], v[198:201], v[36:39]
	v_mfma_f32_16x16x32_bf16 v[28:31], v[148:151], v[206:209], v[28:31]
	v_mfma_f32_16x16x32_bf16 v[20:23], v[156:159], v[206:209], v[20:23]
	v_mfma_f32_16x16x32_bf16 v[12:15], v[148:151], v[214:217], v[12:15]
	v_mfma_f32_16x16x32_bf16 v[4:7], v[156:159], v[214:217], v[4:7]
	v_mfma_f32_16x16x32_bf16 v[56:59], v[170:173], v[186:189], v[56:59]
	v_mfma_f32_16x16x32_bf16 v[48:51], v[178:181], v[186:189], v[48:51]
	v_mfma_f32_16x16x32_bf16 v[40:43], v[170:173], v[194:197], v[40:43]
	v_mfma_f32_16x16x32_bf16 v[32:35], v[178:181], v[194:197], v[32:35]
	v_mfma_f32_16x16x32_bf16 v[24:27], v[170:173], v[202:205], v[24:27]
	v_mfma_f32_16x16x32_bf16 v[16:19], v[178:181], v[202:205], v[16:19]
	v_mfma_f32_16x16x32_bf16 v[8:11], v[170:173], v[210:213], v[8:11]
	v_mfma_f32_16x16x32_bf16 v[0:3], v[178:181], v[210:213], v[0:3]
	v_mfma_f32_16x16x32_bf16 v[56:59], v[174:177], v[190:193], v[56:59]
	v_mfma_f32_16x16x32_bf16 v[48:51], v[182:185], v[190:193], v[48:51]
	v_mfma_f32_16x16x32_bf16 v[40:43], v[174:177], v[198:201], v[40:43]
	v_mfma_f32_16x16x32_bf16 v[32:35], v[182:185], v[198:201], v[32:35]
	v_mfma_f32_16x16x32_bf16 v[24:27], v[174:177], v[206:209], v[24:27]
	v_mfma_f32_16x16x32_bf16 v[16:19], v[182:185], v[206:209], v[16:19]
	v_mfma_f32_16x16x32_bf16 v[8:11], v[174:177], v[214:217], v[8:11]
	v_mfma_f32_16x16x32_bf16 v[0:3], v[182:185], v[214:217], v[0:3]
	s_barrier
	s_add_i32 s83, s83, 2
	s_add_u32 s54, s54, 0x100
	s_addc_u32 s55, s55, 0
	s_add_u32 s79, s79, 0x100
	s_addc_u32 s82, s82, 0
	s_cmp_gt_u32 s83, 29
	s_cbranch_scc0 .LBB0_600
	s_setprio 0
	s_and_b64 vcc, exec, s[10:11]
	s_cbranch_vccz .LBB0_603
	s_barrier
